# P4 chained passes: gate-loop tail and each branch pass tail issue the next pass's first two BK=64 stages (LDS-DMA) so loads stay in flight through the sigmoid block and pass boundaries; branch passes
# speedup vs baseline: 1.1649x; 1.0000x over previous
.LBB0_918:
	s_lshl_b64 s[54:55], s[38:39], 11
	s_add_u32 s100, s0, s54
	s_addc_u32 s101, s1, s55
	s_add_u32 s52, s100, 0x200000
	s_addc_u32 s53, s101, 0
	s_add_u32 s54, s100, 0x400000
	s_addc_u32 s55, s101, 0
	s_mov_b64 s[98:99], s[42:43]
	v_mov_b32_e32 v227, v199
	v_lshrrev_b32_e32 v0, 3, v227
	v_and_b32_e32 v224, 7, v227
	v_bfe_u32 v225, v227, 4, 3
	v_xor_b32_e32 v224, v224, v225
	v_lshlrev_b32_e32 v224, 4, v224
	v_lshl_or_b32 v248, v0, 11, v224
	v_add_u32_e32 v249, 0x10000, v248
	v_add_u32_e32 v250, 0x20000, v248
	v_add_u32_e32 v251, 0x30000, v248
	v_mul_u32_u24_e32 v0, 0x700, v0
	v_add_u32_e32 v200, v0, v224
	v_add_u32_e32 v201, 0xe000, v200
	v_add_u32_e32 v202, 0x1c000, v200
	v_add_u32_e32 v204, 0x2a000, v200
	v_lshlrev_b32_e32 v0, 4, v227
	s_nop 0
	v_readfirstlane_b32 s30, v0
	v_and_b32_e32 v224, 31, v227
	v_bfe_u32 v226, v227, 5, 1
	v_bfe_u32 v225, v227, 1, 3
	v_xor_b32_e32 v226, v226, v225
	v_lshlrev_b32_e32 v226, 4, v226
	v_lshlrev_b32_e32 v0, 7, v224
	v_bfe_u32 v224, v227, 7, 1
	v_bfe_u32 v225, v227, 6, 1
	v_lshl_or_b32 v224, v224, 13, v0
	v_lshl_or_b32 v225, v225, 13, v0
	s_barrier
	s_add_u32 m0, s30, 0x0
	v_mov_b32_e32 v2, 0
	global_load_lds_dwordx4 v248, s[98:99]
	s_add_u32 m0, s30, 0x1000
	v_mov_b32_e32 v3, 0
	global_load_lds_dwordx4 v249, s[98:99]
	s_add_u32 m0, s30, 0x2000
	v_mov_b32_e32 v4, 0
	global_load_lds_dwordx4 v250, s[98:99]
	s_add_u32 m0, s30, 0x3000
	v_mov_b32_e32 v5, 0
	global_load_lds_dwordx4 v251, s[98:99]
	s_add_u32 s98, s98, 0x80
	s_addc_u32 s99, s99, 0
	s_add_u32 m0, s30, 0x8000
	v_mov_b32_e32 v6, 0
	global_load_lds_dwordx4 v248, s[100:101]
	s_add_u32 m0, s30, 0x9000
	v_mov_b32_e32 v7, 0
	global_load_lds_dwordx4 v249, s[100:101]
	s_add_u32 m0, s30, 0xa000
	v_mov_b32_e32 v8, 0
	global_load_lds_dwordx4 v250, s[100:101]
	s_add_u32 m0, s30, 0xb000
	v_mov_b32_e32 v9, 0
	global_load_lds_dwordx4 v251, s[100:101]
	s_add_u32 s100, s100, 0x80
	s_addc_u32 s101, s101, 0
	s_add_u32 m0, s30, 0x4000
	v_mov_b32_e32 v10, 0
	global_load_lds_dwordx4 v248, s[98:99]
	s_add_u32 m0, s30, 0x5000
	v_mov_b32_e32 v11, 0
	global_load_lds_dwordx4 v249, s[98:99]
	s_add_u32 m0, s30, 0x6000
	v_mov_b32_e32 v12, 0
	global_load_lds_dwordx4 v250, s[98:99]
	s_add_u32 m0, s30, 0x7000
	v_mov_b32_e32 v13, 0
	global_load_lds_dwordx4 v251, s[98:99]
	s_add_u32 s98, s98, 0x80
	s_addc_u32 s99, s99, 0
	s_add_u32 m0, s30, 0xc000
	v_mov_b32_e32 v14, 0
	global_load_lds_dwordx4 v248, s[52:53]
	s_add_u32 m0, s30, 0xd000
	v_mov_b32_e32 v15, 0
	global_load_lds_dwordx4 v249, s[52:53]
	s_add_u32 m0, s30, 0xe000
	v_mov_b32_e32 v16, 0
	global_load_lds_dwordx4 v250, s[52:53]
	s_add_u32 m0, s30, 0xf000
	v_mov_b32_e32 v17, 0
	global_load_lds_dwordx4 v251, s[52:53]
	s_add_u32 s52, s52, 0x80
	s_addc_u32 s53, s53, 0
	v_mov_b32_e32 v18, 0
	v_mov_b32_e32 v19, 0
	v_mov_b32_e32 v20, 0
	v_mov_b32_e32 v21, 0
	v_mov_b32_e32 v22, 0
	v_mov_b32_e32 v23, 0
	v_mov_b32_e32 v24, 0
	v_mov_b32_e32 v25, 0
	v_mov_b32_e32 v26, 0
	v_mov_b32_e32 v27, 0
	v_mov_b32_e32 v28, 0
	v_mov_b32_e32 v29, 0
	v_mov_b32_e32 v30, 0
	v_mov_b32_e32 v31, 0
	v_mov_b32_e32 v32, 0
	v_mov_b32_e32 v33, 0
	v_mov_b32_e32 v34, 0
	v_mov_b32_e32 v35, 0
	v_mov_b32_e32 v36, 0
	v_mov_b32_e32 v37, 0
	v_mov_b32_e32 v38, 0
	v_mov_b32_e32 v39, 0
	v_mov_b32_e32 v40, 0
	v_mov_b32_e32 v41, 0
	v_mov_b32_e32 v42, 0
	v_mov_b32_e32 v43, 0
	v_mov_b32_e32 v44, 0
	v_mov_b32_e32 v45, 0
	v_mov_b32_e32 v46, 0
	v_mov_b32_e32 v47, 0
	v_mov_b32_e32 v48, 0
	v_mov_b32_e32 v49, 0
	v_mov_b32_e32 v50, 0
	v_mov_b32_e32 v51, 0
	v_mov_b32_e32 v52, 0
	v_mov_b32_e32 v53, 0
	v_mov_b32_e32 v54, 0
	v_mov_b32_e32 v55, 0
	v_mov_b32_e32 v56, 0
	v_mov_b32_e32 v57, 0
	v_mov_b32_e32 v58, 0
	v_mov_b32_e32 v59, 0
	v_mov_b32_e32 v60, 0
	v_mov_b32_e32 v61, 0
	v_mov_b32_e32 v62, 0
	v_mov_b32_e32 v63, 0
	v_mov_b32_e32 v64, 0
	v_mov_b32_e32 v65, 0
	v_mov_b32_e32 v66, 0
	v_mov_b32_e32 v67, 0
	v_mov_b32_e32 v68, 0
	v_mov_b32_e32 v69, 0
	v_mov_b32_e32 v70, 0
	v_mov_b32_e32 v71, 0
	v_mov_b32_e32 v72, 0
	v_mov_b32_e32 v73, 0
	v_mov_b32_e32 v74, 0
	v_mov_b32_e32 v75, 0
	v_mov_b32_e32 v76, 0
	v_mov_b32_e32 v77, 0
	v_mov_b32_e32 v78, 0
	v_mov_b32_e32 v79, 0
	v_mov_b32_e32 v80, 0
	v_mov_b32_e32 v81, 0
	v_mov_b32_e32 v82, 0
	v_mov_b32_e32 v83, 0
	v_mov_b32_e32 v84, 0
	v_mov_b32_e32 v85, 0
	v_mov_b32_e32 v86, 0
	v_mov_b32_e32 v87, 0
	v_mov_b32_e32 v88, 0
	v_mov_b32_e32 v89, 0
	v_mov_b32_e32 v90, 0
	v_mov_b32_e32 v91, 0
	v_mov_b32_e32 v92, 0
	v_mov_b32_e32 v93, 0
	v_mov_b32_e32 v94, 0
	v_mov_b32_e32 v95, 0
	v_mov_b32_e32 v96, 0
	v_mov_b32_e32 v97, 0
	v_mov_b32_e32 v98, 0
	v_mov_b32_e32 v99, 0
	v_mov_b32_e32 v100, 0
	v_mov_b32_e32 v101, 0
	v_mov_b32_e32 v102, 0
	v_mov_b32_e32 v103, 0
	v_mov_b32_e32 v104, 0
	v_mov_b32_e32 v105, 0
	v_mov_b32_e32 v106, 0
	v_mov_b32_e32 v107, 0
	v_mov_b32_e32 v108, 0
	v_mov_b32_e32 v109, 0
	v_mov_b32_e32 v110, 0
	v_mov_b32_e32 v111, 0
	v_mov_b32_e32 v112, 0
	v_mov_b32_e32 v113, 0
	v_mov_b32_e32 v114, 0
	v_mov_b32_e32 v115, 0
	v_mov_b32_e32 v116, 0
	v_mov_b32_e32 v117, 0
	v_mov_b32_e32 v118, 0
	v_mov_b32_e32 v119, 0
	v_mov_b32_e32 v120, 0
	v_mov_b32_e32 v121, 0
	v_mov_b32_e32 v122, 0
	v_mov_b32_e32 v123, 0
	v_mov_b32_e32 v124, 0
	v_mov_b32_e32 v125, 0
	v_mov_b32_e32 v126, 0
	v_mov_b32_e32 v127, 0
	v_mov_b32_e32 v128, 0
	v_mov_b32_e32 v129, 0
	v_mov_b32_e32 v130, 0
	v_mov_b32_e32 v131, 0
	v_mov_b32_e32 v132, 0
	v_mov_b32_e32 v133, 0
	v_mov_b32_e32 v134, 0
	v_mov_b32_e32 v135, 0
	v_mov_b32_e32 v136, 0
	v_mov_b32_e32 v137, 0
	v_mov_b32_e32 v138, 0
	v_mov_b32_e32 v139, 0
	v_mov_b32_e32 v140, 0
	v_mov_b32_e32 v141, 0
	v_mov_b32_e32 v142, 0
	v_mov_b32_e32 v143, 0
	v_mov_b32_e32 v144, 0
	v_mov_b32_e32 v145, 0
	v_mov_b32_e32 v146, 0
	v_mov_b32_e32 v147, 0
	v_mov_b32_e32 v148, 0
	v_mov_b32_e32 v149, 0
	v_mov_b32_e32 v150, 0
	v_mov_b32_e32 v151, 0
	v_mov_b32_e32 v152, 0
	v_mov_b32_e32 v153, 0
	v_mov_b32_e32 v154, 0
	v_mov_b32_e32 v155, 0
	v_mov_b32_e32 v156, 0
	v_mov_b32_e32 v157, 0
	v_mov_b32_e32 v158, 0
	v_mov_b32_e32 v159, 0
	v_mov_b32_e32 v160, 0
	v_mov_b32_e32 v161, 0
	v_mov_b32_e32 v162, 0
	v_mov_b32_e32 v163, 0
	v_mov_b32_e32 v164, 0
	v_mov_b32_e32 v165, 0
	v_mov_b32_e32 v166, 0
	v_mov_b32_e32 v167, 0
	v_mov_b32_e32 v168, 0
	v_mov_b32_e32 v169, 0
	v_mov_b32_e32 v170, 0
	v_mov_b32_e32 v171, 0
	v_mov_b32_e32 v172, 0
	v_mov_b32_e32 v173, 0
	v_mov_b32_e32 v174, 0
	v_mov_b32_e32 v175, 0
	v_mov_b32_e32 v176, 0
	v_mov_b32_e32 v177, 0
	v_mov_b32_e32 v178, 0
	v_mov_b32_e32 v179, 0
	v_mov_b32_e32 v180, 0
	v_mov_b32_e32 v181, 0
	v_mov_b32_e32 v182, 0
	v_mov_b32_e32 v183, 0
	v_mov_b32_e32 v184, 0
	v_mov_b32_e32 v185, 0
	v_mov_b32_e32 v186, 0
	v_mov_b32_e32 v187, 0
	v_mov_b32_e32 v188, 0
	v_mov_b32_e32 v189, 0
	v_mov_b32_e32 v190, 0
	v_mov_b32_e32 v191, 0
	v_mov_b32_e32 v192, 0
	v_mov_b32_e32 v193, 0
	s_waitcnt vmcnt(8)
	s_barrier
	v_add_u32_e32 v228, v226, v224
	v_add_u32_e32 v240, v226, v225
	ds_read_b128 v[220:223], v228
	ds_read_b128 v[228:231], v228 offset:4096
	ds_read_b128 v[236:239], v240 offset:32768
	ds_read_b128 v[240:243], v240 offset:36864
	s_mov_b32 s51, 7
.Lp4f_gloop:
	s_waitcnt lgkmcnt(0)
	v_mfma_f32_32x32x16_bf16 v[50:65], v[236:239], v[220:223], v[50:65]
	v_xor_b32_e32 v244, 0x20, v226
	v_add_u32_e32 v232, v244, v224
	v_add_u32_e32 v244, v244, v225
	v_mfma_f32_32x32x16_bf16 v[34:49], v[240:243], v[220:223], v[34:49]
	ds_read_b128 v[220:223], v232
	ds_read_b128 v[232:235], v232 offset:4096
	v_mfma_f32_32x32x16_bf16 v[18:33], v[236:239], v[228:231], v[18:33]
	ds_read_b128 v[236:239], v244 offset:32768
	ds_read_b128 v[244:247], v244 offset:36864
	v_mfma_f32_32x32x16_bf16 v[2:17], v[240:243], v[228:231], v[2:17]
	s_waitcnt lgkmcnt(0)
	v_mfma_f32_32x32x16_bf16 v[50:65], v[236:239], v[220:223], v[50:65]
	v_xor_b32_e32 v240, 0x40, v226
	v_add_u32_e32 v228, v240, v224
	v_add_u32_e32 v240, v240, v225
	v_mfma_f32_32x32x16_bf16 v[34:49], v[244:247], v[220:223], v[34:49]
	ds_read_b128 v[220:223], v228
	ds_read_b128 v[228:231], v228 offset:4096
	v_mfma_f32_32x32x16_bf16 v[18:33], v[236:239], v[232:235], v[18:33]
	ds_read_b128 v[236:239], v240 offset:32768
	ds_read_b128 v[240:243], v240 offset:36864
	v_mfma_f32_32x32x16_bf16 v[2:17], v[244:247], v[232:235], v[2:17]
	s_waitcnt lgkmcnt(0)
	v_mfma_f32_32x32x16_bf16 v[50:65], v[236:239], v[220:223], v[50:65]
	v_xor_b32_e32 v244, 0x60, v226
	v_add_u32_e32 v232, v244, v224
	v_add_u32_e32 v244, v244, v225
	v_mfma_f32_32x32x16_bf16 v[34:49], v[240:243], v[220:223], v[34:49]
	ds_read_b128 v[220:223], v232
	ds_read_b128 v[232:235], v232 offset:4096
	v_mfma_f32_32x32x16_bf16 v[18:33], v[236:239], v[228:231], v[18:33]
	ds_read_b128 v[236:239], v244 offset:32768
	ds_read_b128 v[244:247], v244 offset:36864
	v_mfma_f32_32x32x16_bf16 v[2:17], v[240:243], v[228:231], v[2:17]
	s_waitcnt vmcnt(0) lgkmcnt(0)
	s_barrier
	s_waitcnt lgkmcnt(0)
	v_mfma_f32_32x32x16_bf16 v[50:65], v[236:239], v[220:223], v[50:65]
	v_mov_b32_e32 v240, v226
	v_add_u32_e32 v228, v240, v224
	v_add_u32_e32 v240, v240, v225
	v_mfma_f32_32x32x16_bf16 v[34:49], v[244:247], v[220:223], v[34:49]
	ds_read_b128 v[220:223], v228
	ds_read_b128 v[228:231], v228 offset:4096
	s_add_u32 m0, s30, 0x8000
	s_nop 0
	global_load_lds_dwordx4 v248, s[54:55]
	s_add_u32 m0, s30, 0x9000
	s_nop 0
	global_load_lds_dwordx4 v249, s[54:55]
	v_mfma_f32_32x32x16_bf16 v[18:33], v[236:239], v[232:235], v[18:33]
	ds_read_b128 v[236:239], v240 offset:49152
	ds_read_b128 v[240:243], v240 offset:53248
	s_add_u32 m0, s30, 0xa000
	s_nop 0
	global_load_lds_dwordx4 v250, s[54:55]
	s_add_u32 m0, s30, 0xb000
	s_nop 0
	global_load_lds_dwordx4 v251, s[54:55]
	v_mfma_f32_32x32x16_bf16 v[2:17], v[244:247], v[232:235], v[2:17]
	s_add_u32 s54, s54, 0x80
	s_addc_u32 s55, s55, 0
	s_waitcnt lgkmcnt(0)
	v_mfma_f32_32x32x16_bf16 v[114:129], v[236:239], v[220:223], v[114:129]
	v_xor_b32_e32 v244, 0x20, v226
	v_add_u32_e32 v232, v244, v224
	v_add_u32_e32 v244, v244, v225
	v_mfma_f32_32x32x16_bf16 v[98:113], v[240:243], v[220:223], v[98:113]
	ds_read_b128 v[220:223], v232
	ds_read_b128 v[232:235], v232 offset:4096
	v_mfma_f32_32x32x16_bf16 v[82:97], v[236:239], v[228:231], v[82:97]
	ds_read_b128 v[236:239], v244 offset:49152
	ds_read_b128 v[244:247], v244 offset:53248
	v_mfma_f32_32x32x16_bf16 v[66:81], v[240:243], v[228:231], v[66:81]
	s_waitcnt lgkmcnt(0)
	v_mfma_f32_32x32x16_bf16 v[114:129], v[236:239], v[220:223], v[114:129]
	v_xor_b32_e32 v240, 0x40, v226
	v_add_u32_e32 v228, v240, v224
	v_add_u32_e32 v240, v240, v225
	v_mfma_f32_32x32x16_bf16 v[98:113], v[244:247], v[220:223], v[98:113]
	ds_read_b128 v[220:223], v228
	ds_read_b128 v[228:231], v228 offset:4096
	v_mfma_f32_32x32x16_bf16 v[82:97], v[236:239], v[232:235], v[82:97]
	ds_read_b128 v[236:239], v240 offset:49152
	ds_read_b128 v[240:243], v240 offset:53248
	v_mfma_f32_32x32x16_bf16 v[66:81], v[244:247], v[232:235], v[66:81]
	s_waitcnt lgkmcnt(0)
	v_mfma_f32_32x32x16_bf16 v[114:129], v[236:239], v[220:223], v[114:129]
	v_xor_b32_e32 v244, 0x60, v226
	v_add_u32_e32 v232, v244, v224
	v_add_u32_e32 v244, v244, v225
	v_mfma_f32_32x32x16_bf16 v[98:113], v[240:243], v[220:223], v[98:113]
	ds_read_b128 v[220:223], v232
	ds_read_b128 v[232:235], v232 offset:4096
	v_mfma_f32_32x32x16_bf16 v[82:97], v[236:239], v[228:231], v[82:97]
	ds_read_b128 v[236:239], v244 offset:49152
	ds_read_b128 v[244:247], v244 offset:53248
	v_mfma_f32_32x32x16_bf16 v[66:81], v[240:243], v[228:231], v[66:81]
	s_waitcnt vmcnt(0) lgkmcnt(0)
	s_barrier
	s_waitcnt lgkmcnt(0)
	v_mfma_f32_32x32x16_bf16 v[114:129], v[236:239], v[220:223], v[114:129]
	v_mov_b32_e32 v240, v226
	v_add_u32_e32 v228, v240, v224
	v_add_u32_e32 v240, v240, v225
	v_mfma_f32_32x32x16_bf16 v[98:113], v[244:247], v[220:223], v[98:113]
	ds_read_b128 v[220:223], v228
	ds_read_b128 v[228:231], v228 offset:4096
	s_add_u32 m0, s30, 0xc000
	s_nop 0
	global_load_lds_dwordx4 v248, s[100:101]
	s_add_u32 m0, s30, 0xd000
	s_nop 0
	global_load_lds_dwordx4 v249, s[100:101]
	v_mfma_f32_32x32x16_bf16 v[82:97], v[236:239], v[232:235], v[82:97]
	ds_read_b128 v[236:239], v240 offset:32768
	ds_read_b128 v[240:243], v240 offset:36864
	s_add_u32 m0, s30, 0xe000
	s_nop 0
	global_load_lds_dwordx4 v250, s[100:101]
	s_add_u32 m0, s30, 0xf000
	s_nop 0
	global_load_lds_dwordx4 v251, s[100:101]
	v_mfma_f32_32x32x16_bf16 v[66:81], v[244:247], v[232:235], v[66:81]
	s_add_u32 s100, s100, 0x80
	s_addc_u32 s101, s101, 0
	s_waitcnt lgkmcnt(0)
	v_mfma_f32_32x32x16_bf16 v[178:193], v[236:239], v[220:223], v[178:193]
	v_xor_b32_e32 v244, 0x20, v226
	v_add_u32_e32 v232, v244, v224
	v_add_u32_e32 v244, v244, v225
	v_mfma_f32_32x32x16_bf16 v[162:177], v[240:243], v[220:223], v[162:177]
	ds_read_b128 v[220:223], v232
	ds_read_b128 v[232:235], v232 offset:4096
	v_mfma_f32_32x32x16_bf16 v[146:161], v[236:239], v[228:231], v[146:161]
	ds_read_b128 v[236:239], v244 offset:32768
	ds_read_b128 v[244:247], v244 offset:36864
	v_mfma_f32_32x32x16_bf16 v[130:145], v[240:243], v[228:231], v[130:145]
	s_waitcnt lgkmcnt(0)
	v_mfma_f32_32x32x16_bf16 v[178:193], v[236:239], v[220:223], v[178:193]
	v_xor_b32_e32 v240, 0x40, v226
	v_add_u32_e32 v228, v240, v224
	v_add_u32_e32 v240, v240, v225
	v_mfma_f32_32x32x16_bf16 v[162:177], v[244:247], v[220:223], v[162:177]
	ds_read_b128 v[220:223], v228
	ds_read_b128 v[228:231], v228 offset:4096
	v_mfma_f32_32x32x16_bf16 v[146:161], v[236:239], v[232:235], v[146:161]
	ds_read_b128 v[236:239], v240 offset:32768
	ds_read_b128 v[240:243], v240 offset:36864
	v_mfma_f32_32x32x16_bf16 v[130:145], v[244:247], v[232:235], v[130:145]
	s_waitcnt lgkmcnt(0)
	v_mfma_f32_32x32x16_bf16 v[178:193], v[236:239], v[220:223], v[178:193]
	v_xor_b32_e32 v244, 0x60, v226
	v_add_u32_e32 v232, v244, v224
	v_add_u32_e32 v244, v244, v225
	v_mfma_f32_32x32x16_bf16 v[162:177], v[240:243], v[220:223], v[162:177]
	ds_read_b128 v[220:223], v232
	ds_read_b128 v[232:235], v232 offset:4096
	v_mfma_f32_32x32x16_bf16 v[146:161], v[236:239], v[228:231], v[146:161]
	ds_read_b128 v[236:239], v244 offset:32768
	ds_read_b128 v[244:247], v244 offset:36864
	v_mfma_f32_32x32x16_bf16 v[130:145], v[240:243], v[228:231], v[130:145]
	s_waitcnt vmcnt(0) lgkmcnt(0)
	s_barrier
	s_waitcnt lgkmcnt(0)
	v_mfma_f32_32x32x16_bf16 v[178:193], v[236:239], v[220:223], v[178:193]
	v_mov_b32_e32 v240, v226
	v_add_u32_e32 v228, v240, v224
	v_add_u32_e32 v240, v240, v225
	v_mfma_f32_32x32x16_bf16 v[162:177], v[244:247], v[220:223], v[162:177]
	ds_read_b128 v[220:223], v228 offset:16384
	ds_read_b128 v[228:231], v228 offset:20480
	s_add_u32 m0, s30, 0x8000
	s_nop 0
	global_load_lds_dwordx4 v248, s[52:53]
	s_add_u32 m0, s30, 0x9000
	s_nop 0
	global_load_lds_dwordx4 v249, s[52:53]
	v_mfma_f32_32x32x16_bf16 v[146:161], v[236:239], v[232:235], v[146:161]
	ds_read_b128 v[236:239], v240 offset:49152
	ds_read_b128 v[240:243], v240 offset:53248
	s_add_u32 m0, s30, 0xa000
	s_nop 0
	global_load_lds_dwordx4 v250, s[52:53]
	s_add_u32 m0, s30, 0xb000
	s_nop 0
	global_load_lds_dwordx4 v251, s[52:53]
	v_mfma_f32_32x32x16_bf16 v[130:145], v[244:247], v[232:235], v[130:145]
	s_add_u32 m0, s30, 0x0
	s_nop 0
	global_load_lds_dwordx4 v248, s[98:99]
	s_add_u32 m0, s30, 0x1000
	s_nop 0
	global_load_lds_dwordx4 v249, s[98:99]
	s_add_u32 m0, s30, 0x2000
	s_nop 0
	global_load_lds_dwordx4 v250, s[98:99]
	s_add_u32 m0, s30, 0x3000
	s_nop 0
	global_load_lds_dwordx4 v251, s[98:99]
	s_add_u32 s52, s52, 0x80
	s_addc_u32 s53, s53, 0
	s_add_u32 s98, s98, 0x80
	s_addc_u32 s99, s99, 0
	s_waitcnt lgkmcnt(0)
	v_mfma_f32_32x32x16_bf16 v[50:65], v[236:239], v[220:223], v[50:65]
	v_xor_b32_e32 v244, 0x20, v226
	v_add_u32_e32 v232, v244, v224
	v_add_u32_e32 v244, v244, v225
	v_mfma_f32_32x32x16_bf16 v[34:49], v[240:243], v[220:223], v[34:49]
	ds_read_b128 v[220:223], v232 offset:16384
	ds_read_b128 v[232:235], v232 offset:20480
	v_mfma_f32_32x32x16_bf16 v[18:33], v[236:239], v[228:231], v[18:33]
	ds_read_b128 v[236:239], v244 offset:49152
	ds_read_b128 v[244:247], v244 offset:53248
	v_mfma_f32_32x32x16_bf16 v[2:17], v[240:243], v[228:231], v[2:17]
	s_waitcnt lgkmcnt(0)
	v_mfma_f32_32x32x16_bf16 v[50:65], v[236:239], v[220:223], v[50:65]
	v_xor_b32_e32 v240, 0x40, v226
	v_add_u32_e32 v228, v240, v224
	v_add_u32_e32 v240, v240, v225
	v_mfma_f32_32x32x16_bf16 v[34:49], v[244:247], v[220:223], v[34:49]
	ds_read_b128 v[220:223], v228 offset:16384
	ds_read_b128 v[228:231], v228 offset:20480
	v_mfma_f32_32x32x16_bf16 v[18:33], v[236:239], v[232:235], v[18:33]
	ds_read_b128 v[236:239], v240 offset:49152
	ds_read_b128 v[240:243], v240 offset:53248
	v_mfma_f32_32x32x16_bf16 v[2:17], v[244:247], v[232:235], v[2:17]
	s_waitcnt lgkmcnt(0)
	v_mfma_f32_32x32x16_bf16 v[50:65], v[236:239], v[220:223], v[50:65]
	v_xor_b32_e32 v244, 0x60, v226
	v_add_u32_e32 v232, v244, v224
	v_add_u32_e32 v244, v244, v225
	v_mfma_f32_32x32x16_bf16 v[34:49], v[240:243], v[220:223], v[34:49]
	ds_read_b128 v[220:223], v232 offset:16384
	ds_read_b128 v[232:235], v232 offset:20480
	v_mfma_f32_32x32x16_bf16 v[18:33], v[236:239], v[228:231], v[18:33]
	ds_read_b128 v[236:239], v244 offset:49152
	ds_read_b128 v[244:247], v244 offset:53248
	v_mfma_f32_32x32x16_bf16 v[2:17], v[240:243], v[228:231], v[2:17]
	s_waitcnt vmcnt(0) lgkmcnt(0)
	s_barrier
	s_waitcnt lgkmcnt(0)
	v_mfma_f32_32x32x16_bf16 v[50:65], v[236:239], v[220:223], v[50:65]
	v_mov_b32_e32 v240, v226
	v_add_u32_e32 v228, v240, v224
	v_add_u32_e32 v240, v240, v225
	v_mfma_f32_32x32x16_bf16 v[34:49], v[244:247], v[220:223], v[34:49]
	ds_read_b128 v[220:223], v228 offset:16384
	ds_read_b128 v[228:231], v228 offset:20480
	s_add_u32 m0, s30, 0xc000
	s_nop 0
	global_load_lds_dwordx4 v248, s[54:55]
	s_add_u32 m0, s30, 0xd000
	s_nop 0
	global_load_lds_dwordx4 v249, s[54:55]
	v_mfma_f32_32x32x16_bf16 v[18:33], v[236:239], v[232:235], v[18:33]
	ds_read_b128 v[236:239], v240 offset:32768
	ds_read_b128 v[240:243], v240 offset:36864
	s_add_u32 m0, s30, 0xe000
	s_nop 0
	global_load_lds_dwordx4 v250, s[54:55]
	s_add_u32 m0, s30, 0xf000
	s_nop 0
	global_load_lds_dwordx4 v251, s[54:55]
	v_mfma_f32_32x32x16_bf16 v[2:17], v[244:247], v[232:235], v[2:17]
	s_add_u32 s54, s54, 0x80
	s_addc_u32 s55, s55, 0
	s_waitcnt lgkmcnt(0)
	v_mfma_f32_32x32x16_bf16 v[114:129], v[236:239], v[220:223], v[114:129]
	v_xor_b32_e32 v244, 0x20, v226
	v_add_u32_e32 v232, v244, v224
	v_add_u32_e32 v244, v244, v225
	v_mfma_f32_32x32x16_bf16 v[98:113], v[240:243], v[220:223], v[98:113]
	ds_read_b128 v[220:223], v232 offset:16384
	ds_read_b128 v[232:235], v232 offset:20480
	v_mfma_f32_32x32x16_bf16 v[82:97], v[236:239], v[228:231], v[82:97]
	ds_read_b128 v[236:239], v244 offset:32768
	ds_read_b128 v[244:247], v244 offset:36864
	v_mfma_f32_32x32x16_bf16 v[66:81], v[240:243], v[228:231], v[66:81]
	s_waitcnt lgkmcnt(0)
	v_mfma_f32_32x32x16_bf16 v[114:129], v[236:239], v[220:223], v[114:129]
	v_xor_b32_e32 v240, 0x40, v226
	v_add_u32_e32 v228, v240, v224
	v_add_u32_e32 v240, v240, v225
	v_mfma_f32_32x32x16_bf16 v[98:113], v[244:247], v[220:223], v[98:113]
	ds_read_b128 v[220:223], v228 offset:16384
	ds_read_b128 v[228:231], v228 offset:20480
	v_mfma_f32_32x32x16_bf16 v[82:97], v[236:239], v[232:235], v[82:97]
	ds_read_b128 v[236:239], v240 offset:32768
	ds_read_b128 v[240:243], v240 offset:36864
	v_mfma_f32_32x32x16_bf16 v[66:81], v[244:247], v[232:235], v[66:81]
	s_waitcnt lgkmcnt(0)
	v_mfma_f32_32x32x16_bf16 v[114:129], v[236:239], v[220:223], v[114:129]
	v_xor_b32_e32 v244, 0x60, v226
	v_add_u32_e32 v232, v244, v224
	v_add_u32_e32 v244, v244, v225
	v_mfma_f32_32x32x16_bf16 v[98:113], v[240:243], v[220:223], v[98:113]
	ds_read_b128 v[220:223], v232 offset:16384
	ds_read_b128 v[232:235], v232 offset:20480
	v_mfma_f32_32x32x16_bf16 v[82:97], v[236:239], v[228:231], v[82:97]
	ds_read_b128 v[236:239], v244 offset:32768
	ds_read_b128 v[244:247], v244 offset:36864
	v_mfma_f32_32x32x16_bf16 v[66:81], v[240:243], v[228:231], v[66:81]
	s_waitcnt vmcnt(0) lgkmcnt(0)
	s_barrier
	s_waitcnt lgkmcnt(0)
	v_mfma_f32_32x32x16_bf16 v[114:129], v[236:239], v[220:223], v[114:129]
	v_mov_b32_e32 v240, v226
	v_add_u32_e32 v228, v240, v224
	v_add_u32_e32 v240, v240, v225
	v_mfma_f32_32x32x16_bf16 v[98:113], v[244:247], v[220:223], v[98:113]
	ds_read_b128 v[220:223], v228 offset:16384
	ds_read_b128 v[228:231], v228 offset:20480
	s_add_u32 m0, s30, 0x8000
	s_nop 0
	global_load_lds_dwordx4 v248, s[100:101]
	s_add_u32 m0, s30, 0x9000
	s_nop 0
	global_load_lds_dwordx4 v249, s[100:101]
	v_mfma_f32_32x32x16_bf16 v[82:97], v[236:239], v[232:235], v[82:97]
	ds_read_b128 v[236:239], v240 offset:49152
	ds_read_b128 v[240:243], v240 offset:53248
	s_add_u32 m0, s30, 0xa000
	s_nop 0
	global_load_lds_dwordx4 v250, s[100:101]
	s_add_u32 m0, s30, 0xb000
	s_nop 0
	global_load_lds_dwordx4 v251, s[100:101]
	v_mfma_f32_32x32x16_bf16 v[66:81], v[244:247], v[232:235], v[66:81]
	s_add_u32 s100, s100, 0x80
	s_addc_u32 s101, s101, 0
	s_waitcnt lgkmcnt(0)
	v_mfma_f32_32x32x16_bf16 v[178:193], v[236:239], v[220:223], v[178:193]
	v_xor_b32_e32 v244, 0x20, v226
	v_add_u32_e32 v232, v244, v224
	v_add_u32_e32 v244, v244, v225
	v_mfma_f32_32x32x16_bf16 v[162:177], v[240:243], v[220:223], v[162:177]
	ds_read_b128 v[220:223], v232 offset:16384
	ds_read_b128 v[232:235], v232 offset:20480
	v_mfma_f32_32x32x16_bf16 v[146:161], v[236:239], v[228:231], v[146:161]
	ds_read_b128 v[236:239], v244 offset:49152
	ds_read_b128 v[244:247], v244 offset:53248
	v_mfma_f32_32x32x16_bf16 v[130:145], v[240:243], v[228:231], v[130:145]
	s_waitcnt lgkmcnt(0)
	v_mfma_f32_32x32x16_bf16 v[178:193], v[236:239], v[220:223], v[178:193]
	v_xor_b32_e32 v240, 0x40, v226
	v_add_u32_e32 v228, v240, v224
	v_add_u32_e32 v240, v240, v225
	v_mfma_f32_32x32x16_bf16 v[162:177], v[244:247], v[220:223], v[162:177]
	ds_read_b128 v[220:223], v228 offset:16384
	ds_read_b128 v[228:231], v228 offset:20480
	v_mfma_f32_32x32x16_bf16 v[146:161], v[236:239], v[232:235], v[146:161]
	ds_read_b128 v[236:239], v240 offset:49152
	ds_read_b128 v[240:243], v240 offset:53248
	v_mfma_f32_32x32x16_bf16 v[130:145], v[244:247], v[232:235], v[130:145]
	s_waitcnt lgkmcnt(0)
	v_mfma_f32_32x32x16_bf16 v[178:193], v[236:239], v[220:223], v[178:193]
	v_xor_b32_e32 v244, 0x60, v226
	v_add_u32_e32 v232, v244, v224
	v_add_u32_e32 v244, v244, v225
	v_mfma_f32_32x32x16_bf16 v[162:177], v[240:243], v[220:223], v[162:177]
	ds_read_b128 v[220:223], v232 offset:16384
	ds_read_b128 v[232:235], v232 offset:20480
	v_mfma_f32_32x32x16_bf16 v[146:161], v[236:239], v[228:231], v[146:161]
	ds_read_b128 v[236:239], v244 offset:49152
	ds_read_b128 v[244:247], v244 offset:53248
	v_mfma_f32_32x32x16_bf16 v[130:145], v[240:243], v[228:231], v[130:145]
	s_waitcnt vmcnt(0) lgkmcnt(0)
	s_barrier
	s_waitcnt lgkmcnt(0)
	v_mfma_f32_32x32x16_bf16 v[178:193], v[236:239], v[220:223], v[178:193]
	v_mov_b32_e32 v240, v226
	v_add_u32_e32 v228, v240, v224
	v_add_u32_e32 v240, v240, v225
	v_mfma_f32_32x32x16_bf16 v[162:177], v[244:247], v[220:223], v[162:177]
	ds_read_b128 v[220:223], v228
	ds_read_b128 v[228:231], v228 offset:4096
	s_add_u32 m0, s30, 0xc000
	s_nop 0
	global_load_lds_dwordx4 v248, s[52:53]
	s_add_u32 m0, s30, 0xd000
	s_nop 0
	global_load_lds_dwordx4 v249, s[52:53]
	v_mfma_f32_32x32x16_bf16 v[146:161], v[236:239], v[232:235], v[146:161]
	ds_read_b128 v[236:239], v240 offset:32768
	ds_read_b128 v[240:243], v240 offset:36864
	s_add_u32 m0, s30, 0xe000
	s_nop 0
	global_load_lds_dwordx4 v250, s[52:53]
	s_add_u32 m0, s30, 0xf000
	s_nop 0
	global_load_lds_dwordx4 v251, s[52:53]
	v_mfma_f32_32x32x16_bf16 v[130:145], v[244:247], v[232:235], v[130:145]
	s_add_u32 m0, s30, 0x4000
	s_nop 0
	global_load_lds_dwordx4 v248, s[98:99]
	s_add_u32 m0, s30, 0x5000
	s_nop 0
	global_load_lds_dwordx4 v249, s[98:99]
	s_add_u32 m0, s30, 0x6000
	s_nop 0
	global_load_lds_dwordx4 v250, s[98:99]
	s_add_u32 m0, s30, 0x7000
	s_nop 0
	global_load_lds_dwordx4 v251, s[98:99]
	s_add_u32 s52, s52, 0x80
	s_addc_u32 s53, s53, 0
	s_add_u32 s98, s98, 0x80
	s_addc_u32 s99, s99, 0
	s_sub_u32 s51, s51, 1
	s_cmp_lg_u32 s51, 0
	s_cbranch_scc1 .Lp4f_gloop
	s_waitcnt lgkmcnt(0)
	v_mfma_f32_32x32x16_bf16 v[50:65], v[236:239], v[220:223], v[50:65]
	v_xor_b32_e32 v244, 0x20, v226
	v_add_u32_e32 v232, v244, v224
	v_add_u32_e32 v244, v244, v225
	v_mfma_f32_32x32x16_bf16 v[34:49], v[240:243], v[220:223], v[34:49]
	ds_read_b128 v[220:223], v232
	ds_read_b128 v[232:235], v232 offset:4096
	v_mfma_f32_32x32x16_bf16 v[18:33], v[236:239], v[228:231], v[18:33]
	ds_read_b128 v[236:239], v244 offset:32768
	ds_read_b128 v[244:247], v244 offset:36864
	v_mfma_f32_32x32x16_bf16 v[2:17], v[240:243], v[228:231], v[2:17]
	s_waitcnt lgkmcnt(0)
	v_mfma_f32_32x32x16_bf16 v[50:65], v[236:239], v[220:223], v[50:65]
	v_xor_b32_e32 v240, 0x40, v226
	v_add_u32_e32 v228, v240, v224
	v_add_u32_e32 v240, v240, v225
	v_mfma_f32_32x32x16_bf16 v[34:49], v[244:247], v[220:223], v[34:49]
	ds_read_b128 v[220:223], v228
	ds_read_b128 v[228:231], v228 offset:4096
	v_mfma_f32_32x32x16_bf16 v[18:33], v[236:239], v[232:235], v[18:33]
	ds_read_b128 v[236:239], v240 offset:32768
	ds_read_b128 v[240:243], v240 offset:36864
	v_mfma_f32_32x32x16_bf16 v[2:17], v[244:247], v[232:235], v[2:17]
	s_waitcnt lgkmcnt(0)
	v_mfma_f32_32x32x16_bf16 v[50:65], v[236:239], v[220:223], v[50:65]
	v_xor_b32_e32 v244, 0x60, v226
	v_add_u32_e32 v232, v244, v224
	v_add_u32_e32 v244, v244, v225
	v_mfma_f32_32x32x16_bf16 v[34:49], v[240:243], v[220:223], v[34:49]
	ds_read_b128 v[220:223], v232
	ds_read_b128 v[232:235], v232 offset:4096
	v_mfma_f32_32x32x16_bf16 v[18:33], v[236:239], v[228:231], v[18:33]
	ds_read_b128 v[236:239], v244 offset:32768
	ds_read_b128 v[244:247], v244 offset:36864
	v_mfma_f32_32x32x16_bf16 v[2:17], v[240:243], v[228:231], v[2:17]
	s_waitcnt vmcnt(0) lgkmcnt(0)
	s_barrier
	s_waitcnt lgkmcnt(0)
	v_mfma_f32_32x32x16_bf16 v[50:65], v[236:239], v[220:223], v[50:65]
	v_mov_b32_e32 v240, v226
	v_add_u32_e32 v228, v240, v224
	v_add_u32_e32 v240, v240, v225
	v_mfma_f32_32x32x16_bf16 v[34:49], v[244:247], v[220:223], v[34:49]
	ds_read_b128 v[220:223], v228
	ds_read_b128 v[228:231], v228 offset:4096
	s_add_u32 m0, s30, 0x8000
	s_nop 0
	global_load_lds_dwordx4 v248, s[54:55]
	s_add_u32 m0, s30, 0x9000
	s_nop 0
	global_load_lds_dwordx4 v249, s[54:55]
	v_mfma_f32_32x32x16_bf16 v[18:33], v[236:239], v[232:235], v[18:33]
	ds_read_b128 v[236:239], v240 offset:49152
	ds_read_b128 v[240:243], v240 offset:53248
	s_add_u32 m0, s30, 0xa000
	s_nop 0
	global_load_lds_dwordx4 v250, s[54:55]
	s_add_u32 m0, s30, 0xb000
	s_nop 0
	global_load_lds_dwordx4 v251, s[54:55]
	v_mfma_f32_32x32x16_bf16 v[2:17], v[244:247], v[232:235], v[2:17]
	s_add_u32 s54, s54, 0x80
	s_addc_u32 s55, s55, 0
	s_waitcnt lgkmcnt(0)
	v_mfma_f32_32x32x16_bf16 v[114:129], v[236:239], v[220:223], v[114:129]
	v_xor_b32_e32 v244, 0x20, v226
	v_add_u32_e32 v232, v244, v224
	v_add_u32_e32 v244, v244, v225
	v_mfma_f32_32x32x16_bf16 v[98:113], v[240:243], v[220:223], v[98:113]
	ds_read_b128 v[220:223], v232
	ds_read_b128 v[232:235], v232 offset:4096
	v_mfma_f32_32x32x16_bf16 v[82:97], v[236:239], v[228:231], v[82:97]
	ds_read_b128 v[236:239], v244 offset:49152
	ds_read_b128 v[244:247], v244 offset:53248
	v_mfma_f32_32x32x16_bf16 v[66:81], v[240:243], v[228:231], v[66:81]
	s_waitcnt lgkmcnt(0)
	v_mfma_f32_32x32x16_bf16 v[114:129], v[236:239], v[220:223], v[114:129]
	v_xor_b32_e32 v240, 0x40, v226
	v_add_u32_e32 v228, v240, v224
	v_add_u32_e32 v240, v240, v225
	v_mfma_f32_32x32x16_bf16 v[98:113], v[244:247], v[220:223], v[98:113]
	ds_read_b128 v[220:223], v228
	ds_read_b128 v[228:231], v228 offset:4096
	v_mfma_f32_32x32x16_bf16 v[82:97], v[236:239], v[232:235], v[82:97]
	ds_read_b128 v[236:239], v240 offset:49152
	ds_read_b128 v[240:243], v240 offset:53248
	v_mfma_f32_32x32x16_bf16 v[66:81], v[244:247], v[232:235], v[66:81]
	s_waitcnt lgkmcnt(0)
	v_mfma_f32_32x32x16_bf16 v[114:129], v[236:239], v[220:223], v[114:129]
	v_xor_b32_e32 v244, 0x60, v226
	v_add_u32_e32 v232, v244, v224
	v_add_u32_e32 v244, v244, v225
	v_mfma_f32_32x32x16_bf16 v[98:113], v[240:243], v[220:223], v[98:113]
	ds_read_b128 v[220:223], v232
	ds_read_b128 v[232:235], v232 offset:4096
	v_mfma_f32_32x32x16_bf16 v[82:97], v[236:239], v[228:231], v[82:97]
	ds_read_b128 v[236:239], v244 offset:49152
	ds_read_b128 v[244:247], v244 offset:53248
	v_mfma_f32_32x32x16_bf16 v[66:81], v[240:243], v[228:231], v[66:81]
	s_waitcnt vmcnt(0) lgkmcnt(0)
	s_barrier
	s_waitcnt lgkmcnt(0)
	v_mfma_f32_32x32x16_bf16 v[114:129], v[236:239], v[220:223], v[114:129]
	v_mov_b32_e32 v240, v226
	v_add_u32_e32 v228, v240, v224
	v_add_u32_e32 v240, v240, v225
	v_mfma_f32_32x32x16_bf16 v[98:113], v[244:247], v[220:223], v[98:113]
	ds_read_b128 v[220:223], v228
	ds_read_b128 v[228:231], v228 offset:4096
	s_add_u32 m0, s30, 0xc000
	s_nop 0
	global_load_lds_dwordx4 v248, s[100:101]
	s_add_u32 m0, s30, 0xd000
	s_nop 0
	global_load_lds_dwordx4 v249, s[100:101]
	v_mfma_f32_32x32x16_bf16 v[82:97], v[236:239], v[232:235], v[82:97]
	ds_read_b128 v[236:239], v240 offset:32768
	ds_read_b128 v[240:243], v240 offset:36864
	s_add_u32 m0, s30, 0xe000
	s_nop 0
	global_load_lds_dwordx4 v250, s[100:101]
	s_add_u32 m0, s30, 0xf000
	s_nop 0
	global_load_lds_dwordx4 v251, s[100:101]
	v_mfma_f32_32x32x16_bf16 v[66:81], v[244:247], v[232:235], v[66:81]
	s_add_u32 s100, s100, 0x80
	s_addc_u32 s101, s101, 0
	s_waitcnt lgkmcnt(0)
	v_mfma_f32_32x32x16_bf16 v[178:193], v[236:239], v[220:223], v[178:193]
	v_xor_b32_e32 v244, 0x20, v226
	v_add_u32_e32 v232, v244, v224
	v_add_u32_e32 v244, v244, v225
	v_mfma_f32_32x32x16_bf16 v[162:177], v[240:243], v[220:223], v[162:177]
	ds_read_b128 v[220:223], v232
	ds_read_b128 v[232:235], v232 offset:4096
	v_mfma_f32_32x32x16_bf16 v[146:161], v[236:239], v[228:231], v[146:161]
	ds_read_b128 v[236:239], v244 offset:32768
	ds_read_b128 v[244:247], v244 offset:36864
	v_mfma_f32_32x32x16_bf16 v[130:145], v[240:243], v[228:231], v[130:145]
	s_waitcnt lgkmcnt(0)
	v_mfma_f32_32x32x16_bf16 v[178:193], v[236:239], v[220:223], v[178:193]
	v_xor_b32_e32 v240, 0x40, v226
	v_add_u32_e32 v228, v240, v224
	v_add_u32_e32 v240, v240, v225
	v_mfma_f32_32x32x16_bf16 v[162:177], v[244:247], v[220:223], v[162:177]
	ds_read_b128 v[220:223], v228
	ds_read_b128 v[228:231], v228 offset:4096
	v_mfma_f32_32x32x16_bf16 v[146:161], v[236:239], v[232:235], v[146:161]
	ds_read_b128 v[236:239], v240 offset:32768
	ds_read_b128 v[240:243], v240 offset:36864
	v_mfma_f32_32x32x16_bf16 v[130:145], v[244:247], v[232:235], v[130:145]
	s_waitcnt lgkmcnt(0)
	v_mfma_f32_32x32x16_bf16 v[178:193], v[236:239], v[220:223], v[178:193]
	v_xor_b32_e32 v244, 0x60, v226
	v_add_u32_e32 v232, v244, v224
	v_add_u32_e32 v244, v244, v225
	v_mfma_f32_32x32x16_bf16 v[162:177], v[240:243], v[220:223], v[162:177]
	ds_read_b128 v[220:223], v232
	ds_read_b128 v[232:235], v232 offset:4096
	v_mfma_f32_32x32x16_bf16 v[146:161], v[236:239], v[228:231], v[146:161]
	ds_read_b128 v[236:239], v244 offset:32768
	ds_read_b128 v[244:247], v244 offset:36864
	v_mfma_f32_32x32x16_bf16 v[130:145], v[240:243], v[228:231], v[130:145]
	s_waitcnt vmcnt(0) lgkmcnt(0)
	s_barrier
	s_waitcnt lgkmcnt(0)
	v_mfma_f32_32x32x16_bf16 v[178:193], v[236:239], v[220:223], v[178:193]
	v_mov_b32_e32 v240, v226
	v_add_u32_e32 v228, v240, v224
	v_add_u32_e32 v240, v240, v225
	v_mfma_f32_32x32x16_bf16 v[162:177], v[244:247], v[220:223], v[162:177]
	ds_read_b128 v[220:223], v228 offset:16384
	ds_read_b128 v[228:231], v228 offset:20480
	s_add_u32 m0, s30, 0x8000
	s_nop 0
	global_load_lds_dwordx4 v248, s[52:53]
	s_add_u32 m0, s30, 0x9000
	s_nop 0
	global_load_lds_dwordx4 v249, s[52:53]
	v_mfma_f32_32x32x16_bf16 v[146:161], v[236:239], v[232:235], v[146:161]
	ds_read_b128 v[236:239], v240 offset:49152
	ds_read_b128 v[240:243], v240 offset:53248
	s_add_u32 m0, s30, 0xa000
	s_nop 0
	global_load_lds_dwordx4 v250, s[52:53]
	s_add_u32 m0, s30, 0xb000
	s_nop 0
	global_load_lds_dwordx4 v251, s[52:53]
	v_mfma_f32_32x32x16_bf16 v[130:145], v[244:247], v[232:235], v[130:145]
	s_add_u32 s52, s52, 0x80
	s_addc_u32 s53, s53, 0
	s_waitcnt lgkmcnt(0)
	v_mfma_f32_32x32x16_bf16 v[50:65], v[236:239], v[220:223], v[50:65]
	v_xor_b32_e32 v244, 0x20, v226
	v_add_u32_e32 v232, v244, v224
	v_add_u32_e32 v244, v244, v225
	v_mfma_f32_32x32x16_bf16 v[34:49], v[240:243], v[220:223], v[34:49]
	ds_read_b128 v[220:223], v232 offset:16384
	ds_read_b128 v[232:235], v232 offset:20480
	v_mfma_f32_32x32x16_bf16 v[18:33], v[236:239], v[228:231], v[18:33]
	ds_read_b128 v[236:239], v244 offset:49152
	ds_read_b128 v[244:247], v244 offset:53248
	v_mfma_f32_32x32x16_bf16 v[2:17], v[240:243], v[228:231], v[2:17]
	s_waitcnt lgkmcnt(0)
	v_mfma_f32_32x32x16_bf16 v[50:65], v[236:239], v[220:223], v[50:65]
	v_xor_b32_e32 v240, 0x40, v226
	v_add_u32_e32 v228, v240, v224
	v_add_u32_e32 v240, v240, v225
	v_mfma_f32_32x32x16_bf16 v[34:49], v[244:247], v[220:223], v[34:49]
	ds_read_b128 v[220:223], v228 offset:16384
	ds_read_b128 v[228:231], v228 offset:20480
	v_mfma_f32_32x32x16_bf16 v[18:33], v[236:239], v[232:235], v[18:33]
	ds_read_b128 v[236:239], v240 offset:49152
	ds_read_b128 v[240:243], v240 offset:53248
	v_mfma_f32_32x32x16_bf16 v[2:17], v[244:247], v[232:235], v[2:17]
	s_waitcnt lgkmcnt(0)
	v_mfma_f32_32x32x16_bf16 v[50:65], v[236:239], v[220:223], v[50:65]
	v_xor_b32_e32 v244, 0x60, v226
	v_add_u32_e32 v232, v244, v224
	v_add_u32_e32 v244, v244, v225
	v_mfma_f32_32x32x16_bf16 v[34:49], v[240:243], v[220:223], v[34:49]
	ds_read_b128 v[220:223], v232 offset:16384
	ds_read_b128 v[232:235], v232 offset:20480
	v_mfma_f32_32x32x16_bf16 v[18:33], v[236:239], v[228:231], v[18:33]
	ds_read_b128 v[236:239], v244 offset:49152
	ds_read_b128 v[244:247], v244 offset:53248
	v_mfma_f32_32x32x16_bf16 v[2:17], v[240:243], v[228:231], v[2:17]
	s_waitcnt vmcnt(0) lgkmcnt(0)
	s_barrier
	s_waitcnt lgkmcnt(0)
	v_mfma_f32_32x32x16_bf16 v[50:65], v[236:239], v[220:223], v[50:65]
	v_mov_b32_e32 v240, v226
	v_add_u32_e32 v228, v240, v224
	v_add_u32_e32 v240, v240, v225
	v_mfma_f32_32x32x16_bf16 v[34:49], v[244:247], v[220:223], v[34:49]
	ds_read_b128 v[220:223], v228 offset:16384
	ds_read_b128 v[228:231], v228 offset:20480
	s_add_u32 m0, s30, 0xc000
	s_nop 0
	global_load_lds_dwordx4 v248, s[54:55]
	s_add_u32 m0, s30, 0xd000
	s_nop 0
	global_load_lds_dwordx4 v249, s[54:55]
	v_mfma_f32_32x32x16_bf16 v[18:33], v[236:239], v[232:235], v[18:33]
	ds_read_b128 v[236:239], v240 offset:32768
	ds_read_b128 v[240:243], v240 offset:36864
	s_add_u32 m0, s30, 0xe000
	s_nop 0
	global_load_lds_dwordx4 v250, s[54:55]
	s_add_u32 m0, s30, 0xf000
	s_nop 0
	global_load_lds_dwordx4 v251, s[54:55]
	v_mfma_f32_32x32x16_bf16 v[2:17], v[244:247], v[232:235], v[2:17]
	s_add_u32 s54, s54, 0x80
	s_addc_u32 s55, s55, 0
	s_waitcnt lgkmcnt(0)
	v_mfma_f32_32x32x16_bf16 v[114:129], v[236:239], v[220:223], v[114:129]
	v_xor_b32_e32 v244, 0x20, v226
	v_add_u32_e32 v232, v244, v224
	v_add_u32_e32 v244, v244, v225
	v_mfma_f32_32x32x16_bf16 v[98:113], v[240:243], v[220:223], v[98:113]
	ds_read_b128 v[220:223], v232 offset:16384
	ds_read_b128 v[232:235], v232 offset:20480
	v_mfma_f32_32x32x16_bf16 v[82:97], v[236:239], v[228:231], v[82:97]
	ds_read_b128 v[236:239], v244 offset:32768
	ds_read_b128 v[244:247], v244 offset:36864
	v_mfma_f32_32x32x16_bf16 v[66:81], v[240:243], v[228:231], v[66:81]
	s_waitcnt lgkmcnt(0)
	v_mfma_f32_32x32x16_bf16 v[114:129], v[236:239], v[220:223], v[114:129]
	v_xor_b32_e32 v240, 0x40, v226
	v_add_u32_e32 v228, v240, v224
	v_add_u32_e32 v240, v240, v225
	v_mfma_f32_32x32x16_bf16 v[98:113], v[244:247], v[220:223], v[98:113]
	ds_read_b128 v[220:223], v228 offset:16384
	ds_read_b128 v[228:231], v228 offset:20480
	v_mfma_f32_32x32x16_bf16 v[82:97], v[236:239], v[232:235], v[82:97]
	ds_read_b128 v[236:239], v240 offset:32768
	ds_read_b128 v[240:243], v240 offset:36864
	v_mfma_f32_32x32x16_bf16 v[66:81], v[244:247], v[232:235], v[66:81]
	s_waitcnt lgkmcnt(0)
	v_mfma_f32_32x32x16_bf16 v[114:129], v[236:239], v[220:223], v[114:129]
	v_xor_b32_e32 v244, 0x60, v226
	v_add_u32_e32 v232, v244, v224
	v_add_u32_e32 v244, v244, v225
	v_mfma_f32_32x32x16_bf16 v[98:113], v[240:243], v[220:223], v[98:113]
	ds_read_b128 v[220:223], v232 offset:16384
	ds_read_b128 v[232:235], v232 offset:20480
	v_mfma_f32_32x32x16_bf16 v[82:97], v[236:239], v[228:231], v[82:97]
	ds_read_b128 v[236:239], v244 offset:32768
	ds_read_b128 v[244:247], v244 offset:36864
	v_mfma_f32_32x32x16_bf16 v[66:81], v[240:243], v[228:231], v[66:81]
	s_add_u32 s98, s48, 0x0
	s_addc_u32 s99, s49, 0
	s_add_u32 s100, s44, 0x0
	s_addc_u32 s101, s45, 0
	s_waitcnt vmcnt(0) lgkmcnt(0)
	s_barrier
	s_waitcnt lgkmcnt(0)
	v_mfma_f32_32x32x16_bf16 v[114:129], v[236:239], v[220:223], v[114:129]
	v_mov_b32_e32 v240, v226
	v_add_u32_e32 v228, v240, v224
	v_add_u32_e32 v240, v240, v225
	v_mfma_f32_32x32x16_bf16 v[98:113], v[244:247], v[220:223], v[98:113]
	ds_read_b128 v[220:223], v228 offset:16384
	ds_read_b128 v[228:231], v228 offset:20480
	s_add_u32 m0, s30, 0x0
	s_nop 0
	global_load_lds_dwordx4 v200, s[98:99]
	s_add_u32 m0, s30, 0x1000
	s_nop 0
	global_load_lds_dwordx4 v201, s[98:99]
	v_mfma_f32_32x32x16_bf16 v[82:97], v[236:239], v[232:235], v[82:97]
	ds_read_b128 v[236:239], v240 offset:49152
	ds_read_b128 v[240:243], v240 offset:53248
	s_add_u32 m0, s30, 0x2000
	s_nop 0
	global_load_lds_dwordx4 v202, s[98:99]
	s_add_u32 m0, s30, 0x3000
	s_nop 0
	global_load_lds_dwordx4 v204, s[98:99]
	v_mfma_f32_32x32x16_bf16 v[66:81], v[244:247], v[232:235], v[66:81]
	s_add_u32 m0, s30, 0x8000
	s_nop 0
	global_load_lds_dwordx4 v200, s[100:101]
	s_add_u32 m0, s30, 0x9000
	s_nop 0
	global_load_lds_dwordx4 v201, s[100:101]
	s_add_u32 m0, s30, 0xa000
	s_nop 0
	global_load_lds_dwordx4 v202, s[100:101]
	s_add_u32 m0, s30, 0xb000
	s_nop 0
	global_load_lds_dwordx4 v204, s[100:101]
	s_add_u32 s98, s98, 0x80
	s_addc_u32 s99, s99, 0
	s_add_u32 s100, s100, 0x80
	s_addc_u32 s101, s101, 0
	s_waitcnt lgkmcnt(0)
	v_mfma_f32_32x32x16_bf16 v[178:193], v[236:239], v[220:223], v[178:193]
	v_xor_b32_e32 v244, 0x20, v226
	v_add_u32_e32 v232, v244, v224
	v_add_u32_e32 v244, v244, v225
	v_mfma_f32_32x32x16_bf16 v[162:177], v[240:243], v[220:223], v[162:177]
	ds_read_b128 v[220:223], v232 offset:16384
	ds_read_b128 v[232:235], v232 offset:20480
	v_mfma_f32_32x32x16_bf16 v[146:161], v[236:239], v[228:231], v[146:161]
	ds_read_b128 v[236:239], v244 offset:49152
	ds_read_b128 v[244:247], v244 offset:53248
	v_mfma_f32_32x32x16_bf16 v[130:145], v[240:243], v[228:231], v[130:145]
	s_waitcnt lgkmcnt(0)
	v_mfma_f32_32x32x16_bf16 v[178:193], v[236:239], v[220:223], v[178:193]
	v_xor_b32_e32 v240, 0x40, v226
	v_add_u32_e32 v228, v240, v224
	v_add_u32_e32 v240, v240, v225
	v_mfma_f32_32x32x16_bf16 v[162:177], v[244:247], v[220:223], v[162:177]
	ds_read_b128 v[220:223], v228 offset:16384
	ds_read_b128 v[228:231], v228 offset:20480
	v_mfma_f32_32x32x16_bf16 v[146:161], v[236:239], v[232:235], v[146:161]
	ds_read_b128 v[236:239], v240 offset:49152
	ds_read_b128 v[240:243], v240 offset:53248
	v_mfma_f32_32x32x16_bf16 v[130:145], v[244:247], v[232:235], v[130:145]
	s_waitcnt lgkmcnt(0)
	v_mfma_f32_32x32x16_bf16 v[178:193], v[236:239], v[220:223], v[178:193]
	v_xor_b32_e32 v244, 0x60, v226
	v_add_u32_e32 v232, v244, v224
	v_add_u32_e32 v244, v244, v225
	v_mfma_f32_32x32x16_bf16 v[162:177], v[240:243], v[220:223], v[162:177]
	ds_read_b128 v[220:223], v232 offset:16384
	ds_read_b128 v[232:235], v232 offset:20480
	v_mfma_f32_32x32x16_bf16 v[146:161], v[236:239], v[228:231], v[146:161]
	ds_read_b128 v[236:239], v244 offset:49152
	ds_read_b128 v[244:247], v244 offset:53248
	v_mfma_f32_32x32x16_bf16 v[130:145], v[240:243], v[228:231], v[130:145]
	s_waitcnt lgkmcnt(0)
	v_mfma_f32_32x32x16_bf16 v[178:193], v[236:239], v[220:223], v[178:193]
	v_mfma_f32_32x32x16_bf16 v[162:177], v[244:247], v[220:223], v[162:177]
	v_mfma_f32_32x32x16_bf16 v[146:161], v[236:239], v[232:235], v[146:161]
	v_mfma_f32_32x32x16_bf16 v[130:145], v[244:247], v[232:235], v[130:145]
	s_waitcnt lgkmcnt(0)
	s_barrier
	s_add_u32 m0, s30, 0x4000
	s_nop 0
	global_load_lds_dwordx4 v200, s[98:99]
	s_add_u32 m0, s30, 0x5000
	s_nop 0
	global_load_lds_dwordx4 v201, s[98:99]
	s_add_u32 m0, s30, 0x6000
	s_nop 0
	global_load_lds_dwordx4 v202, s[98:99]
	s_add_u32 m0, s30, 0x7000
	s_nop 0
	global_load_lds_dwordx4 v204, s[98:99]
	s_add_u32 m0, s30, 0xc000
	s_nop 0
	global_load_lds_dwordx4 v200, s[100:101]
	s_add_u32 m0, s30, 0xd000
	s_nop 0
	global_load_lds_dwordx4 v201, s[100:101]
	s_add_u32 m0, s30, 0xe000
	s_nop 0
	global_load_lds_dwordx4 v202, s[100:101]
	s_add_u32 m0, s30, 0xf000
	s_nop 0
	global_load_lds_dwordx4 v204, s[100:101]
	s_add_u32 s98, s98, 0x80
	s_addc_u32 s99, s99, 0
	s_add_u32 s100, s100, 0x80
	s_addc_u32 s101, s101, 0
	s_nop 7
	v_mul_f32_e32 v220, 0xbfb8aa3b, v192
	v_mul_f32_e32 v221, 0xbfb8aa3b, v193
	v_mul_f32_e32 v222, 0xbfb8aa3b, v190
	v_mul_f32_e32 v223, 0xbfb8aa3b, v191
	v_exp_f32_e32 v220, v220
	v_exp_f32_e32 v221, v221
	v_exp_f32_e32 v222, v222
	v_exp_f32_e32 v223, v223
	v_add_f32_e32 v220, 1.0, v220
	v_add_f32_e32 v221, 1.0, v221
	v_add_f32_e32 v222, 1.0, v222
	v_add_f32_e32 v223, 1.0, v223
	v_rcp_f32_e32 v228, v220
	v_rcp_f32_e32 v229, v221
	v_rcp_f32_e32 v230, v222
	v_rcp_f32_e32 v231, v223
	v_fma_f32 v232, -v220, v228, 1.0
	v_fma_f32 v233, -v221, v229, 1.0
	v_fma_f32 v234, -v222, v230, 1.0
	v_fma_f32 v235, -v223, v231, 1.0
	v_fmac_f32_e32 v228, v232, v228
	v_fmac_f32_e32 v229, v233, v229
	v_fmac_f32_e32 v230, v234, v230
	v_fmac_f32_e32 v231, v235, v231
	v_div_fixup_f32 v228, v228, v220, 1.0
	v_div_fixup_f32 v229, v229, v221, 1.0
	v_div_fixup_f32 v230, v230, v222, 1.0
	v_div_fixup_f32 v231, v231, v223, 1.0
	v_cvt_pk_bf16_f32 v193, v228, v229
	v_cvt_pk_bf16_f32 v192, v230, v231
	v_mul_f32_e32 v220, 0xbfb8aa3b, v188
	v_mul_f32_e32 v221, 0xbfb8aa3b, v189
	v_mul_f32_e32 v222, 0xbfb8aa3b, v186
	v_mul_f32_e32 v223, 0xbfb8aa3b, v187
	v_exp_f32_e32 v220, v220
	v_exp_f32_e32 v221, v221
	v_exp_f32_e32 v222, v222
	v_exp_f32_e32 v223, v223
	v_add_f32_e32 v220, 1.0, v220
	v_add_f32_e32 v221, 1.0, v221
	v_add_f32_e32 v222, 1.0, v222
	v_add_f32_e32 v223, 1.0, v223
	v_rcp_f32_e32 v228, v220
	v_rcp_f32_e32 v229, v221
	v_rcp_f32_e32 v230, v222
	v_rcp_f32_e32 v231, v223
	v_fma_f32 v232, -v220, v228, 1.0
	v_fma_f32 v233, -v221, v229, 1.0
	v_fma_f32 v234, -v222, v230, 1.0
	v_fma_f32 v235, -v223, v231, 1.0
	v_fmac_f32_e32 v228, v232, v228
	v_fmac_f32_e32 v229, v233, v229
	v_fmac_f32_e32 v230, v234, v230
	v_fmac_f32_e32 v231, v235, v231
	v_div_fixup_f32 v228, v228, v220, 1.0
	v_div_fixup_f32 v229, v229, v221, 1.0
	v_div_fixup_f32 v230, v230, v222, 1.0
	v_div_fixup_f32 v231, v231, v223, 1.0
	v_cvt_pk_bf16_f32 v191, v228, v229
	v_cvt_pk_bf16_f32 v190, v230, v231
	v_mul_f32_e32 v220, 0xbfb8aa3b, v184
	v_mul_f32_e32 v221, 0xbfb8aa3b, v185
	v_mul_f32_e32 v222, 0xbfb8aa3b, v182
	v_mul_f32_e32 v223, 0xbfb8aa3b, v183
	v_exp_f32_e32 v220, v220
	v_exp_f32_e32 v221, v221
	v_exp_f32_e32 v222, v222
	v_exp_f32_e32 v223, v223
	v_add_f32_e32 v220, 1.0, v220
	v_add_f32_e32 v221, 1.0, v221
	v_add_f32_e32 v222, 1.0, v222
	v_add_f32_e32 v223, 1.0, v223
	v_rcp_f32_e32 v228, v220
	v_rcp_f32_e32 v229, v221
	v_rcp_f32_e32 v230, v222
	v_rcp_f32_e32 v231, v223
	v_fma_f32 v232, -v220, v228, 1.0
	v_fma_f32 v233, -v221, v229, 1.0
	v_fma_f32 v234, -v222, v230, 1.0
	v_fma_f32 v235, -v223, v231, 1.0
	v_fmac_f32_e32 v228, v232, v228
	v_fmac_f32_e32 v229, v233, v229
	v_fmac_f32_e32 v230, v234, v230
	v_fmac_f32_e32 v231, v235, v231
	v_div_fixup_f32 v228, v228, v220, 1.0
	v_div_fixup_f32 v229, v229, v221, 1.0
	v_div_fixup_f32 v230, v230, v222, 1.0
	v_div_fixup_f32 v231, v231, v223, 1.0
	v_cvt_pk_bf16_f32 v189, v228, v229
	v_cvt_pk_bf16_f32 v188, v230, v231
	v_mul_f32_e32 v220, 0xbfb8aa3b, v180
	v_mul_f32_e32 v221, 0xbfb8aa3b, v181
	v_mul_f32_e32 v222, 0xbfb8aa3b, v178
	v_mul_f32_e32 v223, 0xbfb8aa3b, v179
	v_exp_f32_e32 v220, v220
	v_exp_f32_e32 v221, v221
	v_exp_f32_e32 v222, v222
	v_exp_f32_e32 v223, v223
	v_add_f32_e32 v220, 1.0, v220
	v_add_f32_e32 v221, 1.0, v221
	v_add_f32_e32 v222, 1.0, v222
	v_add_f32_e32 v223, 1.0, v223
	v_rcp_f32_e32 v228, v220
	v_rcp_f32_e32 v229, v221
	v_rcp_f32_e32 v230, v222
	v_rcp_f32_e32 v231, v223
	v_fma_f32 v232, -v220, v228, 1.0
	v_fma_f32 v233, -v221, v229, 1.0
	v_fma_f32 v234, -v222, v230, 1.0
	v_fma_f32 v235, -v223, v231, 1.0
	v_fmac_f32_e32 v228, v232, v228
	v_fmac_f32_e32 v229, v233, v229
	v_fmac_f32_e32 v230, v234, v230
	v_fmac_f32_e32 v231, v235, v231
	v_div_fixup_f32 v228, v228, v220, 1.0
	v_div_fixup_f32 v229, v229, v221, 1.0
	v_div_fixup_f32 v230, v230, v222, 1.0
	v_div_fixup_f32 v231, v231, v223, 1.0
	v_cvt_pk_bf16_f32 v187, v228, v229
	v_cvt_pk_bf16_f32 v186, v230, v231
	v_mul_f32_e32 v220, 0xbfb8aa3b, v176
	v_mul_f32_e32 v221, 0xbfb8aa3b, v177
	v_mul_f32_e32 v222, 0xbfb8aa3b, v174
	v_mul_f32_e32 v223, 0xbfb8aa3b, v175
	v_exp_f32_e32 v220, v220
	v_exp_f32_e32 v221, v221
	v_exp_f32_e32 v222, v222
	v_exp_f32_e32 v223, v223
	v_add_f32_e32 v220, 1.0, v220
	v_add_f32_e32 v221, 1.0, v221
	v_add_f32_e32 v222, 1.0, v222
	v_add_f32_e32 v223, 1.0, v223
	v_rcp_f32_e32 v228, v220
	v_rcp_f32_e32 v229, v221
	v_rcp_f32_e32 v230, v222
	v_rcp_f32_e32 v231, v223
	v_fma_f32 v232, -v220, v228, 1.0
	v_fma_f32 v233, -v221, v229, 1.0
	v_fma_f32 v234, -v222, v230, 1.0
	v_fma_f32 v235, -v223, v231, 1.0
	v_fmac_f32_e32 v228, v232, v228
	v_fmac_f32_e32 v229, v233, v229
	v_fmac_f32_e32 v230, v234, v230
	v_fmac_f32_e32 v231, v235, v231
	v_div_fixup_f32 v228, v228, v220, 1.0
	v_div_fixup_f32 v229, v229, v221, 1.0
	v_div_fixup_f32 v230, v230, v222, 1.0
	v_div_fixup_f32 v231, v231, v223, 1.0
	v_cvt_pk_bf16_f32 v185, v228, v229
	v_cvt_pk_bf16_f32 v184, v230, v231
	v_mul_f32_e32 v220, 0xbfb8aa3b, v172
	v_mul_f32_e32 v221, 0xbfb8aa3b, v173
	v_mul_f32_e32 v222, 0xbfb8aa3b, v170
	v_mul_f32_e32 v223, 0xbfb8aa3b, v171
	v_exp_f32_e32 v220, v220
	v_exp_f32_e32 v221, v221
	v_exp_f32_e32 v222, v222
	v_exp_f32_e32 v223, v223
	v_add_f32_e32 v220, 1.0, v220
	v_add_f32_e32 v221, 1.0, v221
	v_add_f32_e32 v222, 1.0, v222
	v_add_f32_e32 v223, 1.0, v223
	v_rcp_f32_e32 v228, v220
	v_rcp_f32_e32 v229, v221
	v_rcp_f32_e32 v230, v222
	v_rcp_f32_e32 v231, v223
	v_fma_f32 v232, -v220, v228, 1.0
	v_fma_f32 v233, -v221, v229, 1.0
	v_fma_f32 v234, -v222, v230, 1.0
	v_fma_f32 v235, -v223, v231, 1.0
	v_fmac_f32_e32 v228, v232, v228
	v_fmac_f32_e32 v229, v233, v229
	v_fmac_f32_e32 v230, v234, v230
	v_fmac_f32_e32 v231, v235, v231
	v_div_fixup_f32 v228, v228, v220, 1.0
	v_div_fixup_f32 v229, v229, v221, 1.0
	v_div_fixup_f32 v230, v230, v222, 1.0
	v_div_fixup_f32 v231, v231, v223, 1.0
	v_cvt_pk_bf16_f32 v183, v228, v229
	v_cvt_pk_bf16_f32 v182, v230, v231
	v_mul_f32_e32 v220, 0xbfb8aa3b, v168
	v_mul_f32_e32 v221, 0xbfb8aa3b, v169
	v_mul_f32_e32 v222, 0xbfb8aa3b, v166
	v_mul_f32_e32 v223, 0xbfb8aa3b, v167
	v_exp_f32_e32 v220, v220
	v_exp_f32_e32 v221, v221
	v_exp_f32_e32 v222, v222
	v_exp_f32_e32 v223, v223
	v_add_f32_e32 v220, 1.0, v220
	v_add_f32_e32 v221, 1.0, v221
	v_add_f32_e32 v222, 1.0, v222
	v_add_f32_e32 v223, 1.0, v223
	v_rcp_f32_e32 v228, v220
	v_rcp_f32_e32 v229, v221
	v_rcp_f32_e32 v230, v222
	v_rcp_f32_e32 v231, v223
	v_fma_f32 v232, -v220, v228, 1.0
	v_fma_f32 v233, -v221, v229, 1.0
	v_fma_f32 v234, -v222, v230, 1.0
	v_fma_f32 v235, -v223, v231, 1.0
	v_fmac_f32_e32 v228, v232, v228
	v_fmac_f32_e32 v229, v233, v229
	v_fmac_f32_e32 v230, v234, v230
	v_fmac_f32_e32 v231, v235, v231
	v_div_fixup_f32 v228, v228, v220, 1.0
	v_div_fixup_f32 v229, v229, v221, 1.0
	v_div_fixup_f32 v230, v230, v222, 1.0
	v_div_fixup_f32 v231, v231, v223, 1.0
	v_cvt_pk_bf16_f32 v181, v228, v229
	v_cvt_pk_bf16_f32 v180, v230, v231
	v_mul_f32_e32 v220, 0xbfb8aa3b, v164
	v_mul_f32_e32 v221, 0xbfb8aa3b, v165
	v_mul_f32_e32 v222, 0xbfb8aa3b, v162
	v_mul_f32_e32 v223, 0xbfb8aa3b, v163
	v_exp_f32_e32 v220, v220
	v_exp_f32_e32 v221, v221
	v_exp_f32_e32 v222, v222
	v_exp_f32_e32 v223, v223
	v_add_f32_e32 v220, 1.0, v220
	v_add_f32_e32 v221, 1.0, v221
	v_add_f32_e32 v222, 1.0, v222
	v_add_f32_e32 v223, 1.0, v223
	v_rcp_f32_e32 v228, v220
	v_rcp_f32_e32 v229, v221
	v_rcp_f32_e32 v230, v222
	v_rcp_f32_e32 v231, v223
	v_fma_f32 v232, -v220, v228, 1.0
	v_fma_f32 v233, -v221, v229, 1.0
	v_fma_f32 v234, -v222, v230, 1.0
	v_fma_f32 v235, -v223, v231, 1.0
	v_fmac_f32_e32 v228, v232, v228
	v_fmac_f32_e32 v229, v233, v229
	v_fmac_f32_e32 v230, v234, v230
	v_fmac_f32_e32 v231, v235, v231
	v_div_fixup_f32 v228, v228, v220, 1.0
	v_div_fixup_f32 v229, v229, v221, 1.0
	v_div_fixup_f32 v230, v230, v222, 1.0
	v_div_fixup_f32 v231, v231, v223, 1.0
	v_cvt_pk_bf16_f32 v179, v228, v229
	v_cvt_pk_bf16_f32 v178, v230, v231
	v_mul_f32_e32 v220, 0xbfb8aa3b, v160
	v_mul_f32_e32 v221, 0xbfb8aa3b, v161
	v_mul_f32_e32 v222, 0xbfb8aa3b, v158
	v_mul_f32_e32 v223, 0xbfb8aa3b, v159
	v_exp_f32_e32 v220, v220
	v_exp_f32_e32 v221, v221
	v_exp_f32_e32 v222, v222
	v_exp_f32_e32 v223, v223
	v_add_f32_e32 v220, 1.0, v220
	v_add_f32_e32 v221, 1.0, v221
	v_add_f32_e32 v222, 1.0, v222
	v_add_f32_e32 v223, 1.0, v223
	v_rcp_f32_e32 v228, v220
	v_rcp_f32_e32 v229, v221
	v_rcp_f32_e32 v230, v222
	v_rcp_f32_e32 v231, v223
	v_fma_f32 v232, -v220, v228, 1.0
	v_fma_f32 v233, -v221, v229, 1.0
	v_fma_f32 v234, -v222, v230, 1.0
	v_fma_f32 v235, -v223, v231, 1.0
	v_fmac_f32_e32 v228, v232, v228
	v_fmac_f32_e32 v229, v233, v229
	v_fmac_f32_e32 v230, v234, v230
	v_fmac_f32_e32 v231, v235, v231
	v_div_fixup_f32 v228, v228, v220, 1.0
	v_div_fixup_f32 v229, v229, v221, 1.0
	v_div_fixup_f32 v230, v230, v222, 1.0
	v_div_fixup_f32 v231, v231, v223, 1.0
	v_cvt_pk_bf16_f32 v177, v228, v229
	v_cvt_pk_bf16_f32 v176, v230, v231
	v_mul_f32_e32 v220, 0xbfb8aa3b, v156
	v_mul_f32_e32 v221, 0xbfb8aa3b, v157
	v_mul_f32_e32 v222, 0xbfb8aa3b, v154
	v_mul_f32_e32 v223, 0xbfb8aa3b, v155
	v_exp_f32_e32 v220, v220
	v_exp_f32_e32 v221, v221
	v_exp_f32_e32 v222, v222
	v_exp_f32_e32 v223, v223
	v_add_f32_e32 v220, 1.0, v220
	v_add_f32_e32 v221, 1.0, v221
	v_add_f32_e32 v222, 1.0, v222
	v_add_f32_e32 v223, 1.0, v223
	v_rcp_f32_e32 v228, v220
	v_rcp_f32_e32 v229, v221
	v_rcp_f32_e32 v230, v222
	v_rcp_f32_e32 v231, v223
	v_fma_f32 v232, -v220, v228, 1.0
	v_fma_f32 v233, -v221, v229, 1.0
	v_fma_f32 v234, -v222, v230, 1.0
	v_fma_f32 v235, -v223, v231, 1.0
	v_fmac_f32_e32 v228, v232, v228
	v_fmac_f32_e32 v229, v233, v229
	v_fmac_f32_e32 v230, v234, v230
	v_fmac_f32_e32 v231, v235, v231
	v_div_fixup_f32 v228, v228, v220, 1.0
	v_div_fixup_f32 v229, v229, v221, 1.0
	v_div_fixup_f32 v230, v230, v222, 1.0
	v_div_fixup_f32 v231, v231, v223, 1.0
	v_cvt_pk_bf16_f32 v175, v228, v229
	v_cvt_pk_bf16_f32 v174, v230, v231
	v_mul_f32_e32 v220, 0xbfb8aa3b, v152
	v_mul_f32_e32 v221, 0xbfb8aa3b, v153
	v_mul_f32_e32 v222, 0xbfb8aa3b, v150
	v_mul_f32_e32 v223, 0xbfb8aa3b, v151
	v_exp_f32_e32 v220, v220
	v_exp_f32_e32 v221, v221
	v_exp_f32_e32 v222, v222
	v_exp_f32_e32 v223, v223
	v_add_f32_e32 v220, 1.0, v220
	v_add_f32_e32 v221, 1.0, v221
	v_add_f32_e32 v222, 1.0, v222
	v_add_f32_e32 v223, 1.0, v223
	v_rcp_f32_e32 v228, v220
	v_rcp_f32_e32 v229, v221
	v_rcp_f32_e32 v230, v222
	v_rcp_f32_e32 v231, v223
	v_fma_f32 v232, -v220, v228, 1.0
	v_fma_f32 v233, -v221, v229, 1.0
	v_fma_f32 v234, -v222, v230, 1.0
	v_fma_f32 v235, -v223, v231, 1.0
	v_fmac_f32_e32 v228, v232, v228
	v_fmac_f32_e32 v229, v233, v229
	v_fmac_f32_e32 v230, v234, v230
	v_fmac_f32_e32 v231, v235, v231
	v_div_fixup_f32 v228, v228, v220, 1.0
	v_div_fixup_f32 v229, v229, v221, 1.0
	v_div_fixup_f32 v230, v230, v222, 1.0
	v_div_fixup_f32 v231, v231, v223, 1.0
	v_cvt_pk_bf16_f32 v173, v228, v229
	v_cvt_pk_bf16_f32 v172, v230, v231
	v_mul_f32_e32 v220, 0xbfb8aa3b, v148
	v_mul_f32_e32 v221, 0xbfb8aa3b, v149
	v_mul_f32_e32 v222, 0xbfb8aa3b, v146
	v_mul_f32_e32 v223, 0xbfb8aa3b, v147
	v_exp_f32_e32 v220, v220
	v_exp_f32_e32 v221, v221
	v_exp_f32_e32 v222, v222
	v_exp_f32_e32 v223, v223
	v_add_f32_e32 v220, 1.0, v220
	v_add_f32_e32 v221, 1.0, v221
	v_add_f32_e32 v222, 1.0, v222
	v_add_f32_e32 v223, 1.0, v223
	v_rcp_f32_e32 v228, v220
	v_rcp_f32_e32 v229, v221
	v_rcp_f32_e32 v230, v222
	v_rcp_f32_e32 v231, v223
	v_fma_f32 v232, -v220, v228, 1.0
	v_fma_f32 v233, -v221, v229, 1.0
	v_fma_f32 v234, -v222, v230, 1.0
	v_fma_f32 v235, -v223, v231, 1.0
	v_fmac_f32_e32 v228, v232, v228
	v_fmac_f32_e32 v229, v233, v229
	v_fmac_f32_e32 v230, v234, v230
	v_fmac_f32_e32 v231, v235, v231
	v_div_fixup_f32 v228, v228, v220, 1.0
	v_div_fixup_f32 v229, v229, v221, 1.0
	v_div_fixup_f32 v230, v230, v222, 1.0
	v_div_fixup_f32 v231, v231, v223, 1.0
	v_cvt_pk_bf16_f32 v171, v228, v229
	v_cvt_pk_bf16_f32 v170, v230, v231
	v_mul_f32_e32 v220, 0xbfb8aa3b, v144
	v_mul_f32_e32 v221, 0xbfb8aa3b, v145
	v_mul_f32_e32 v222, 0xbfb8aa3b, v142
	v_mul_f32_e32 v223, 0xbfb8aa3b, v143
	v_exp_f32_e32 v220, v220
	v_exp_f32_e32 v221, v221
	v_exp_f32_e32 v222, v222
	v_exp_f32_e32 v223, v223
	v_add_f32_e32 v220, 1.0, v220
	v_add_f32_e32 v221, 1.0, v221
	v_add_f32_e32 v222, 1.0, v222
	v_add_f32_e32 v223, 1.0, v223
	v_rcp_f32_e32 v228, v220
	v_rcp_f32_e32 v229, v221
	v_rcp_f32_e32 v230, v222
	v_rcp_f32_e32 v231, v223
	v_fma_f32 v232, -v220, v228, 1.0
	v_fma_f32 v233, -v221, v229, 1.0
	v_fma_f32 v234, -v222, v230, 1.0
	v_fma_f32 v235, -v223, v231, 1.0
	v_fmac_f32_e32 v228, v232, v228
	v_fmac_f32_e32 v229, v233, v229
	v_fmac_f32_e32 v230, v234, v230
	v_fmac_f32_e32 v231, v235, v231
	v_div_fixup_f32 v228, v228, v220, 1.0
	v_div_fixup_f32 v229, v229, v221, 1.0
	v_div_fixup_f32 v230, v230, v222, 1.0
	v_div_fixup_f32 v231, v231, v223, 1.0
	v_cvt_pk_bf16_f32 v169, v228, v229
	v_cvt_pk_bf16_f32 v168, v230, v231
	v_mul_f32_e32 v220, 0xbfb8aa3b, v140
	v_mul_f32_e32 v221, 0xbfb8aa3b, v141
	v_mul_f32_e32 v222, 0xbfb8aa3b, v138
	v_mul_f32_e32 v223, 0xbfb8aa3b, v139
	v_exp_f32_e32 v220, v220
	v_exp_f32_e32 v221, v221
	v_exp_f32_e32 v222, v222
	v_exp_f32_e32 v223, v223
	v_add_f32_e32 v220, 1.0, v220
	v_add_f32_e32 v221, 1.0, v221
	v_add_f32_e32 v222, 1.0, v222
	v_add_f32_e32 v223, 1.0, v223
	v_rcp_f32_e32 v228, v220
	v_rcp_f32_e32 v229, v221
	v_rcp_f32_e32 v230, v222
	v_rcp_f32_e32 v231, v223
	v_fma_f32 v232, -v220, v228, 1.0
	v_fma_f32 v233, -v221, v229, 1.0
	v_fma_f32 v234, -v222, v230, 1.0
	v_fma_f32 v235, -v223, v231, 1.0
	v_fmac_f32_e32 v228, v232, v228
	v_fmac_f32_e32 v229, v233, v229
	v_fmac_f32_e32 v230, v234, v230
	v_fmac_f32_e32 v231, v235, v231
	v_div_fixup_f32 v228, v228, v220, 1.0
	v_div_fixup_f32 v229, v229, v221, 1.0
	v_div_fixup_f32 v230, v230, v222, 1.0
	v_div_fixup_f32 v231, v231, v223, 1.0
	v_cvt_pk_bf16_f32 v167, v228, v229
	v_cvt_pk_bf16_f32 v166, v230, v231
	v_mul_f32_e32 v220, 0xbfb8aa3b, v136
	v_mul_f32_e32 v221, 0xbfb8aa3b, v137
	v_mul_f32_e32 v222, 0xbfb8aa3b, v134
	v_mul_f32_e32 v223, 0xbfb8aa3b, v135
	v_exp_f32_e32 v220, v220
	v_exp_f32_e32 v221, v221
	v_exp_f32_e32 v222, v222
	v_exp_f32_e32 v223, v223
	v_add_f32_e32 v220, 1.0, v220
	v_add_f32_e32 v221, 1.0, v221
	v_add_f32_e32 v222, 1.0, v222
	v_add_f32_e32 v223, 1.0, v223
	v_rcp_f32_e32 v228, v220
	v_rcp_f32_e32 v229, v221
	v_rcp_f32_e32 v230, v222
	v_rcp_f32_e32 v231, v223
	v_fma_f32 v232, -v220, v228, 1.0
	v_fma_f32 v233, -v221, v229, 1.0
	v_fma_f32 v234, -v222, v230, 1.0
	v_fma_f32 v235, -v223, v231, 1.0
	v_fmac_f32_e32 v228, v232, v228
	v_fmac_f32_e32 v229, v233, v229
	v_fmac_f32_e32 v230, v234, v230
	v_fmac_f32_e32 v231, v235, v231
	v_div_fixup_f32 v228, v228, v220, 1.0
	v_div_fixup_f32 v229, v229, v221, 1.0
	v_div_fixup_f32 v230, v230, v222, 1.0
	v_div_fixup_f32 v231, v231, v223, 1.0
	v_cvt_pk_bf16_f32 v165, v228, v229
	v_cvt_pk_bf16_f32 v164, v230, v231
	v_mul_f32_e32 v220, 0xbfb8aa3b, v132
	v_mul_f32_e32 v221, 0xbfb8aa3b, v133
	v_mul_f32_e32 v222, 0xbfb8aa3b, v130
	v_mul_f32_e32 v223, 0xbfb8aa3b, v131
	v_exp_f32_e32 v220, v220
	v_exp_f32_e32 v221, v221
	v_exp_f32_e32 v222, v222
	v_exp_f32_e32 v223, v223
	v_add_f32_e32 v220, 1.0, v220
	v_add_f32_e32 v221, 1.0, v221
	v_add_f32_e32 v222, 1.0, v222
	v_add_f32_e32 v223, 1.0, v223
	v_rcp_f32_e32 v228, v220
	v_rcp_f32_e32 v229, v221
	v_rcp_f32_e32 v230, v222
	v_rcp_f32_e32 v231, v223
	v_fma_f32 v232, -v220, v228, 1.0
	v_fma_f32 v233, -v221, v229, 1.0
	v_fma_f32 v234, -v222, v230, 1.0
	v_fma_f32 v235, -v223, v231, 1.0
	v_fmac_f32_e32 v228, v232, v228
	v_fmac_f32_e32 v229, v233, v229
	v_fmac_f32_e32 v230, v234, v230
	v_fmac_f32_e32 v231, v235, v231
	v_div_fixup_f32 v228, v228, v220, 1.0
	v_div_fixup_f32 v229, v229, v221, 1.0
	v_div_fixup_f32 v230, v230, v222, 1.0
	v_div_fixup_f32 v231, v231, v223, 1.0
	v_cvt_pk_bf16_f32 v163, v228, v229
	v_cvt_pk_bf16_f32 v162, v230, v231
	v_mul_f32_e32 v220, 0xbfb8aa3b, v128
	v_mul_f32_e32 v221, 0xbfb8aa3b, v129
	v_mul_f32_e32 v222, 0xbfb8aa3b, v126
	v_mul_f32_e32 v223, 0xbfb8aa3b, v127
	v_exp_f32_e32 v220, v220
	v_exp_f32_e32 v221, v221
	v_exp_f32_e32 v222, v222
	v_exp_f32_e32 v223, v223
	v_add_f32_e32 v220, 1.0, v220
	v_add_f32_e32 v221, 1.0, v221
	v_add_f32_e32 v222, 1.0, v222
	v_add_f32_e32 v223, 1.0, v223
	v_rcp_f32_e32 v228, v220
	v_rcp_f32_e32 v229, v221
	v_rcp_f32_e32 v230, v222
	v_rcp_f32_e32 v231, v223
	v_fma_f32 v232, -v220, v228, 1.0
	v_fma_f32 v233, -v221, v229, 1.0
	v_fma_f32 v234, -v222, v230, 1.0
	v_fma_f32 v235, -v223, v231, 1.0
	v_fmac_f32_e32 v228, v232, v228
	v_fmac_f32_e32 v229, v233, v229
	v_fmac_f32_e32 v230, v234, v230
	v_fmac_f32_e32 v231, v235, v231
	v_div_fixup_f32 v228, v228, v220, 1.0
	v_div_fixup_f32 v229, v229, v221, 1.0
	v_div_fixup_f32 v230, v230, v222, 1.0
	v_div_fixup_f32 v231, v231, v223, 1.0
	v_cvt_pk_bf16_f32 v161, v228, v229
	v_cvt_pk_bf16_f32 v160, v230, v231
	v_mul_f32_e32 v220, 0xbfb8aa3b, v124
	v_mul_f32_e32 v221, 0xbfb8aa3b, v125
	v_mul_f32_e32 v222, 0xbfb8aa3b, v122
	v_mul_f32_e32 v223, 0xbfb8aa3b, v123
	v_exp_f32_e32 v220, v220
	v_exp_f32_e32 v221, v221
	v_exp_f32_e32 v222, v222
	v_exp_f32_e32 v223, v223
	v_add_f32_e32 v220, 1.0, v220
	v_add_f32_e32 v221, 1.0, v221
	v_add_f32_e32 v222, 1.0, v222
	v_add_f32_e32 v223, 1.0, v223
	v_rcp_f32_e32 v228, v220
	v_rcp_f32_e32 v229, v221
	v_rcp_f32_e32 v230, v222
	v_rcp_f32_e32 v231, v223
	v_fma_f32 v232, -v220, v228, 1.0
	v_fma_f32 v233, -v221, v229, 1.0
	v_fma_f32 v234, -v222, v230, 1.0
	v_fma_f32 v235, -v223, v231, 1.0
	v_fmac_f32_e32 v228, v232, v228
	v_fmac_f32_e32 v229, v233, v229
	v_fmac_f32_e32 v230, v234, v230
	v_fmac_f32_e32 v231, v235, v231
	v_div_fixup_f32 v228, v228, v220, 1.0
	v_div_fixup_f32 v229, v229, v221, 1.0
	v_div_fixup_f32 v230, v230, v222, 1.0
	v_div_fixup_f32 v231, v231, v223, 1.0
	v_cvt_pk_bf16_f32 v159, v228, v229
	v_cvt_pk_bf16_f32 v158, v230, v231
	v_mul_f32_e32 v220, 0xbfb8aa3b, v120
	v_mul_f32_e32 v221, 0xbfb8aa3b, v121
	v_mul_f32_e32 v222, 0xbfb8aa3b, v118
	v_mul_f32_e32 v223, 0xbfb8aa3b, v119
	v_exp_f32_e32 v220, v220
	v_exp_f32_e32 v221, v221
	v_exp_f32_e32 v222, v222
	v_exp_f32_e32 v223, v223
	v_add_f32_e32 v220, 1.0, v220
	v_add_f32_e32 v221, 1.0, v221
	v_add_f32_e32 v222, 1.0, v222
	v_add_f32_e32 v223, 1.0, v223
	v_rcp_f32_e32 v228, v220
	v_rcp_f32_e32 v229, v221
	v_rcp_f32_e32 v230, v222
	v_rcp_f32_e32 v231, v223
	v_fma_f32 v232, -v220, v228, 1.0
	v_fma_f32 v233, -v221, v229, 1.0
	v_fma_f32 v234, -v222, v230, 1.0
	v_fma_f32 v235, -v223, v231, 1.0
	v_fmac_f32_e32 v228, v232, v228
	v_fmac_f32_e32 v229, v233, v229
	v_fmac_f32_e32 v230, v234, v230
	v_fmac_f32_e32 v231, v235, v231
	v_div_fixup_f32 v228, v228, v220, 1.0
	v_div_fixup_f32 v229, v229, v221, 1.0
	v_div_fixup_f32 v230, v230, v222, 1.0
	v_div_fixup_f32 v231, v231, v223, 1.0
	v_cvt_pk_bf16_f32 v157, v228, v229
	v_cvt_pk_bf16_f32 v156, v230, v231
	v_mul_f32_e32 v220, 0xbfb8aa3b, v116
	v_mul_f32_e32 v221, 0xbfb8aa3b, v117
	v_mul_f32_e32 v222, 0xbfb8aa3b, v114
	v_mul_f32_e32 v223, 0xbfb8aa3b, v115
	v_exp_f32_e32 v220, v220
	v_exp_f32_e32 v221, v221
	v_exp_f32_e32 v222, v222
	v_exp_f32_e32 v223, v223
	v_add_f32_e32 v220, 1.0, v220
	v_add_f32_e32 v221, 1.0, v221
	v_add_f32_e32 v222, 1.0, v222
	v_add_f32_e32 v223, 1.0, v223
	v_rcp_f32_e32 v228, v220
	v_rcp_f32_e32 v229, v221
	v_rcp_f32_e32 v230, v222
	v_rcp_f32_e32 v231, v223
	v_fma_f32 v232, -v220, v228, 1.0
	v_fma_f32 v233, -v221, v229, 1.0
	v_fma_f32 v234, -v222, v230, 1.0
	v_fma_f32 v235, -v223, v231, 1.0
	v_fmac_f32_e32 v228, v232, v228
	v_fmac_f32_e32 v229, v233, v229
	v_fmac_f32_e32 v230, v234, v230
	v_fmac_f32_e32 v231, v235, v231
	v_div_fixup_f32 v228, v228, v220, 1.0
	v_div_fixup_f32 v229, v229, v221, 1.0
	v_div_fixup_f32 v230, v230, v222, 1.0
	v_div_fixup_f32 v231, v231, v223, 1.0
	v_cvt_pk_bf16_f32 v155, v228, v229
	v_cvt_pk_bf16_f32 v154, v230, v231
	v_mul_f32_e32 v220, 0xbfb8aa3b, v112
	v_mul_f32_e32 v221, 0xbfb8aa3b, v113
	v_mul_f32_e32 v222, 0xbfb8aa3b, v110
	v_mul_f32_e32 v223, 0xbfb8aa3b, v111
	v_exp_f32_e32 v220, v220
	v_exp_f32_e32 v221, v221
	v_exp_f32_e32 v222, v222
	v_exp_f32_e32 v223, v223
	v_add_f32_e32 v220, 1.0, v220
	v_add_f32_e32 v221, 1.0, v221
	v_add_f32_e32 v222, 1.0, v222
	v_add_f32_e32 v223, 1.0, v223
	v_rcp_f32_e32 v228, v220
	v_rcp_f32_e32 v229, v221
	v_rcp_f32_e32 v230, v222
	v_rcp_f32_e32 v231, v223
	v_fma_f32 v232, -v220, v228, 1.0
	v_fma_f32 v233, -v221, v229, 1.0
	v_fma_f32 v234, -v222, v230, 1.0
	v_fma_f32 v235, -v223, v231, 1.0
	v_fmac_f32_e32 v228, v232, v228
	v_fmac_f32_e32 v229, v233, v229
	v_fmac_f32_e32 v230, v234, v230
	v_fmac_f32_e32 v231, v235, v231
	v_div_fixup_f32 v228, v228, v220, 1.0
	v_div_fixup_f32 v229, v229, v221, 1.0
	v_div_fixup_f32 v230, v230, v222, 1.0
	v_div_fixup_f32 v231, v231, v223, 1.0
	v_cvt_pk_bf16_f32 v153, v228, v229
	v_cvt_pk_bf16_f32 v152, v230, v231
	v_mul_f32_e32 v220, 0xbfb8aa3b, v108
	v_mul_f32_e32 v221, 0xbfb8aa3b, v109
	v_mul_f32_e32 v222, 0xbfb8aa3b, v106
	v_mul_f32_e32 v223, 0xbfb8aa3b, v107
	v_exp_f32_e32 v220, v220
	v_exp_f32_e32 v221, v221
	v_exp_f32_e32 v222, v222
	v_exp_f32_e32 v223, v223
	v_add_f32_e32 v220, 1.0, v220
	v_add_f32_e32 v221, 1.0, v221
	v_add_f32_e32 v222, 1.0, v222
	v_add_f32_e32 v223, 1.0, v223
	v_rcp_f32_e32 v228, v220
	v_rcp_f32_e32 v229, v221
	v_rcp_f32_e32 v230, v222
	v_rcp_f32_e32 v231, v223
	v_fma_f32 v232, -v220, v228, 1.0
	v_fma_f32 v233, -v221, v229, 1.0
	v_fma_f32 v234, -v222, v230, 1.0
	v_fma_f32 v235, -v223, v231, 1.0
	v_fmac_f32_e32 v228, v232, v228
	v_fmac_f32_e32 v229, v233, v229
	v_fmac_f32_e32 v230, v234, v230
	v_fmac_f32_e32 v231, v235, v231
	v_div_fixup_f32 v228, v228, v220, 1.0
	v_div_fixup_f32 v229, v229, v221, 1.0
	v_div_fixup_f32 v230, v230, v222, 1.0
	v_div_fixup_f32 v231, v231, v223, 1.0
	v_cvt_pk_bf16_f32 v151, v228, v229
	v_cvt_pk_bf16_f32 v150, v230, v231
	v_mul_f32_e32 v220, 0xbfb8aa3b, v104
	v_mul_f32_e32 v221, 0xbfb8aa3b, v105
	v_mul_f32_e32 v222, 0xbfb8aa3b, v102
	v_mul_f32_e32 v223, 0xbfb8aa3b, v103
	v_exp_f32_e32 v220, v220
	v_exp_f32_e32 v221, v221
	v_exp_f32_e32 v222, v222
	v_exp_f32_e32 v223, v223
	v_add_f32_e32 v220, 1.0, v220
	v_add_f32_e32 v221, 1.0, v221
	v_add_f32_e32 v222, 1.0, v222
	v_add_f32_e32 v223, 1.0, v223
	v_rcp_f32_e32 v228, v220
	v_rcp_f32_e32 v229, v221
	v_rcp_f32_e32 v230, v222
	v_rcp_f32_e32 v231, v223
	v_fma_f32 v232, -v220, v228, 1.0
	v_fma_f32 v233, -v221, v229, 1.0
	v_fma_f32 v234, -v222, v230, 1.0
	v_fma_f32 v235, -v223, v231, 1.0
	v_fmac_f32_e32 v228, v232, v228
	v_fmac_f32_e32 v229, v233, v229
	v_fmac_f32_e32 v230, v234, v230
	v_fmac_f32_e32 v231, v235, v231
	v_div_fixup_f32 v228, v228, v220, 1.0
	v_div_fixup_f32 v229, v229, v221, 1.0
	v_div_fixup_f32 v230, v230, v222, 1.0
	v_div_fixup_f32 v231, v231, v223, 1.0
	v_cvt_pk_bf16_f32 v149, v228, v229
	v_cvt_pk_bf16_f32 v148, v230, v231
	v_mul_f32_e32 v220, 0xbfb8aa3b, v100
	v_mul_f32_e32 v221, 0xbfb8aa3b, v101
	v_mul_f32_e32 v222, 0xbfb8aa3b, v98
	v_mul_f32_e32 v223, 0xbfb8aa3b, v99
	v_exp_f32_e32 v220, v220
	v_exp_f32_e32 v221, v221
	v_exp_f32_e32 v222, v222
	v_exp_f32_e32 v223, v223
	v_add_f32_e32 v220, 1.0, v220
	v_add_f32_e32 v221, 1.0, v221
	v_add_f32_e32 v222, 1.0, v222
	v_add_f32_e32 v223, 1.0, v223
	v_rcp_f32_e32 v228, v220
	v_rcp_f32_e32 v229, v221
	v_rcp_f32_e32 v230, v222
	v_rcp_f32_e32 v231, v223
	v_fma_f32 v232, -v220, v228, 1.0
	v_fma_f32 v233, -v221, v229, 1.0
	v_fma_f32 v234, -v222, v230, 1.0
	v_fma_f32 v235, -v223, v231, 1.0
	v_fmac_f32_e32 v228, v232, v228
	v_fmac_f32_e32 v229, v233, v229
	v_fmac_f32_e32 v230, v234, v230
	v_fmac_f32_e32 v231, v235, v231
	v_div_fixup_f32 v228, v228, v220, 1.0
	v_div_fixup_f32 v229, v229, v221, 1.0
	v_div_fixup_f32 v230, v230, v222, 1.0
	v_div_fixup_f32 v231, v231, v223, 1.0
	v_cvt_pk_bf16_f32 v147, v228, v229
	v_cvt_pk_bf16_f32 v146, v230, v231
	v_mul_f32_e32 v220, 0xbfb8aa3b, v96
	v_mul_f32_e32 v221, 0xbfb8aa3b, v97
	v_mul_f32_e32 v222, 0xbfb8aa3b, v94
	v_mul_f32_e32 v223, 0xbfb8aa3b, v95
	v_exp_f32_e32 v220, v220
	v_exp_f32_e32 v221, v221
	v_exp_f32_e32 v222, v222
	v_exp_f32_e32 v223, v223
	v_add_f32_e32 v220, 1.0, v220
	v_add_f32_e32 v221, 1.0, v221
	v_add_f32_e32 v222, 1.0, v222
	v_add_f32_e32 v223, 1.0, v223
	v_rcp_f32_e32 v228, v220
	v_rcp_f32_e32 v229, v221
	v_rcp_f32_e32 v230, v222
	v_rcp_f32_e32 v231, v223
	v_fma_f32 v232, -v220, v228, 1.0
	v_fma_f32 v233, -v221, v229, 1.0
	v_fma_f32 v234, -v222, v230, 1.0
	v_fma_f32 v235, -v223, v231, 1.0
	v_fmac_f32_e32 v228, v232, v228
	v_fmac_f32_e32 v229, v233, v229
	v_fmac_f32_e32 v230, v234, v230
	v_fmac_f32_e32 v231, v235, v231
	v_div_fixup_f32 v228, v228, v220, 1.0
	v_div_fixup_f32 v229, v229, v221, 1.0
	v_div_fixup_f32 v230, v230, v222, 1.0
	v_div_fixup_f32 v231, v231, v223, 1.0
	v_cvt_pk_bf16_f32 v145, v228, v229
	v_cvt_pk_bf16_f32 v144, v230, v231
	v_mul_f32_e32 v220, 0xbfb8aa3b, v92
	v_mul_f32_e32 v221, 0xbfb8aa3b, v93
	v_mul_f32_e32 v222, 0xbfb8aa3b, v90
	v_mul_f32_e32 v223, 0xbfb8aa3b, v91
	v_exp_f32_e32 v220, v220
	v_exp_f32_e32 v221, v221
	v_exp_f32_e32 v222, v222
	v_exp_f32_e32 v223, v223
	v_add_f32_e32 v220, 1.0, v220
	v_add_f32_e32 v221, 1.0, v221
	v_add_f32_e32 v222, 1.0, v222
	v_add_f32_e32 v223, 1.0, v223
	v_rcp_f32_e32 v228, v220
	v_rcp_f32_e32 v229, v221
	v_rcp_f32_e32 v230, v222
	v_rcp_f32_e32 v231, v223
	v_fma_f32 v232, -v220, v228, 1.0
	v_fma_f32 v233, -v221, v229, 1.0
	v_fma_f32 v234, -v222, v230, 1.0
	v_fma_f32 v235, -v223, v231, 1.0
	v_fmac_f32_e32 v228, v232, v228
	v_fmac_f32_e32 v229, v233, v229
	v_fmac_f32_e32 v230, v234, v230
	v_fmac_f32_e32 v231, v235, v231
	v_div_fixup_f32 v228, v228, v220, 1.0
	v_div_fixup_f32 v229, v229, v221, 1.0
	v_div_fixup_f32 v230, v230, v222, 1.0
	v_div_fixup_f32 v231, v231, v223, 1.0
	v_cvt_pk_bf16_f32 v143, v228, v229
	v_cvt_pk_bf16_f32 v142, v230, v231
	v_mul_f32_e32 v220, 0xbfb8aa3b, v88
	v_mul_f32_e32 v221, 0xbfb8aa3b, v89
	v_mul_f32_e32 v222, 0xbfb8aa3b, v86
	v_mul_f32_e32 v223, 0xbfb8aa3b, v87
	v_exp_f32_e32 v220, v220
	v_exp_f32_e32 v221, v221
	v_exp_f32_e32 v222, v222
	v_exp_f32_e32 v223, v223
	v_add_f32_e32 v220, 1.0, v220
	v_add_f32_e32 v221, 1.0, v221
	v_add_f32_e32 v222, 1.0, v222
	v_add_f32_e32 v223, 1.0, v223
	v_rcp_f32_e32 v228, v220
	v_rcp_f32_e32 v229, v221
	v_rcp_f32_e32 v230, v222
	v_rcp_f32_e32 v231, v223
	v_fma_f32 v232, -v220, v228, 1.0
	v_fma_f32 v233, -v221, v229, 1.0
	v_fma_f32 v234, -v222, v230, 1.0
	v_fma_f32 v235, -v223, v231, 1.0
	v_fmac_f32_e32 v228, v232, v228
	v_fmac_f32_e32 v229, v233, v229
	v_fmac_f32_e32 v230, v234, v230
	v_fmac_f32_e32 v231, v235, v231
	v_div_fixup_f32 v228, v228, v220, 1.0
	v_div_fixup_f32 v229, v229, v221, 1.0
	v_div_fixup_f32 v230, v230, v222, 1.0
	v_div_fixup_f32 v231, v231, v223, 1.0
	v_cvt_pk_bf16_f32 v141, v228, v229
	v_cvt_pk_bf16_f32 v140, v230, v231
	v_mul_f32_e32 v220, 0xbfb8aa3b, v84
	v_mul_f32_e32 v221, 0xbfb8aa3b, v85
	v_mul_f32_e32 v222, 0xbfb8aa3b, v82
	v_mul_f32_e32 v223, 0xbfb8aa3b, v83
	v_exp_f32_e32 v220, v220
	v_exp_f32_e32 v221, v221
	v_exp_f32_e32 v222, v222
	v_exp_f32_e32 v223, v223
	v_add_f32_e32 v220, 1.0, v220
	v_add_f32_e32 v221, 1.0, v221
	v_add_f32_e32 v222, 1.0, v222
	v_add_f32_e32 v223, 1.0, v223
	v_rcp_f32_e32 v228, v220
	v_rcp_f32_e32 v229, v221
	v_rcp_f32_e32 v230, v222
	v_rcp_f32_e32 v231, v223
	v_fma_f32 v232, -v220, v228, 1.0
	v_fma_f32 v233, -v221, v229, 1.0
	v_fma_f32 v234, -v222, v230, 1.0
	v_fma_f32 v235, -v223, v231, 1.0
	v_fmac_f32_e32 v228, v232, v228
	v_fmac_f32_e32 v229, v233, v229
	v_fmac_f32_e32 v230, v234, v230
	v_fmac_f32_e32 v231, v235, v231
	v_div_fixup_f32 v228, v228, v220, 1.0
	v_div_fixup_f32 v229, v229, v221, 1.0
	v_div_fixup_f32 v230, v230, v222, 1.0
	v_div_fixup_f32 v231, v231, v223, 1.0
	v_cvt_pk_bf16_f32 v139, v228, v229
	v_cvt_pk_bf16_f32 v138, v230, v231
	v_mul_f32_e32 v220, 0xbfb8aa3b, v80
	v_mul_f32_e32 v221, 0xbfb8aa3b, v81
	v_mul_f32_e32 v222, 0xbfb8aa3b, v78
	v_mul_f32_e32 v223, 0xbfb8aa3b, v79
	v_exp_f32_e32 v220, v220
	v_exp_f32_e32 v221, v221
	v_exp_f32_e32 v222, v222
	v_exp_f32_e32 v223, v223
	v_add_f32_e32 v220, 1.0, v220
	v_add_f32_e32 v221, 1.0, v221
	v_add_f32_e32 v222, 1.0, v222
	v_add_f32_e32 v223, 1.0, v223
	v_rcp_f32_e32 v228, v220
	v_rcp_f32_e32 v229, v221
	v_rcp_f32_e32 v230, v222
	v_rcp_f32_e32 v231, v223
	v_fma_f32 v232, -v220, v228, 1.0
	v_fma_f32 v233, -v221, v229, 1.0
	v_fma_f32 v234, -v222, v230, 1.0
	v_fma_f32 v235, -v223, v231, 1.0
	v_fmac_f32_e32 v228, v232, v228
	v_fmac_f32_e32 v229, v233, v229
	v_fmac_f32_e32 v230, v234, v230
	v_fmac_f32_e32 v231, v235, v231
	v_div_fixup_f32 v228, v228, v220, 1.0
	v_div_fixup_f32 v229, v229, v221, 1.0
	v_div_fixup_f32 v230, v230, v222, 1.0
	v_div_fixup_f32 v231, v231, v223, 1.0
	v_cvt_pk_bf16_f32 v137, v228, v229
	v_cvt_pk_bf16_f32 v136, v230, v231
	v_mul_f32_e32 v220, 0xbfb8aa3b, v76
	v_mul_f32_e32 v221, 0xbfb8aa3b, v77
	v_mul_f32_e32 v222, 0xbfb8aa3b, v74
	v_mul_f32_e32 v223, 0xbfb8aa3b, v75
	v_exp_f32_e32 v220, v220
	v_exp_f32_e32 v221, v221
	v_exp_f32_e32 v222, v222
	v_exp_f32_e32 v223, v223
	v_add_f32_e32 v220, 1.0, v220
	v_add_f32_e32 v221, 1.0, v221
	v_add_f32_e32 v222, 1.0, v222
	v_add_f32_e32 v223, 1.0, v223
	v_rcp_f32_e32 v228, v220
	v_rcp_f32_e32 v229, v221
	v_rcp_f32_e32 v230, v222
	v_rcp_f32_e32 v231, v223
	v_fma_f32 v232, -v220, v228, 1.0
	v_fma_f32 v233, -v221, v229, 1.0
	v_fma_f32 v234, -v222, v230, 1.0
	v_fma_f32 v235, -v223, v231, 1.0
	v_fmac_f32_e32 v228, v232, v228
	v_fmac_f32_e32 v229, v233, v229
	v_fmac_f32_e32 v230, v234, v230
	v_fmac_f32_e32 v231, v235, v231
	v_div_fixup_f32 v228, v228, v220, 1.0
	v_div_fixup_f32 v229, v229, v221, 1.0
	v_div_fixup_f32 v230, v230, v222, 1.0
	v_div_fixup_f32 v231, v231, v223, 1.0
	v_cvt_pk_bf16_f32 v135, v228, v229
	v_cvt_pk_bf16_f32 v134, v230, v231
	v_mul_f32_e32 v220, 0xbfb8aa3b, v72
	v_mul_f32_e32 v221, 0xbfb8aa3b, v73
	v_mul_f32_e32 v222, 0xbfb8aa3b, v70
	v_mul_f32_e32 v223, 0xbfb8aa3b, v71
	v_exp_f32_e32 v220, v220
	v_exp_f32_e32 v221, v221
	v_exp_f32_e32 v222, v222
	v_exp_f32_e32 v223, v223
	v_add_f32_e32 v220, 1.0, v220
	v_add_f32_e32 v221, 1.0, v221
	v_add_f32_e32 v222, 1.0, v222
	v_add_f32_e32 v223, 1.0, v223
	v_rcp_f32_e32 v228, v220
	v_rcp_f32_e32 v229, v221
	v_rcp_f32_e32 v230, v222
	v_rcp_f32_e32 v231, v223
	v_fma_f32 v232, -v220, v228, 1.0
	v_fma_f32 v233, -v221, v229, 1.0
	v_fma_f32 v234, -v222, v230, 1.0
	v_fma_f32 v235, -v223, v231, 1.0
	v_fmac_f32_e32 v228, v232, v228
	v_fmac_f32_e32 v229, v233, v229
	v_fmac_f32_e32 v230, v234, v230
	v_fmac_f32_e32 v231, v235, v231
	v_div_fixup_f32 v228, v228, v220, 1.0
	v_div_fixup_f32 v229, v229, v221, 1.0
	v_div_fixup_f32 v230, v230, v222, 1.0
	v_div_fixup_f32 v231, v231, v223, 1.0
	v_cvt_pk_bf16_f32 v133, v228, v229
	v_cvt_pk_bf16_f32 v132, v230, v231
	v_mul_f32_e32 v220, 0xbfb8aa3b, v68
	v_mul_f32_e32 v221, 0xbfb8aa3b, v69
	v_mul_f32_e32 v222, 0xbfb8aa3b, v66
	v_mul_f32_e32 v223, 0xbfb8aa3b, v67
	v_exp_f32_e32 v220, v220
	v_exp_f32_e32 v221, v221
	v_exp_f32_e32 v222, v222
	v_exp_f32_e32 v223, v223
	v_add_f32_e32 v220, 1.0, v220
	v_add_f32_e32 v221, 1.0, v221
	v_add_f32_e32 v222, 1.0, v222
	v_add_f32_e32 v223, 1.0, v223
	v_rcp_f32_e32 v228, v220
	v_rcp_f32_e32 v229, v221
	v_rcp_f32_e32 v230, v222
	v_rcp_f32_e32 v231, v223
	v_fma_f32 v232, -v220, v228, 1.0
	v_fma_f32 v233, -v221, v229, 1.0
	v_fma_f32 v234, -v222, v230, 1.0
	v_fma_f32 v235, -v223, v231, 1.0
	v_fmac_f32_e32 v228, v232, v228
	v_fmac_f32_e32 v229, v233, v229
	v_fmac_f32_e32 v230, v234, v230
	v_fmac_f32_e32 v231, v235, v231
	v_div_fixup_f32 v228, v228, v220, 1.0
	v_div_fixup_f32 v229, v229, v221, 1.0
	v_div_fixup_f32 v230, v230, v222, 1.0
	v_div_fixup_f32 v231, v231, v223, 1.0
	v_cvt_pk_bf16_f32 v131, v228, v229
	v_cvt_pk_bf16_f32 v130, v230, v231
	v_mul_f32_e32 v220, 0xbfb8aa3b, v64
	v_mul_f32_e32 v221, 0xbfb8aa3b, v65
	v_mul_f32_e32 v222, 0xbfb8aa3b, v62
	v_mul_f32_e32 v223, 0xbfb8aa3b, v63
	v_exp_f32_e32 v220, v220
	v_exp_f32_e32 v221, v221
	v_exp_f32_e32 v222, v222
	v_exp_f32_e32 v223, v223
	v_add_f32_e32 v220, 1.0, v220
	v_add_f32_e32 v221, 1.0, v221
	v_add_f32_e32 v222, 1.0, v222
	v_add_f32_e32 v223, 1.0, v223
	v_rcp_f32_e32 v228, v220
	v_rcp_f32_e32 v229, v221
	v_rcp_f32_e32 v230, v222
	v_rcp_f32_e32 v231, v223
	v_fma_f32 v232, -v220, v228, 1.0
	v_fma_f32 v233, -v221, v229, 1.0
	v_fma_f32 v234, -v222, v230, 1.0
	v_fma_f32 v235, -v223, v231, 1.0
	v_fmac_f32_e32 v228, v232, v228
	v_fmac_f32_e32 v229, v233, v229
	v_fmac_f32_e32 v230, v234, v230
	v_fmac_f32_e32 v231, v235, v231
	v_div_fixup_f32 v228, v228, v220, 1.0
	v_div_fixup_f32 v229, v229, v221, 1.0
	v_div_fixup_f32 v230, v230, v222, 1.0
	v_div_fixup_f32 v231, v231, v223, 1.0
	v_cvt_pk_bf16_f32 v129, v228, v229
	v_cvt_pk_bf16_f32 v128, v230, v231
	v_mul_f32_e32 v220, 0xbfb8aa3b, v60
	v_mul_f32_e32 v221, 0xbfb8aa3b, v61
	v_mul_f32_e32 v222, 0xbfb8aa3b, v58
	v_mul_f32_e32 v223, 0xbfb8aa3b, v59
	v_exp_f32_e32 v220, v220
	v_exp_f32_e32 v221, v221
	v_exp_f32_e32 v222, v222
	v_exp_f32_e32 v223, v223
	v_add_f32_e32 v220, 1.0, v220
	v_add_f32_e32 v221, 1.0, v221
	v_add_f32_e32 v222, 1.0, v222
	v_add_f32_e32 v223, 1.0, v223
	v_rcp_f32_e32 v228, v220
	v_rcp_f32_e32 v229, v221
	v_rcp_f32_e32 v230, v222
	v_rcp_f32_e32 v231, v223
	v_fma_f32 v232, -v220, v228, 1.0
	v_fma_f32 v233, -v221, v229, 1.0
	v_fma_f32 v234, -v222, v230, 1.0
	v_fma_f32 v235, -v223, v231, 1.0
	v_fmac_f32_e32 v228, v232, v228
	v_fmac_f32_e32 v229, v233, v229
	v_fmac_f32_e32 v230, v234, v230
	v_fmac_f32_e32 v231, v235, v231
	v_div_fixup_f32 v228, v228, v220, 1.0
	v_div_fixup_f32 v229, v229, v221, 1.0
	v_div_fixup_f32 v230, v230, v222, 1.0
	v_div_fixup_f32 v231, v231, v223, 1.0
	v_cvt_pk_bf16_f32 v127, v228, v229
	v_cvt_pk_bf16_f32 v126, v230, v231
	v_mul_f32_e32 v220, 0xbfb8aa3b, v56
	v_mul_f32_e32 v221, 0xbfb8aa3b, v57
	v_mul_f32_e32 v222, 0xbfb8aa3b, v54
	v_mul_f32_e32 v223, 0xbfb8aa3b, v55
	v_exp_f32_e32 v220, v220
	v_exp_f32_e32 v221, v221
	v_exp_f32_e32 v222, v222
	v_exp_f32_e32 v223, v223
	v_add_f32_e32 v220, 1.0, v220
	v_add_f32_e32 v221, 1.0, v221
	v_add_f32_e32 v222, 1.0, v222
	v_add_f32_e32 v223, 1.0, v223
	v_rcp_f32_e32 v228, v220
	v_rcp_f32_e32 v229, v221
	v_rcp_f32_e32 v230, v222
	v_rcp_f32_e32 v231, v223
	v_fma_f32 v232, -v220, v228, 1.0
	v_fma_f32 v233, -v221, v229, 1.0
	v_fma_f32 v234, -v222, v230, 1.0
	v_fma_f32 v235, -v223, v231, 1.0
	v_fmac_f32_e32 v228, v232, v228
	v_fmac_f32_e32 v229, v233, v229
	v_fmac_f32_e32 v230, v234, v230
	v_fmac_f32_e32 v231, v235, v231
	v_div_fixup_f32 v228, v228, v220, 1.0
	v_div_fixup_f32 v229, v229, v221, 1.0
	v_div_fixup_f32 v230, v230, v222, 1.0
	v_div_fixup_f32 v231, v231, v223, 1.0
	v_cvt_pk_bf16_f32 v125, v228, v229
	v_cvt_pk_bf16_f32 v124, v230, v231
	v_mul_f32_e32 v220, 0xbfb8aa3b, v52
	v_mul_f32_e32 v221, 0xbfb8aa3b, v53
	v_mul_f32_e32 v222, 0xbfb8aa3b, v50
	v_mul_f32_e32 v223, 0xbfb8aa3b, v51
	v_exp_f32_e32 v220, v220
	v_exp_f32_e32 v221, v221
	v_exp_f32_e32 v222, v222
	v_exp_f32_e32 v223, v223
	v_add_f32_e32 v220, 1.0, v220
	v_add_f32_e32 v221, 1.0, v221
	v_add_f32_e32 v222, 1.0, v222
	v_add_f32_e32 v223, 1.0, v223
	v_rcp_f32_e32 v228, v220
	v_rcp_f32_e32 v229, v221
	v_rcp_f32_e32 v230, v222
	v_rcp_f32_e32 v231, v223
	v_fma_f32 v232, -v220, v228, 1.0
	v_fma_f32 v233, -v221, v229, 1.0
	v_fma_f32 v234, -v222, v230, 1.0
	v_fma_f32 v235, -v223, v231, 1.0
	v_fmac_f32_e32 v228, v232, v228
	v_fmac_f32_e32 v229, v233, v229
	v_fmac_f32_e32 v230, v234, v230
	v_fmac_f32_e32 v231, v235, v231
	v_div_fixup_f32 v228, v228, v220, 1.0
	v_div_fixup_f32 v229, v229, v221, 1.0
	v_div_fixup_f32 v230, v230, v222, 1.0
	v_div_fixup_f32 v231, v231, v223, 1.0
	v_cvt_pk_bf16_f32 v123, v228, v229
	v_cvt_pk_bf16_f32 v122, v230, v231
	v_mul_f32_e32 v220, 0xbfb8aa3b, v48
	v_mul_f32_e32 v221, 0xbfb8aa3b, v49
	v_mul_f32_e32 v222, 0xbfb8aa3b, v46
	v_mul_f32_e32 v223, 0xbfb8aa3b, v47
	v_exp_f32_e32 v220, v220
	v_exp_f32_e32 v221, v221
	v_exp_f32_e32 v222, v222
	v_exp_f32_e32 v223, v223
	v_add_f32_e32 v220, 1.0, v220
	v_add_f32_e32 v221, 1.0, v221
	v_add_f32_e32 v222, 1.0, v222
	v_add_f32_e32 v223, 1.0, v223
	v_rcp_f32_e32 v228, v220
	v_rcp_f32_e32 v229, v221
	v_rcp_f32_e32 v230, v222
	v_rcp_f32_e32 v231, v223
	v_fma_f32 v232, -v220, v228, 1.0
	v_fma_f32 v233, -v221, v229, 1.0
	v_fma_f32 v234, -v222, v230, 1.0
	v_fma_f32 v235, -v223, v231, 1.0
	v_fmac_f32_e32 v228, v232, v228
	v_fmac_f32_e32 v229, v233, v229
	v_fmac_f32_e32 v230, v234, v230
	v_fmac_f32_e32 v231, v235, v231
	v_div_fixup_f32 v228, v228, v220, 1.0
	v_div_fixup_f32 v229, v229, v221, 1.0
	v_div_fixup_f32 v230, v230, v222, 1.0
	v_div_fixup_f32 v231, v231, v223, 1.0
	v_cvt_pk_bf16_f32 v121, v228, v229
	v_cvt_pk_bf16_f32 v120, v230, v231
	v_mul_f32_e32 v220, 0xbfb8aa3b, v44
	v_mul_f32_e32 v221, 0xbfb8aa3b, v45
	v_mul_f32_e32 v222, 0xbfb8aa3b, v42
	v_mul_f32_e32 v223, 0xbfb8aa3b, v43
	v_exp_f32_e32 v220, v220
	v_exp_f32_e32 v221, v221
	v_exp_f32_e32 v222, v222
	v_exp_f32_e32 v223, v223
	v_add_f32_e32 v220, 1.0, v220
	v_add_f32_e32 v221, 1.0, v221
	v_add_f32_e32 v222, 1.0, v222
	v_add_f32_e32 v223, 1.0, v223
	v_rcp_f32_e32 v228, v220
	v_rcp_f32_e32 v229, v221
	v_rcp_f32_e32 v230, v222
	v_rcp_f32_e32 v231, v223
	v_fma_f32 v232, -v220, v228, 1.0
	v_fma_f32 v233, -v221, v229, 1.0
	v_fma_f32 v234, -v222, v230, 1.0
	v_fma_f32 v235, -v223, v231, 1.0
	v_fmac_f32_e32 v228, v232, v228
	v_fmac_f32_e32 v229, v233, v229
	v_fmac_f32_e32 v230, v234, v230
	v_fmac_f32_e32 v231, v235, v231
	v_div_fixup_f32 v228, v228, v220, 1.0
	v_div_fixup_f32 v229, v229, v221, 1.0
	v_div_fixup_f32 v230, v230, v222, 1.0
	v_div_fixup_f32 v231, v231, v223, 1.0
	v_cvt_pk_bf16_f32 v119, v228, v229
	v_cvt_pk_bf16_f32 v118, v230, v231
	v_mul_f32_e32 v220, 0xbfb8aa3b, v40
	v_mul_f32_e32 v221, 0xbfb8aa3b, v41
	v_mul_f32_e32 v222, 0xbfb8aa3b, v38
	v_mul_f32_e32 v223, 0xbfb8aa3b, v39
	v_exp_f32_e32 v220, v220
	v_exp_f32_e32 v221, v221
	v_exp_f32_e32 v222, v222
	v_exp_f32_e32 v223, v223
	v_add_f32_e32 v220, 1.0, v220
	v_add_f32_e32 v221, 1.0, v221
	v_add_f32_e32 v222, 1.0, v222
	v_add_f32_e32 v223, 1.0, v223
	v_rcp_f32_e32 v228, v220
	v_rcp_f32_e32 v229, v221
	v_rcp_f32_e32 v230, v222
	v_rcp_f32_e32 v231, v223
	v_fma_f32 v232, -v220, v228, 1.0
	v_fma_f32 v233, -v221, v229, 1.0
	v_fma_f32 v234, -v222, v230, 1.0
	v_fma_f32 v235, -v223, v231, 1.0
	v_fmac_f32_e32 v228, v232, v228
	v_fmac_f32_e32 v229, v233, v229
	v_fmac_f32_e32 v230, v234, v230
	v_fmac_f32_e32 v231, v235, v231
	v_div_fixup_f32 v228, v228, v220, 1.0
	v_div_fixup_f32 v229, v229, v221, 1.0
	v_div_fixup_f32 v230, v230, v222, 1.0
	v_div_fixup_f32 v231, v231, v223, 1.0
	v_cvt_pk_bf16_f32 v117, v228, v229
	v_cvt_pk_bf16_f32 v116, v230, v231
	v_mul_f32_e32 v220, 0xbfb8aa3b, v36
	v_mul_f32_e32 v221, 0xbfb8aa3b, v37
	v_mul_f32_e32 v222, 0xbfb8aa3b, v34
	v_mul_f32_e32 v223, 0xbfb8aa3b, v35
	v_exp_f32_e32 v220, v220
	v_exp_f32_e32 v221, v221
	v_exp_f32_e32 v222, v222
	v_exp_f32_e32 v223, v223
	v_add_f32_e32 v220, 1.0, v220
	v_add_f32_e32 v221, 1.0, v221
	v_add_f32_e32 v222, 1.0, v222
	v_add_f32_e32 v223, 1.0, v223
	v_rcp_f32_e32 v228, v220
	v_rcp_f32_e32 v229, v221
	v_rcp_f32_e32 v230, v222
	v_rcp_f32_e32 v231, v223
	v_fma_f32 v232, -v220, v228, 1.0
	v_fma_f32 v233, -v221, v229, 1.0
	v_fma_f32 v234, -v222, v230, 1.0
	v_fma_f32 v235, -v223, v231, 1.0
	v_fmac_f32_e32 v228, v232, v228
	v_fmac_f32_e32 v229, v233, v229
	v_fmac_f32_e32 v230, v234, v230
	v_fmac_f32_e32 v231, v235, v231
	v_div_fixup_f32 v228, v228, v220, 1.0
	v_div_fixup_f32 v229, v229, v221, 1.0
	v_div_fixup_f32 v230, v230, v222, 1.0
	v_div_fixup_f32 v231, v231, v223, 1.0
	v_cvt_pk_bf16_f32 v115, v228, v229
	v_cvt_pk_bf16_f32 v114, v230, v231
	v_mul_f32_e32 v220, 0xbfb8aa3b, v32
	v_mul_f32_e32 v221, 0xbfb8aa3b, v33
	v_mul_f32_e32 v222, 0xbfb8aa3b, v30
	v_mul_f32_e32 v223, 0xbfb8aa3b, v31
	v_exp_f32_e32 v220, v220
	v_exp_f32_e32 v221, v221
	v_exp_f32_e32 v222, v222
	v_exp_f32_e32 v223, v223
	v_add_f32_e32 v220, 1.0, v220
	v_add_f32_e32 v221, 1.0, v221
	v_add_f32_e32 v222, 1.0, v222
	v_add_f32_e32 v223, 1.0, v223
	v_rcp_f32_e32 v228, v220
	v_rcp_f32_e32 v229, v221
	v_rcp_f32_e32 v230, v222
	v_rcp_f32_e32 v231, v223
	v_fma_f32 v232, -v220, v228, 1.0
	v_fma_f32 v233, -v221, v229, 1.0
	v_fma_f32 v234, -v222, v230, 1.0
	v_fma_f32 v235, -v223, v231, 1.0
	v_fmac_f32_e32 v228, v232, v228
	v_fmac_f32_e32 v229, v233, v229
	v_fmac_f32_e32 v230, v234, v230
	v_fmac_f32_e32 v231, v235, v231
	v_div_fixup_f32 v228, v228, v220, 1.0
	v_div_fixup_f32 v229, v229, v221, 1.0
	v_div_fixup_f32 v230, v230, v222, 1.0
	v_div_fixup_f32 v231, v231, v223, 1.0
	v_cvt_pk_bf16_f32 v113, v228, v229
	v_cvt_pk_bf16_f32 v112, v230, v231
	v_mul_f32_e32 v220, 0xbfb8aa3b, v28
	v_mul_f32_e32 v221, 0xbfb8aa3b, v29
	v_mul_f32_e32 v222, 0xbfb8aa3b, v26
	v_mul_f32_e32 v223, 0xbfb8aa3b, v27
	v_exp_f32_e32 v220, v220
	v_exp_f32_e32 v221, v221
	v_exp_f32_e32 v222, v222
	v_exp_f32_e32 v223, v223
	v_add_f32_e32 v220, 1.0, v220
	v_add_f32_e32 v221, 1.0, v221
	v_add_f32_e32 v222, 1.0, v222
	v_add_f32_e32 v223, 1.0, v223
	v_rcp_f32_e32 v228, v220
	v_rcp_f32_e32 v229, v221
	v_rcp_f32_e32 v230, v222
	v_rcp_f32_e32 v231, v223
	v_fma_f32 v232, -v220, v228, 1.0
	v_fma_f32 v233, -v221, v229, 1.0
	v_fma_f32 v234, -v222, v230, 1.0
	v_fma_f32 v235, -v223, v231, 1.0
	v_fmac_f32_e32 v228, v232, v228
	v_fmac_f32_e32 v229, v233, v229
	v_fmac_f32_e32 v230, v234, v230
	v_fmac_f32_e32 v231, v235, v231
	v_div_fixup_f32 v228, v228, v220, 1.0
	v_div_fixup_f32 v229, v229, v221, 1.0
	v_div_fixup_f32 v230, v230, v222, 1.0
	v_div_fixup_f32 v231, v231, v223, 1.0
	v_cvt_pk_bf16_f32 v111, v228, v229
	v_cvt_pk_bf16_f32 v110, v230, v231
	v_mul_f32_e32 v220, 0xbfb8aa3b, v24
	v_mul_f32_e32 v221, 0xbfb8aa3b, v25
	v_mul_f32_e32 v222, 0xbfb8aa3b, v22
	v_mul_f32_e32 v223, 0xbfb8aa3b, v23
	v_exp_f32_e32 v220, v220
	v_exp_f32_e32 v221, v221
	v_exp_f32_e32 v222, v222
	v_exp_f32_e32 v223, v223
	v_add_f32_e32 v220, 1.0, v220
	v_add_f32_e32 v221, 1.0, v221
	v_add_f32_e32 v222, 1.0, v222
	v_add_f32_e32 v223, 1.0, v223
	v_rcp_f32_e32 v228, v220
	v_rcp_f32_e32 v229, v221
	v_rcp_f32_e32 v230, v222
	v_rcp_f32_e32 v231, v223
	v_fma_f32 v232, -v220, v228, 1.0
	v_fma_f32 v233, -v221, v229, 1.0
	v_fma_f32 v234, -v222, v230, 1.0
	v_fma_f32 v235, -v223, v231, 1.0
	v_fmac_f32_e32 v228, v232, v228
	v_fmac_f32_e32 v229, v233, v229
	v_fmac_f32_e32 v230, v234, v230
	v_fmac_f32_e32 v231, v235, v231
	v_div_fixup_f32 v228, v228, v220, 1.0
	v_div_fixup_f32 v229, v229, v221, 1.0
	v_div_fixup_f32 v230, v230, v222, 1.0
	v_div_fixup_f32 v231, v231, v223, 1.0
	v_cvt_pk_bf16_f32 v109, v228, v229
	v_cvt_pk_bf16_f32 v108, v230, v231
	v_mul_f32_e32 v220, 0xbfb8aa3b, v20
	v_mul_f32_e32 v221, 0xbfb8aa3b, v21
	v_mul_f32_e32 v222, 0xbfb8aa3b, v18
	v_mul_f32_e32 v223, 0xbfb8aa3b, v19
	v_exp_f32_e32 v220, v220
	v_exp_f32_e32 v221, v221
	v_exp_f32_e32 v222, v222
	v_exp_f32_e32 v223, v223
	v_add_f32_e32 v220, 1.0, v220
	v_add_f32_e32 v221, 1.0, v221
	v_add_f32_e32 v222, 1.0, v222
	v_add_f32_e32 v223, 1.0, v223
	v_rcp_f32_e32 v228, v220
	v_rcp_f32_e32 v229, v221
	v_rcp_f32_e32 v230, v222
	v_rcp_f32_e32 v231, v223
	v_fma_f32 v232, -v220, v228, 1.0
	v_fma_f32 v233, -v221, v229, 1.0
	v_fma_f32 v234, -v222, v230, 1.0
	v_fma_f32 v235, -v223, v231, 1.0
	v_fmac_f32_e32 v228, v232, v228
	v_fmac_f32_e32 v229, v233, v229
	v_fmac_f32_e32 v230, v234, v230
	v_fmac_f32_e32 v231, v235, v231
	v_div_fixup_f32 v228, v228, v220, 1.0
	v_div_fixup_f32 v229, v229, v221, 1.0
	v_div_fixup_f32 v230, v230, v222, 1.0
	v_div_fixup_f32 v231, v231, v223, 1.0
	v_cvt_pk_bf16_f32 v107, v228, v229
	v_cvt_pk_bf16_f32 v106, v230, v231
	v_mul_f32_e32 v220, 0xbfb8aa3b, v16
	v_mul_f32_e32 v221, 0xbfb8aa3b, v17
	v_mul_f32_e32 v222, 0xbfb8aa3b, v14
	v_mul_f32_e32 v223, 0xbfb8aa3b, v15
	v_exp_f32_e32 v220, v220
	v_exp_f32_e32 v221, v221
	v_exp_f32_e32 v222, v222
	v_exp_f32_e32 v223, v223
	v_add_f32_e32 v220, 1.0, v220
	v_add_f32_e32 v221, 1.0, v221
	v_add_f32_e32 v222, 1.0, v222
	v_add_f32_e32 v223, 1.0, v223
	v_rcp_f32_e32 v228, v220
	v_rcp_f32_e32 v229, v221
	v_rcp_f32_e32 v230, v222
	v_rcp_f32_e32 v231, v223
	v_fma_f32 v232, -v220, v228, 1.0
	v_fma_f32 v233, -v221, v229, 1.0
	v_fma_f32 v234, -v222, v230, 1.0
	v_fma_f32 v235, -v223, v231, 1.0
	v_fmac_f32_e32 v228, v232, v228
	v_fmac_f32_e32 v229, v233, v229
	v_fmac_f32_e32 v230, v234, v230
	v_fmac_f32_e32 v231, v235, v231
	v_div_fixup_f32 v228, v228, v220, 1.0
	v_div_fixup_f32 v229, v229, v221, 1.0
	v_div_fixup_f32 v230, v230, v222, 1.0
	v_div_fixup_f32 v231, v231, v223, 1.0
	v_cvt_pk_bf16_f32 v105, v228, v229
	v_cvt_pk_bf16_f32 v104, v230, v231
	v_mul_f32_e32 v220, 0xbfb8aa3b, v12
	v_mul_f32_e32 v221, 0xbfb8aa3b, v13
	v_mul_f32_e32 v222, 0xbfb8aa3b, v10
	v_mul_f32_e32 v223, 0xbfb8aa3b, v11
	v_exp_f32_e32 v220, v220
	v_exp_f32_e32 v221, v221
	v_exp_f32_e32 v222, v222
	v_exp_f32_e32 v223, v223
	v_add_f32_e32 v220, 1.0, v220
	v_add_f32_e32 v221, 1.0, v221
	v_add_f32_e32 v222, 1.0, v222
	v_add_f32_e32 v223, 1.0, v223
	v_rcp_f32_e32 v228, v220
	v_rcp_f32_e32 v229, v221
	v_rcp_f32_e32 v230, v222
	v_rcp_f32_e32 v231, v223
	v_fma_f32 v232, -v220, v228, 1.0
	v_fma_f32 v233, -v221, v229, 1.0
	v_fma_f32 v234, -v222, v230, 1.0
	v_fma_f32 v235, -v223, v231, 1.0
	v_fmac_f32_e32 v228, v232, v228
	v_fmac_f32_e32 v229, v233, v229
	v_fmac_f32_e32 v230, v234, v230
	v_fmac_f32_e32 v231, v235, v231
	v_div_fixup_f32 v228, v228, v220, 1.0
	v_div_fixup_f32 v229, v229, v221, 1.0
	v_div_fixup_f32 v230, v230, v222, 1.0
	v_div_fixup_f32 v231, v231, v223, 1.0
	v_cvt_pk_bf16_f32 v103, v228, v229
	v_cvt_pk_bf16_f32 v102, v230, v231
	v_mul_f32_e32 v220, 0xbfb8aa3b, v8
	v_mul_f32_e32 v221, 0xbfb8aa3b, v9
	v_mul_f32_e32 v222, 0xbfb8aa3b, v6
	v_mul_f32_e32 v223, 0xbfb8aa3b, v7
	v_exp_f32_e32 v220, v220
	v_exp_f32_e32 v221, v221
	v_exp_f32_e32 v222, v222
	v_exp_f32_e32 v223, v223
	v_add_f32_e32 v220, 1.0, v220
	v_add_f32_e32 v221, 1.0, v221
	v_add_f32_e32 v222, 1.0, v222
	v_add_f32_e32 v223, 1.0, v223
	v_rcp_f32_e32 v228, v220
	v_rcp_f32_e32 v229, v221
	v_rcp_f32_e32 v230, v222
	v_rcp_f32_e32 v231, v223
	v_fma_f32 v232, -v220, v228, 1.0
	v_fma_f32 v233, -v221, v229, 1.0
	v_fma_f32 v234, -v222, v230, 1.0
	v_fma_f32 v235, -v223, v231, 1.0
	v_fmac_f32_e32 v228, v232, v228
	v_fmac_f32_e32 v229, v233, v229
	v_fmac_f32_e32 v230, v234, v230
	v_fmac_f32_e32 v231, v235, v231
	v_div_fixup_f32 v228, v228, v220, 1.0
	v_div_fixup_f32 v229, v229, v221, 1.0
	v_div_fixup_f32 v230, v230, v222, 1.0
	v_div_fixup_f32 v231, v231, v223, 1.0
	v_cvt_pk_bf16_f32 v101, v228, v229
	v_cvt_pk_bf16_f32 v100, v230, v231
	v_mul_f32_e32 v220, 0xbfb8aa3b, v4
	v_mul_f32_e32 v221, 0xbfb8aa3b, v5
	v_mul_f32_e32 v222, 0xbfb8aa3b, v2
	v_mul_f32_e32 v223, 0xbfb8aa3b, v3
	v_exp_f32_e32 v220, v220
	v_exp_f32_e32 v221, v221
	v_exp_f32_e32 v222, v222
	v_exp_f32_e32 v223, v223
	v_add_f32_e32 v220, 1.0, v220
	v_add_f32_e32 v221, 1.0, v221
	v_add_f32_e32 v222, 1.0, v222
	v_add_f32_e32 v223, 1.0, v223
	v_rcp_f32_e32 v228, v220
	v_rcp_f32_e32 v229, v221
	v_rcp_f32_e32 v230, v222
	v_rcp_f32_e32 v231, v223
	v_fma_f32 v232, -v220, v228, 1.0
	v_fma_f32 v233, -v221, v229, 1.0
	v_fma_f32 v234, -v222, v230, 1.0
	v_fma_f32 v235, -v223, v231, 1.0
	v_fmac_f32_e32 v228, v232, v228
	v_fmac_f32_e32 v229, v233, v229
	v_fmac_f32_e32 v230, v234, v230
	v_fmac_f32_e32 v231, v235, v231
	v_div_fixup_f32 v228, v228, v220, 1.0
	v_div_fixup_f32 v229, v229, v221, 1.0
	v_div_fixup_f32 v230, v230, v222, 1.0
	v_div_fixup_f32 v231, v231, v223, 1.0
	v_cvt_pk_bf16_f32 v99, v228, v229
	v_cvt_pk_bf16_f32 v98, v230, v231
	v_mov_b32_e32 v2, 0
	v_mov_b32_e32 v3, 0
	v_mov_b32_e32 v4, 0
	v_mov_b32_e32 v5, 0
	v_mov_b32_e32 v6, 0
	v_mov_b32_e32 v7, 0
	v_mov_b32_e32 v8, 0
	v_mov_b32_e32 v9, 0
	v_mov_b32_e32 v10, 0
	v_mov_b32_e32 v11, 0
	v_mov_b32_e32 v12, 0
	v_mov_b32_e32 v13, 0
	v_mov_b32_e32 v14, 0
	v_mov_b32_e32 v15, 0
	v_mov_b32_e32 v16, 0
	v_mov_b32_e32 v17, 0
	v_mov_b32_e32 v18, 0
	v_mov_b32_e32 v19, 0
	v_mov_b32_e32 v20, 0
	v_mov_b32_e32 v21, 0
	v_mov_b32_e32 v22, 0
	v_mov_b32_e32 v23, 0
	v_mov_b32_e32 v24, 0
	v_mov_b32_e32 v25, 0
	v_mov_b32_e32 v26, 0
	v_mov_b32_e32 v27, 0
	v_mov_b32_e32 v28, 0
	v_mov_b32_e32 v29, 0
	v_mov_b32_e32 v30, 0
	v_mov_b32_e32 v31, 0
	v_mov_b32_e32 v32, 0
	v_mov_b32_e32 v33, 0
	v_mov_b32_e32 v34, 0
	v_mov_b32_e32 v35, 0
	v_mov_b32_e32 v36, 0
	v_mov_b32_e32 v37, 0
	v_mov_b32_e32 v38, 0
	v_mov_b32_e32 v39, 0
	v_mov_b32_e32 v40, 0
	v_mov_b32_e32 v41, 0
	v_mov_b32_e32 v42, 0
	v_mov_b32_e32 v43, 0
	v_mov_b32_e32 v44, 0
	v_mov_b32_e32 v45, 0
	v_mov_b32_e32 v46, 0
	v_mov_b32_e32 v47, 0
	v_mov_b32_e32 v48, 0
	v_mov_b32_e32 v49, 0
	v_mov_b32_e32 v50, 0
	v_mov_b32_e32 v51, 0
	v_mov_b32_e32 v52, 0
	v_mov_b32_e32 v53, 0
	v_mov_b32_e32 v54, 0
	v_mov_b32_e32 v55, 0
	v_mov_b32_e32 v56, 0
	v_mov_b32_e32 v57, 0
	v_mov_b32_e32 v58, 0
	v_mov_b32_e32 v59, 0
	v_mov_b32_e32 v60, 0
	v_mov_b32_e32 v61, 0
	v_mov_b32_e32 v62, 0
	v_mov_b32_e32 v63, 0
	v_mov_b32_e32 v64, 0
	v_mov_b32_e32 v65, 0
	s_waitcnt vmcnt(8)
	s_barrier
	v_add_u32_e32 v66, v226, v224
	v_add_u32_e32 v70, v226, v225
	ds_read_b128 v[78:81], v66
	ds_read_b128 v[66:69], v66 offset:4096
	ds_read_b128 v[74:77], v70 offset:32768
	ds_read_b128 v[70:73], v70 offset:36864
	s_waitcnt lgkmcnt(0)
	v_mfma_f32_32x32x16_bf16 v[50:65], v[74:77], v[78:81], v[50:65]
	v_xor_b32_e32 v86, 0x20, v226
	v_add_u32_e32 v82, v86, v224
	v_add_u32_e32 v86, v86, v225
	v_mfma_f32_32x32x16_bf16 v[34:49], v[70:73], v[78:81], v[34:49]
	ds_read_b128 v[78:81], v82
	ds_read_b128 v[82:85], v82 offset:4096
	v_mfma_f32_32x32x16_bf16 v[18:33], v[74:77], v[66:69], v[18:33]
	ds_read_b128 v[74:77], v86 offset:32768
	ds_read_b128 v[86:89], v86 offset:36864
	v_mfma_f32_32x32x16_bf16 v[2:17], v[70:73], v[66:69], v[2:17]
	s_waitcnt lgkmcnt(0)
	v_mfma_f32_32x32x16_bf16 v[50:65], v[74:77], v[78:81], v[50:65]
	v_xor_b32_e32 v70, 0x40, v226
	v_add_u32_e32 v66, v70, v224
	v_add_u32_e32 v70, v70, v225
	v_mfma_f32_32x32x16_bf16 v[34:49], v[86:89], v[78:81], v[34:49]
	ds_read_b128 v[78:81], v66
	ds_read_b128 v[66:69], v66 offset:4096
	v_mfma_f32_32x32x16_bf16 v[18:33], v[74:77], v[82:85], v[18:33]
	ds_read_b128 v[74:77], v70 offset:32768
	ds_read_b128 v[70:73], v70 offset:36864
	v_mfma_f32_32x32x16_bf16 v[2:17], v[86:89], v[82:85], v[2:17]
	s_waitcnt lgkmcnt(0)
	v_mfma_f32_32x32x16_bf16 v[50:65], v[74:77], v[78:81], v[50:65]
	v_xor_b32_e32 v86, 0x60, v226
	v_add_u32_e32 v82, v86, v224
	v_add_u32_e32 v86, v86, v225
	v_mfma_f32_32x32x16_bf16 v[34:49], v[70:73], v[78:81], v[34:49]
	ds_read_b128 v[78:81], v82
	ds_read_b128 v[82:85], v82 offset:4096
	v_mfma_f32_32x32x16_bf16 v[18:33], v[74:77], v[66:69], v[18:33]
	ds_read_b128 v[74:77], v86 offset:32768
	ds_read_b128 v[86:89], v86 offset:36864
	v_mfma_f32_32x32x16_bf16 v[2:17], v[70:73], v[66:69], v[2:17]
	s_waitcnt vmcnt(0) lgkmcnt(0)
	s_barrier
	s_waitcnt lgkmcnt(0)
	v_mfma_f32_32x32x16_bf16 v[50:65], v[74:77], v[78:81], v[50:65]
	v_mov_b32_e32 v70, v226
	v_add_u32_e32 v66, v70, v224
	v_add_u32_e32 v70, v70, v225
	v_mfma_f32_32x32x16_bf16 v[34:49], v[86:89], v[78:81], v[34:49]
	ds_read_b128 v[78:81], v66 offset:16384
	ds_read_b128 v[66:69], v66 offset:20480
	s_add_u32 m0, s30, 0x0
	s_nop 0
	global_load_lds_dwordx4 v200, s[98:99]
	s_add_u32 m0, s30, 0x1000
	s_nop 0
	global_load_lds_dwordx4 v201, s[98:99]
	v_mfma_f32_32x32x16_bf16 v[18:33], v[74:77], v[82:85], v[18:33]
	ds_read_b128 v[74:77], v70 offset:49152
	ds_read_b128 v[70:73], v70 offset:53248
	s_add_u32 m0, s30, 0x2000
	s_nop 0
	global_load_lds_dwordx4 v202, s[98:99]
	s_add_u32 m0, s30, 0x3000
	s_nop 0
	global_load_lds_dwordx4 v204, s[98:99]
	v_mfma_f32_32x32x16_bf16 v[2:17], v[86:89], v[82:85], v[2:17]
	s_add_u32 m0, s30, 0x8000
	s_nop 0
	global_load_lds_dwordx4 v200, s[100:101]
	s_add_u32 m0, s30, 0x9000
	s_nop 0
	global_load_lds_dwordx4 v201, s[100:101]
	s_add_u32 m0, s30, 0xa000
	s_nop 0
	global_load_lds_dwordx4 v202, s[100:101]
	s_add_u32 m0, s30, 0xb000
	s_nop 0
	global_load_lds_dwordx4 v204, s[100:101]
	s_add_u32 s98, s98, 0x80
	s_addc_u32 s99, s99, 0
	s_add_u32 s100, s100, 0x80
	s_addc_u32 s101, s101, 0
	s_waitcnt lgkmcnt(0)
	v_mfma_f32_32x32x16_bf16 v[50:65], v[74:77], v[78:81], v[50:65]
	v_xor_b32_e32 v86, 0x20, v226
	v_add_u32_e32 v82, v86, v224
	v_add_u32_e32 v86, v86, v225
	v_mfma_f32_32x32x16_bf16 v[34:49], v[70:73], v[78:81], v[34:49]
	ds_read_b128 v[78:81], v82 offset:16384
	ds_read_b128 v[82:85], v82 offset:20480
	v_mfma_f32_32x32x16_bf16 v[18:33], v[74:77], v[66:69], v[18:33]
	ds_read_b128 v[74:77], v86 offset:49152
	ds_read_b128 v[86:89], v86 offset:53248
	v_mfma_f32_32x32x16_bf16 v[2:17], v[70:73], v[66:69], v[2:17]
	s_waitcnt lgkmcnt(0)
	v_mfma_f32_32x32x16_bf16 v[50:65], v[74:77], v[78:81], v[50:65]
	v_xor_b32_e32 v70, 0x40, v226
	v_add_u32_e32 v66, v70, v224
	v_add_u32_e32 v70, v70, v225
	v_mfma_f32_32x32x16_bf16 v[34:49], v[86:89], v[78:81], v[34:49]
	ds_read_b128 v[78:81], v66 offset:16384
	ds_read_b128 v[66:69], v66 offset:20480
	v_mfma_f32_32x32x16_bf16 v[18:33], v[74:77], v[82:85], v[18:33]
	ds_read_b128 v[74:77], v70 offset:49152
	ds_read_b128 v[70:73], v70 offset:53248
	v_mfma_f32_32x32x16_bf16 v[2:17], v[86:89], v[82:85], v[2:17]
	s_waitcnt lgkmcnt(0)
	v_mfma_f32_32x32x16_bf16 v[50:65], v[74:77], v[78:81], v[50:65]
	v_xor_b32_e32 v86, 0x60, v226
	v_add_u32_e32 v82, v86, v224
	v_add_u32_e32 v86, v86, v225
	v_mfma_f32_32x32x16_bf16 v[34:49], v[70:73], v[78:81], v[34:49]
	ds_read_b128 v[78:81], v82 offset:16384
	ds_read_b128 v[82:85], v82 offset:20480
	v_mfma_f32_32x32x16_bf16 v[18:33], v[74:77], v[66:69], v[18:33]
	ds_read_b128 v[74:77], v86 offset:49152
	ds_read_b128 v[86:89], v86 offset:53248
	v_mfma_f32_32x32x16_bf16 v[2:17], v[70:73], v[66:69], v[2:17]
	s_waitcnt vmcnt(0) lgkmcnt(0)
	s_barrier
	s_waitcnt lgkmcnt(0)
	v_mfma_f32_32x32x16_bf16 v[50:65], v[74:77], v[78:81], v[50:65]
	v_mov_b32_e32 v70, v226
	v_add_u32_e32 v66, v70, v224
	v_add_u32_e32 v70, v70, v225
	v_mfma_f32_32x32x16_bf16 v[34:49], v[86:89], v[78:81], v[34:49]
	ds_read_b128 v[78:81], v66
	ds_read_b128 v[66:69], v66 offset:4096
	s_add_u32 m0, s30, 0x4000
	s_nop 0
	global_load_lds_dwordx4 v200, s[98:99]
	s_add_u32 m0, s30, 0x5000
	s_nop 0
	global_load_lds_dwordx4 v201, s[98:99]
	v_mfma_f32_32x32x16_bf16 v[18:33], v[74:77], v[82:85], v[18:33]
	ds_read_b128 v[74:77], v70 offset:32768
	ds_read_b128 v[70:73], v70 offset:36864
	s_add_u32 m0, s30, 0x6000
	s_nop 0
	global_load_lds_dwordx4 v202, s[98:99]
	s_add_u32 m0, s30, 0x7000
	s_nop 0
	global_load_lds_dwordx4 v204, s[98:99]
	v_mfma_f32_32x32x16_bf16 v[2:17], v[86:89], v[82:85], v[2:17]
	s_add_u32 m0, s30, 0xc000
	s_nop 0
	global_load_lds_dwordx4 v200, s[100:101]
	s_add_u32 m0, s30, 0xd000
	s_nop 0
	global_load_lds_dwordx4 v201, s[100:101]
	s_add_u32 m0, s30, 0xe000
	s_nop 0
	global_load_lds_dwordx4 v202, s[100:101]
	s_add_u32 m0, s30, 0xf000
	s_nop 0
	global_load_lds_dwordx4 v204, s[100:101]
	s_add_u32 s98, s98, 0x80
	s_addc_u32 s99, s99, 0
	s_add_u32 s100, s100, 0x80
	s_addc_u32 s101, s101, 0
	s_waitcnt lgkmcnt(0)
	v_mfma_f32_32x32x16_bf16 v[50:65], v[74:77], v[78:81], v[50:65]
	v_xor_b32_e32 v86, 0x20, v226
	v_add_u32_e32 v82, v86, v224
	v_add_u32_e32 v86, v86, v225
	v_mfma_f32_32x32x16_bf16 v[34:49], v[70:73], v[78:81], v[34:49]
	ds_read_b128 v[78:81], v82
	ds_read_b128 v[82:85], v82 offset:4096
	v_mfma_f32_32x32x16_bf16 v[18:33], v[74:77], v[66:69], v[18:33]
	ds_read_b128 v[74:77], v86 offset:32768
	ds_read_b128 v[86:89], v86 offset:36864
	v_mfma_f32_32x32x16_bf16 v[2:17], v[70:73], v[66:69], v[2:17]
	s_waitcnt lgkmcnt(0)
	v_mfma_f32_32x32x16_bf16 v[50:65], v[74:77], v[78:81], v[50:65]
	v_xor_b32_e32 v70, 0x40, v226
	v_add_u32_e32 v66, v70, v224
	v_add_u32_e32 v70, v70, v225
	v_mfma_f32_32x32x16_bf16 v[34:49], v[86:89], v[78:81], v[34:49]
	ds_read_b128 v[78:81], v66
	ds_read_b128 v[66:69], v66 offset:4096
	v_mfma_f32_32x32x16_bf16 v[18:33], v[74:77], v[82:85], v[18:33]
	ds_read_b128 v[74:77], v70 offset:32768
	ds_read_b128 v[70:73], v70 offset:36864
	v_mfma_f32_32x32x16_bf16 v[2:17], v[86:89], v[82:85], v[2:17]
	s_waitcnt lgkmcnt(0)
	v_mfma_f32_32x32x16_bf16 v[50:65], v[74:77], v[78:81], v[50:65]
	v_xor_b32_e32 v86, 0x60, v226
	v_add_u32_e32 v82, v86, v224
	v_add_u32_e32 v86, v86, v225
	v_mfma_f32_32x32x16_bf16 v[34:49], v[70:73], v[78:81], v[34:49]
	ds_read_b128 v[78:81], v82
	ds_read_b128 v[82:85], v82 offset:4096
	v_mfma_f32_32x32x16_bf16 v[18:33], v[74:77], v[66:69], v[18:33]
	ds_read_b128 v[74:77], v86 offset:32768
	ds_read_b128 v[86:89], v86 offset:36864
	v_mfma_f32_32x32x16_bf16 v[2:17], v[70:73], v[66:69], v[2:17]
	s_waitcnt vmcnt(0) lgkmcnt(0)
	s_barrier
	s_waitcnt lgkmcnt(0)
	v_mfma_f32_32x32x16_bf16 v[50:65], v[74:77], v[78:81], v[50:65]
	v_mov_b32_e32 v70, v226
	v_add_u32_e32 v66, v70, v224
	v_add_u32_e32 v70, v70, v225
	v_mfma_f32_32x32x16_bf16 v[34:49], v[86:89], v[78:81], v[34:49]
	ds_read_b128 v[78:81], v66 offset:16384
	ds_read_b128 v[66:69], v66 offset:20480
	s_add_u32 m0, s30, 0x0
	s_nop 0
	global_load_lds_dwordx4 v200, s[98:99]
	s_add_u32 m0, s30, 0x1000
	s_nop 0
	global_load_lds_dwordx4 v201, s[98:99]
	v_mfma_f32_32x32x16_bf16 v[18:33], v[74:77], v[82:85], v[18:33]
	ds_read_b128 v[74:77], v70 offset:49152
	ds_read_b128 v[70:73], v70 offset:53248
	s_add_u32 m0, s30, 0x2000
	s_nop 0
	global_load_lds_dwordx4 v202, s[98:99]
	s_add_u32 m0, s30, 0x3000
	s_nop 0
	global_load_lds_dwordx4 v204, s[98:99]
	v_mfma_f32_32x32x16_bf16 v[2:17], v[86:89], v[82:85], v[2:17]
	s_add_u32 m0, s30, 0x8000
	s_nop 0
	global_load_lds_dwordx4 v200, s[100:101]
	s_add_u32 m0, s30, 0x9000
	s_nop 0
	global_load_lds_dwordx4 v201, s[100:101]
	s_add_u32 m0, s30, 0xa000
	s_nop 0
	global_load_lds_dwordx4 v202, s[100:101]
	s_add_u32 m0, s30, 0xb000
	s_nop 0
	global_load_lds_dwordx4 v204, s[100:101]
	s_add_u32 s98, s98, 0x80
	s_addc_u32 s99, s99, 0
	s_add_u32 s100, s100, 0x80
	s_addc_u32 s101, s101, 0
	s_waitcnt lgkmcnt(0)
	v_mfma_f32_32x32x16_bf16 v[50:65], v[74:77], v[78:81], v[50:65]
	v_xor_b32_e32 v86, 0x20, v226
	v_add_u32_e32 v82, v86, v224
	v_add_u32_e32 v86, v86, v225
	v_mfma_f32_32x32x16_bf16 v[34:49], v[70:73], v[78:81], v[34:49]
	ds_read_b128 v[78:81], v82 offset:16384
	ds_read_b128 v[82:85], v82 offset:20480
	v_mfma_f32_32x32x16_bf16 v[18:33], v[74:77], v[66:69], v[18:33]
	ds_read_b128 v[74:77], v86 offset:49152
	ds_read_b128 v[86:89], v86 offset:53248
	v_mfma_f32_32x32x16_bf16 v[2:17], v[70:73], v[66:69], v[2:17]
	s_waitcnt lgkmcnt(0)
	v_mfma_f32_32x32x16_bf16 v[50:65], v[74:77], v[78:81], v[50:65]
	v_xor_b32_e32 v70, 0x40, v226
	v_add_u32_e32 v66, v70, v224
	v_add_u32_e32 v70, v70, v225
	v_mfma_f32_32x32x16_bf16 v[34:49], v[86:89], v[78:81], v[34:49]
	ds_read_b128 v[78:81], v66 offset:16384
	ds_read_b128 v[66:69], v66 offset:20480
	v_mfma_f32_32x32x16_bf16 v[18:33], v[74:77], v[82:85], v[18:33]
	ds_read_b128 v[74:77], v70 offset:49152
	ds_read_b128 v[70:73], v70 offset:53248
	v_mfma_f32_32x32x16_bf16 v[2:17], v[86:89], v[82:85], v[2:17]
	s_waitcnt lgkmcnt(0)
	v_mfma_f32_32x32x16_bf16 v[50:65], v[74:77], v[78:81], v[50:65]
	v_xor_b32_e32 v86, 0x60, v226
	v_add_u32_e32 v82, v86, v224
	v_add_u32_e32 v86, v86, v225
	v_mfma_f32_32x32x16_bf16 v[34:49], v[70:73], v[78:81], v[34:49]
	ds_read_b128 v[78:81], v82 offset:16384
	ds_read_b128 v[82:85], v82 offset:20480
	v_mfma_f32_32x32x16_bf16 v[18:33], v[74:77], v[66:69], v[18:33]
	ds_read_b128 v[74:77], v86 offset:49152
	ds_read_b128 v[86:89], v86 offset:53248
	v_mfma_f32_32x32x16_bf16 v[2:17], v[70:73], v[66:69], v[2:17]
	s_waitcnt vmcnt(0) lgkmcnt(0)
	s_barrier
	s_waitcnt lgkmcnt(0)
	v_mfma_f32_32x32x16_bf16 v[50:65], v[74:77], v[78:81], v[50:65]
	v_mov_b32_e32 v70, v226
	v_add_u32_e32 v66, v70, v224
	v_add_u32_e32 v70, v70, v225
	v_mfma_f32_32x32x16_bf16 v[34:49], v[86:89], v[78:81], v[34:49]
	ds_read_b128 v[78:81], v66
	ds_read_b128 v[66:69], v66 offset:4096
	s_add_u32 m0, s30, 0x4000
	s_nop 0
	global_load_lds_dwordx4 v200, s[98:99]
	s_add_u32 m0, s30, 0x5000
	s_nop 0
	global_load_lds_dwordx4 v201, s[98:99]
	v_mfma_f32_32x32x16_bf16 v[18:33], v[74:77], v[82:85], v[18:33]
	ds_read_b128 v[74:77], v70 offset:32768
	ds_read_b128 v[70:73], v70 offset:36864
	s_add_u32 m0, s30, 0x6000
	s_nop 0
	global_load_lds_dwordx4 v202, s[98:99]
	s_add_u32 m0, s30, 0x7000
	s_nop 0
	global_load_lds_dwordx4 v204, s[98:99]
	v_mfma_f32_32x32x16_bf16 v[2:17], v[86:89], v[82:85], v[2:17]
	s_add_u32 m0, s30, 0xc000
	s_nop 0
	global_load_lds_dwordx4 v200, s[100:101]
	s_add_u32 m0, s30, 0xd000
	s_nop 0
	global_load_lds_dwordx4 v201, s[100:101]
	s_add_u32 m0, s30, 0xe000
	s_nop 0
	global_load_lds_dwordx4 v202, s[100:101]
	s_add_u32 m0, s30, 0xf000
	s_nop 0
	global_load_lds_dwordx4 v204, s[100:101]
	s_add_u32 s98, s98, 0x80
	s_addc_u32 s99, s99, 0
	s_add_u32 s100, s100, 0x80
	s_addc_u32 s101, s101, 0
	s_waitcnt lgkmcnt(0)
	v_mfma_f32_32x32x16_bf16 v[50:65], v[74:77], v[78:81], v[50:65]
	v_xor_b32_e32 v86, 0x20, v226
	v_add_u32_e32 v82, v86, v224
	v_add_u32_e32 v86, v86, v225
	v_mfma_f32_32x32x16_bf16 v[34:49], v[70:73], v[78:81], v[34:49]
	ds_read_b128 v[78:81], v82
	ds_read_b128 v[82:85], v82 offset:4096
	v_mfma_f32_32x32x16_bf16 v[18:33], v[74:77], v[66:69], v[18:33]
	ds_read_b128 v[74:77], v86 offset:32768
	ds_read_b128 v[86:89], v86 offset:36864
	v_mfma_f32_32x32x16_bf16 v[2:17], v[70:73], v[66:69], v[2:17]
	s_waitcnt lgkmcnt(0)
	v_mfma_f32_32x32x16_bf16 v[50:65], v[74:77], v[78:81], v[50:65]
	v_xor_b32_e32 v70, 0x40, v226
	v_add_u32_e32 v66, v70, v224
	v_add_u32_e32 v70, v70, v225
	v_mfma_f32_32x32x16_bf16 v[34:49], v[86:89], v[78:81], v[34:49]
	ds_read_b128 v[78:81], v66
	ds_read_b128 v[66:69], v66 offset:4096
	v_mfma_f32_32x32x16_bf16 v[18:33], v[74:77], v[82:85], v[18:33]
	ds_read_b128 v[74:77], v70 offset:32768
	ds_read_b128 v[70:73], v70 offset:36864
	v_mfma_f32_32x32x16_bf16 v[2:17], v[86:89], v[82:85], v[2:17]
	s_waitcnt lgkmcnt(0)
	v_mfma_f32_32x32x16_bf16 v[50:65], v[74:77], v[78:81], v[50:65]
	v_xor_b32_e32 v86, 0x60, v226
	v_add_u32_e32 v82, v86, v224
	v_add_u32_e32 v86, v86, v225
	v_mfma_f32_32x32x16_bf16 v[34:49], v[70:73], v[78:81], v[34:49]
	ds_read_b128 v[78:81], v82
	ds_read_b128 v[82:85], v82 offset:4096
	v_mfma_f32_32x32x16_bf16 v[18:33], v[74:77], v[66:69], v[18:33]
	ds_read_b128 v[74:77], v86 offset:32768
	ds_read_b128 v[86:89], v86 offset:36864
	v_mfma_f32_32x32x16_bf16 v[2:17], v[70:73], v[66:69], v[2:17]
	s_add_u32 s98, s48, 0x300
	s_addc_u32 s99, s49, 0
	s_add_u32 s100, s44, 0x300
	s_addc_u32 s101, s45, 0
	s_waitcnt vmcnt(0) lgkmcnt(0)
	s_barrier
	s_waitcnt lgkmcnt(0)
	v_mfma_f32_32x32x16_bf16 v[50:65], v[74:77], v[78:81], v[50:65]
	v_mov_b32_e32 v70, v226
	v_add_u32_e32 v66, v70, v224
	v_add_u32_e32 v70, v70, v225
	v_mfma_f32_32x32x16_bf16 v[34:49], v[86:89], v[78:81], v[34:49]
	ds_read_b128 v[78:81], v66 offset:16384
	ds_read_b128 v[66:69], v66 offset:20480
	s_add_u32 m0, s30, 0x0
	s_nop 0
	global_load_lds_dwordx4 v200, s[98:99]
	s_add_u32 m0, s30, 0x1000
	s_nop 0
	global_load_lds_dwordx4 v201, s[98:99]
	v_mfma_f32_32x32x16_bf16 v[18:33], v[74:77], v[82:85], v[18:33]
	ds_read_b128 v[74:77], v70 offset:49152
	ds_read_b128 v[70:73], v70 offset:53248
	s_add_u32 m0, s30, 0x2000
	s_nop 0
	global_load_lds_dwordx4 v202, s[98:99]
	s_add_u32 m0, s30, 0x3000
	s_nop 0
	global_load_lds_dwordx4 v204, s[98:99]
	v_mfma_f32_32x32x16_bf16 v[2:17], v[86:89], v[82:85], v[2:17]
	s_add_u32 m0, s30, 0x8000
	s_nop 0
	global_load_lds_dwordx4 v200, s[100:101]
	s_add_u32 m0, s30, 0x9000
	s_nop 0
	global_load_lds_dwordx4 v201, s[100:101]
	s_add_u32 m0, s30, 0xa000
	s_nop 0
	global_load_lds_dwordx4 v202, s[100:101]
	s_add_u32 m0, s30, 0xb000
	s_nop 0
	global_load_lds_dwordx4 v204, s[100:101]
	s_add_u32 s98, s98, 0x80
	s_addc_u32 s99, s99, 0
	s_add_u32 s100, s100, 0x80
	s_addc_u32 s101, s101, 0
	s_waitcnt lgkmcnt(0)
	v_mfma_f32_32x32x16_bf16 v[50:65], v[74:77], v[78:81], v[50:65]
	v_xor_b32_e32 v86, 0x20, v226
	v_add_u32_e32 v82, v86, v224
	v_add_u32_e32 v86, v86, v225
	v_mfma_f32_32x32x16_bf16 v[34:49], v[70:73], v[78:81], v[34:49]
	ds_read_b128 v[78:81], v82 offset:16384
	ds_read_b128 v[82:85], v82 offset:20480
	v_mfma_f32_32x32x16_bf16 v[18:33], v[74:77], v[66:69], v[18:33]
	ds_read_b128 v[74:77], v86 offset:49152
	ds_read_b128 v[86:89], v86 offset:53248
	v_mfma_f32_32x32x16_bf16 v[2:17], v[70:73], v[66:69], v[2:17]
	s_waitcnt lgkmcnt(0)
	v_mfma_f32_32x32x16_bf16 v[50:65], v[74:77], v[78:81], v[50:65]
	v_xor_b32_e32 v70, 0x40, v226
	v_add_u32_e32 v66, v70, v224
	v_add_u32_e32 v70, v70, v225
	v_mfma_f32_32x32x16_bf16 v[34:49], v[86:89], v[78:81], v[34:49]
	ds_read_b128 v[78:81], v66 offset:16384
	ds_read_b128 v[66:69], v66 offset:20480
	v_mfma_f32_32x32x16_bf16 v[18:33], v[74:77], v[82:85], v[18:33]
	ds_read_b128 v[74:77], v70 offset:49152
	ds_read_b128 v[70:73], v70 offset:53248
	v_mfma_f32_32x32x16_bf16 v[2:17], v[86:89], v[82:85], v[2:17]
	s_waitcnt lgkmcnt(0)
	v_mfma_f32_32x32x16_bf16 v[50:65], v[74:77], v[78:81], v[50:65]
	v_xor_b32_e32 v86, 0x60, v226
	v_add_u32_e32 v82, v86, v224
	v_add_u32_e32 v86, v86, v225
	v_mfma_f32_32x32x16_bf16 v[34:49], v[70:73], v[78:81], v[34:49]
	ds_read_b128 v[78:81], v82 offset:16384
	ds_read_b128 v[82:85], v82 offset:20480
	v_mfma_f32_32x32x16_bf16 v[18:33], v[74:77], v[66:69], v[18:33]
	ds_read_b128 v[74:77], v86 offset:49152
	ds_read_b128 v[86:89], v86 offset:53248
	v_mfma_f32_32x32x16_bf16 v[2:17], v[70:73], v[66:69], v[2:17]
	s_waitcnt vmcnt(0) lgkmcnt(0)
	s_barrier
	s_waitcnt lgkmcnt(0)
	v_mfma_f32_32x32x16_bf16 v[50:65], v[74:77], v[78:81], v[50:65]
	v_mov_b32_e32 v70, v226
	v_add_u32_e32 v66, v70, v224
	v_add_u32_e32 v70, v70, v225
	v_mfma_f32_32x32x16_bf16 v[34:49], v[86:89], v[78:81], v[34:49]
	ds_read_b128 v[78:81], v66
	ds_read_b128 v[66:69], v66 offset:4096
	s_add_u32 m0, s30, 0x4000
	s_nop 0
	global_load_lds_dwordx4 v200, s[98:99]
	s_add_u32 m0, s30, 0x5000
	s_nop 0
	global_load_lds_dwordx4 v201, s[98:99]
	v_mfma_f32_32x32x16_bf16 v[18:33], v[74:77], v[82:85], v[18:33]
	ds_read_b128 v[74:77], v70 offset:32768
	ds_read_b128 v[70:73], v70 offset:36864
	s_add_u32 m0, s30, 0x6000
	s_nop 0
	global_load_lds_dwordx4 v202, s[98:99]
	s_add_u32 m0, s30, 0x7000
	s_nop 0
	global_load_lds_dwordx4 v204, s[98:99]
	v_mfma_f32_32x32x16_bf16 v[2:17], v[86:89], v[82:85], v[2:17]
	s_add_u32 m0, s30, 0xc000
	s_nop 0
	global_load_lds_dwordx4 v200, s[100:101]
	s_add_u32 m0, s30, 0xd000
	s_nop 0
	global_load_lds_dwordx4 v201, s[100:101]
	s_add_u32 m0, s30, 0xe000
	s_nop 0
	global_load_lds_dwordx4 v202, s[100:101]
	s_add_u32 m0, s30, 0xf000
	s_nop 0
	global_load_lds_dwordx4 v204, s[100:101]
	s_add_u32 s98, s98, 0x80
	s_addc_u32 s99, s99, 0
	s_add_u32 s100, s100, 0x80
	s_addc_u32 s101, s101, 0
	s_nop 15
	v_lshlrev_b32_e32 v220, 16, v98
	v_and_b32_e32 v221, 0xffff0000, v98
	v_mul_f32_e32 v227, v2, v220
	v_mul_f32_e32 v228, v3, v221
	v_lshlrev_b32_e32 v220, 16, v99
	v_and_b32_e32 v221, 0xffff0000, v99
	v_mul_f32_e32 v229, v4, v220
	v_mul_f32_e32 v230, v5, v221
	v_lshlrev_b32_e32 v220, 16, v100
	v_and_b32_e32 v221, 0xffff0000, v100
	v_mul_f32_e32 v231, v6, v220
	v_mul_f32_e32 v232, v7, v221
	v_lshlrev_b32_e32 v220, 16, v101
	v_and_b32_e32 v221, 0xffff0000, v101
	v_mul_f32_e32 v233, v8, v220
	v_mul_f32_e32 v234, v9, v221
	v_lshlrev_b32_e32 v220, 16, v102
	v_and_b32_e32 v221, 0xffff0000, v102
	v_mul_f32_e32 v235, v10, v220
	v_mul_f32_e32 v236, v11, v221
	v_lshlrev_b32_e32 v220, 16, v103
	v_and_b32_e32 v221, 0xffff0000, v103
	v_mul_f32_e32 v237, v12, v220
	v_mul_f32_e32 v238, v13, v221
	v_lshlrev_b32_e32 v220, 16, v104
	v_and_b32_e32 v221, 0xffff0000, v104
	v_mul_f32_e32 v239, v14, v220
	v_mul_f32_e32 v240, v15, v221
	v_lshlrev_b32_e32 v220, 16, v105
	v_and_b32_e32 v221, 0xffff0000, v105
	v_mul_f32_e32 v241, v16, v220
	v_mul_f32_e32 v242, v17, v221
	v_lshlrev_b32_e32 v220, 16, v106
	v_and_b32_e32 v221, 0xffff0000, v106
	v_mul_f32_e32 v243, v18, v220
	v_mul_f32_e32 v244, v19, v221
	v_lshlrev_b32_e32 v220, 16, v107
	v_and_b32_e32 v221, 0xffff0000, v107
	v_mul_f32_e32 v245, v20, v220
	v_mul_f32_e32 v246, v21, v221
	v_lshlrev_b32_e32 v220, 16, v108
	v_and_b32_e32 v221, 0xffff0000, v108
	v_mul_f32_e32 v247, v22, v220
	v_mul_f32_e32 v248, v23, v221
	v_lshlrev_b32_e32 v220, 16, v109
	v_and_b32_e32 v221, 0xffff0000, v109
	v_mul_f32_e32 v249, v24, v220
	v_mul_f32_e32 v250, v25, v221
	v_lshlrev_b32_e32 v220, 16, v110
	v_and_b32_e32 v221, 0xffff0000, v110
	v_mul_f32_e32 v251, v26, v220
	v_mul_f32_e32 v90, v27, v221
	v_lshlrev_b32_e32 v220, 16, v111
	v_and_b32_e32 v221, 0xffff0000, v111
	v_mul_f32_e32 v91, v28, v220
	v_mul_f32_e32 v92, v29, v221
	v_lshlrev_b32_e32 v220, 16, v112
	v_and_b32_e32 v221, 0xffff0000, v112
	v_mul_f32_e32 v93, v30, v220
	v_mul_f32_e32 v94, v31, v221
	v_lshlrev_b32_e32 v220, 16, v113
	v_and_b32_e32 v221, 0xffff0000, v113
	v_mul_f32_e32 v95, v32, v220
	v_mul_f32_e32 v96, v33, v221
	v_lshlrev_b32_e32 v220, 16, v114
	v_and_b32_e32 v221, 0xffff0000, v114
	v_mul_f32_e32 v98, v34, v220
	v_mul_f32_e32 v99, v35, v221
	v_lshlrev_b32_e32 v220, 16, v115
	v_and_b32_e32 v221, 0xffff0000, v115
	v_mul_f32_e32 v100, v36, v220
	v_mul_f32_e32 v101, v37, v221
	v_lshlrev_b32_e32 v220, 16, v116
	v_and_b32_e32 v221, 0xffff0000, v116
	v_mul_f32_e32 v102, v38, v220
	v_mul_f32_e32 v103, v39, v221
	v_lshlrev_b32_e32 v220, 16, v117
	v_and_b32_e32 v221, 0xffff0000, v117
	v_mul_f32_e32 v104, v40, v220
	v_mul_f32_e32 v105, v41, v221
	v_lshlrev_b32_e32 v220, 16, v118
	v_and_b32_e32 v221, 0xffff0000, v118
	v_mul_f32_e32 v106, v42, v220
	v_mul_f32_e32 v107, v43, v221
	v_lshlrev_b32_e32 v220, 16, v119
	v_and_b32_e32 v221, 0xffff0000, v119
	v_mul_f32_e32 v108, v44, v220
	v_mul_f32_e32 v109, v45, v221
	v_lshlrev_b32_e32 v220, 16, v120
	v_and_b32_e32 v221, 0xffff0000, v120
	v_mul_f32_e32 v110, v46, v220
	v_mul_f32_e32 v111, v47, v221
	v_lshlrev_b32_e32 v220, 16, v121
	v_and_b32_e32 v221, 0xffff0000, v121
	v_mul_f32_e32 v112, v48, v220
	v_mul_f32_e32 v113, v49, v221
	v_lshlrev_b32_e32 v220, 16, v122
	v_and_b32_e32 v221, 0xffff0000, v122
	v_mul_f32_e32 v114, v50, v220
	v_mul_f32_e32 v115, v51, v221
	v_lshlrev_b32_e32 v220, 16, v123
	v_and_b32_e32 v221, 0xffff0000, v123
	v_mul_f32_e32 v116, v52, v220
	v_mul_f32_e32 v117, v53, v221
	v_lshlrev_b32_e32 v220, 16, v124
	v_and_b32_e32 v221, 0xffff0000, v124
	v_mul_f32_e32 v118, v54, v220
	v_mul_f32_e32 v119, v55, v221
	v_lshlrev_b32_e32 v220, 16, v125
	v_and_b32_e32 v221, 0xffff0000, v125
	v_mul_f32_e32 v120, v56, v220
	v_mul_f32_e32 v121, v57, v221
	v_lshlrev_b32_e32 v220, 16, v126
	v_and_b32_e32 v221, 0xffff0000, v126
	v_mul_f32_e32 v122, v58, v220
	v_mul_f32_e32 v123, v59, v221
	v_lshlrev_b32_e32 v220, 16, v127
	v_and_b32_e32 v221, 0xffff0000, v127
	v_mul_f32_e32 v124, v60, v220
	v_mul_f32_e32 v125, v61, v221
	v_lshlrev_b32_e32 v220, 16, v128
	v_and_b32_e32 v221, 0xffff0000, v128
	v_mul_f32_e32 v126, v62, v220
	v_mul_f32_e32 v127, v63, v221
	v_lshlrev_b32_e32 v220, 16, v129
	v_and_b32_e32 v221, 0xffff0000, v129
	v_mul_f32_e32 v128, v64, v220
	v_mul_f32_e32 v129, v65, v221
	v_mov_b32_e32 v2, 0
	v_mov_b32_e32 v3, 0
	v_mov_b32_e32 v4, 0
	v_mov_b32_e32 v5, 0
	v_mov_b32_e32 v6, 0
	v_mov_b32_e32 v7, 0
	v_mov_b32_e32 v8, 0
	v_mov_b32_e32 v9, 0
	v_mov_b32_e32 v10, 0
	v_mov_b32_e32 v11, 0
	v_mov_b32_e32 v12, 0
	v_mov_b32_e32 v13, 0
	v_mov_b32_e32 v14, 0
	v_mov_b32_e32 v15, 0
	v_mov_b32_e32 v16, 0
	v_mov_b32_e32 v17, 0
	v_mov_b32_e32 v18, 0
	v_mov_b32_e32 v19, 0
	v_mov_b32_e32 v20, 0
	v_mov_b32_e32 v21, 0
	v_mov_b32_e32 v22, 0
	v_mov_b32_e32 v23, 0
	v_mov_b32_e32 v24, 0
	v_mov_b32_e32 v25, 0
	v_mov_b32_e32 v26, 0
	v_mov_b32_e32 v27, 0
	v_mov_b32_e32 v28, 0
	v_mov_b32_e32 v29, 0
	v_mov_b32_e32 v30, 0
	v_mov_b32_e32 v31, 0
	v_mov_b32_e32 v32, 0
	v_mov_b32_e32 v33, 0
	v_mov_b32_e32 v34, 0
	v_mov_b32_e32 v35, 0
	v_mov_b32_e32 v36, 0
	v_mov_b32_e32 v37, 0
	v_mov_b32_e32 v38, 0
	v_mov_b32_e32 v39, 0
	v_mov_b32_e32 v40, 0
	v_mov_b32_e32 v41, 0
	v_mov_b32_e32 v42, 0
	v_mov_b32_e32 v43, 0
	v_mov_b32_e32 v44, 0
	v_mov_b32_e32 v45, 0
	v_mov_b32_e32 v46, 0
	v_mov_b32_e32 v47, 0
	v_mov_b32_e32 v48, 0
	v_mov_b32_e32 v49, 0
	v_mov_b32_e32 v50, 0
	v_mov_b32_e32 v51, 0
	v_mov_b32_e32 v52, 0
	v_mov_b32_e32 v53, 0
	v_mov_b32_e32 v54, 0
	v_mov_b32_e32 v55, 0
	v_mov_b32_e32 v56, 0
	v_mov_b32_e32 v57, 0
	v_mov_b32_e32 v58, 0
	v_mov_b32_e32 v59, 0
	v_mov_b32_e32 v60, 0
	v_mov_b32_e32 v61, 0
	v_mov_b32_e32 v62, 0
	v_mov_b32_e32 v63, 0
	v_mov_b32_e32 v64, 0
	v_mov_b32_e32 v65, 0
	s_nop 4
	s_waitcnt lgkmcnt(0)
	v_mfma_f32_32x32x16_bf16 v[50:65], v[74:77], v[78:81], v[50:65]
	v_xor_b32_e32 v86, 0x20, v226
	v_add_u32_e32 v82, v86, v224
	v_add_u32_e32 v86, v86, v225
	v_mfma_f32_32x32x16_bf16 v[34:49], v[70:73], v[78:81], v[34:49]
	ds_read_b128 v[78:81], v82
	ds_read_b128 v[82:85], v82 offset:4096
	v_mfma_f32_32x32x16_bf16 v[18:33], v[74:77], v[66:69], v[18:33]
	ds_read_b128 v[74:77], v86 offset:32768
	ds_read_b128 v[86:89], v86 offset:36864
	v_mfma_f32_32x32x16_bf16 v[2:17], v[70:73], v[66:69], v[2:17]
	s_waitcnt lgkmcnt(0)
	v_mfma_f32_32x32x16_bf16 v[50:65], v[74:77], v[78:81], v[50:65]
	v_xor_b32_e32 v70, 0x40, v226
	v_add_u32_e32 v66, v70, v224
	v_add_u32_e32 v70, v70, v225
	v_mfma_f32_32x32x16_bf16 v[34:49], v[86:89], v[78:81], v[34:49]
	ds_read_b128 v[78:81], v66
	ds_read_b128 v[66:69], v66 offset:4096
	v_mfma_f32_32x32x16_bf16 v[18:33], v[74:77], v[82:85], v[18:33]
	ds_read_b128 v[74:77], v70 offset:32768
	ds_read_b128 v[70:73], v70 offset:36864
	v_mfma_f32_32x32x16_bf16 v[2:17], v[86:89], v[82:85], v[2:17]
	s_waitcnt lgkmcnt(0)
	v_mfma_f32_32x32x16_bf16 v[50:65], v[74:77], v[78:81], v[50:65]
	v_xor_b32_e32 v86, 0x60, v226
	v_add_u32_e32 v82, v86, v224
	v_add_u32_e32 v86, v86, v225
	v_mfma_f32_32x32x16_bf16 v[34:49], v[70:73], v[78:81], v[34:49]
	ds_read_b128 v[78:81], v82
	ds_read_b128 v[82:85], v82 offset:4096
	v_mfma_f32_32x32x16_bf16 v[18:33], v[74:77], v[66:69], v[18:33]
	ds_read_b128 v[74:77], v86 offset:32768
	ds_read_b128 v[86:89], v86 offset:36864
	v_mfma_f32_32x32x16_bf16 v[2:17], v[70:73], v[66:69], v[2:17]
	s_waitcnt vmcnt(0) lgkmcnt(0)
	s_barrier
	s_waitcnt lgkmcnt(0)
	v_mfma_f32_32x32x16_bf16 v[50:65], v[74:77], v[78:81], v[50:65]
	v_mov_b32_e32 v70, v226
	v_add_u32_e32 v66, v70, v224
	v_add_u32_e32 v70, v70, v225
	v_mfma_f32_32x32x16_bf16 v[34:49], v[86:89], v[78:81], v[34:49]
	ds_read_b128 v[78:81], v66 offset:16384
	ds_read_b128 v[66:69], v66 offset:20480
	s_add_u32 m0, s30, 0x0
	s_nop 0
	global_load_lds_dwordx4 v200, s[98:99]
	s_add_u32 m0, s30, 0x1000
	s_nop 0
	global_load_lds_dwordx4 v201, s[98:99]
	v_mfma_f32_32x32x16_bf16 v[18:33], v[74:77], v[82:85], v[18:33]
	ds_read_b128 v[74:77], v70 offset:49152
	ds_read_b128 v[70:73], v70 offset:53248
	s_add_u32 m0, s30, 0x2000
	s_nop 0
	global_load_lds_dwordx4 v202, s[98:99]
	s_add_u32 m0, s30, 0x3000
	s_nop 0
	global_load_lds_dwordx4 v204, s[98:99]
	v_mfma_f32_32x32x16_bf16 v[2:17], v[86:89], v[82:85], v[2:17]
	s_add_u32 m0, s30, 0x8000
	s_nop 0
	global_load_lds_dwordx4 v200, s[100:101]
	s_add_u32 m0, s30, 0x9000
	s_nop 0
	global_load_lds_dwordx4 v201, s[100:101]
	s_add_u32 m0, s30, 0xa000
	s_nop 0
	global_load_lds_dwordx4 v202, s[100:101]
	s_add_u32 m0, s30, 0xb000
	s_nop 0
	global_load_lds_dwordx4 v204, s[100:101]
	s_add_u32 s98, s98, 0x80
	s_addc_u32 s99, s99, 0
	s_add_u32 s100, s100, 0x80
	s_addc_u32 s101, s101, 0
	s_waitcnt lgkmcnt(0)
	v_mfma_f32_32x32x16_bf16 v[50:65], v[74:77], v[78:81], v[50:65]
	v_xor_b32_e32 v86, 0x20, v226
	v_add_u32_e32 v82, v86, v224
	v_add_u32_e32 v86, v86, v225
	v_mfma_f32_32x32x16_bf16 v[34:49], v[70:73], v[78:81], v[34:49]
	ds_read_b128 v[78:81], v82 offset:16384
	ds_read_b128 v[82:85], v82 offset:20480
	v_mfma_f32_32x32x16_bf16 v[18:33], v[74:77], v[66:69], v[18:33]
	ds_read_b128 v[74:77], v86 offset:49152
	ds_read_b128 v[86:89], v86 offset:53248
	v_mfma_f32_32x32x16_bf16 v[2:17], v[70:73], v[66:69], v[2:17]
	s_waitcnt lgkmcnt(0)
	v_mfma_f32_32x32x16_bf16 v[50:65], v[74:77], v[78:81], v[50:65]
	v_xor_b32_e32 v70, 0x40, v226
	v_add_u32_e32 v66, v70, v224
	v_add_u32_e32 v70, v70, v225
	v_mfma_f32_32x32x16_bf16 v[34:49], v[86:89], v[78:81], v[34:49]
	ds_read_b128 v[78:81], v66 offset:16384
	ds_read_b128 v[66:69], v66 offset:20480
	v_mfma_f32_32x32x16_bf16 v[18:33], v[74:77], v[82:85], v[18:33]
	ds_read_b128 v[74:77], v70 offset:49152
	ds_read_b128 v[70:73], v70 offset:53248
	v_mfma_f32_32x32x16_bf16 v[2:17], v[86:89], v[82:85], v[2:17]
	s_waitcnt lgkmcnt(0)
	v_mfma_f32_32x32x16_bf16 v[50:65], v[74:77], v[78:81], v[50:65]
	v_xor_b32_e32 v86, 0x60, v226
	v_add_u32_e32 v82, v86, v224
	v_add_u32_e32 v86, v86, v225
	v_mfma_f32_32x32x16_bf16 v[34:49], v[70:73], v[78:81], v[34:49]
	ds_read_b128 v[78:81], v82 offset:16384
	ds_read_b128 v[82:85], v82 offset:20480
	v_mfma_f32_32x32x16_bf16 v[18:33], v[74:77], v[66:69], v[18:33]
	ds_read_b128 v[74:77], v86 offset:49152
	ds_read_b128 v[86:89], v86 offset:53248
	v_mfma_f32_32x32x16_bf16 v[2:17], v[70:73], v[66:69], v[2:17]
	s_waitcnt vmcnt(0) lgkmcnt(0)
	s_barrier
	s_waitcnt lgkmcnt(0)
	v_mfma_f32_32x32x16_bf16 v[50:65], v[74:77], v[78:81], v[50:65]
	v_mov_b32_e32 v70, v226
	v_add_u32_e32 v66, v70, v224
	v_add_u32_e32 v70, v70, v225
	v_mfma_f32_32x32x16_bf16 v[34:49], v[86:89], v[78:81], v[34:49]
	ds_read_b128 v[78:81], v66
	ds_read_b128 v[66:69], v66 offset:4096
	s_add_u32 m0, s30, 0x4000
	s_nop 0
	global_load_lds_dwordx4 v200, s[98:99]
	s_add_u32 m0, s30, 0x5000
	s_nop 0
	global_load_lds_dwordx4 v201, s[98:99]
	v_mfma_f32_32x32x16_bf16 v[18:33], v[74:77], v[82:85], v[18:33]
	ds_read_b128 v[74:77], v70 offset:32768
	ds_read_b128 v[70:73], v70 offset:36864
	s_add_u32 m0, s30, 0x6000
	s_nop 0
	global_load_lds_dwordx4 v202, s[98:99]
	s_add_u32 m0, s30, 0x7000
	s_nop 0
	global_load_lds_dwordx4 v204, s[98:99]
	v_mfma_f32_32x32x16_bf16 v[2:17], v[86:89], v[82:85], v[2:17]
	s_add_u32 m0, s30, 0xc000
	s_nop 0
	global_load_lds_dwordx4 v200, s[100:101]
	s_add_u32 m0, s30, 0xd000
	s_nop 0
	global_load_lds_dwordx4 v201, s[100:101]
	s_add_u32 m0, s30, 0xe000
	s_nop 0
	global_load_lds_dwordx4 v202, s[100:101]
	s_add_u32 m0, s30, 0xf000
	s_nop 0
	global_load_lds_dwordx4 v204, s[100:101]
	s_add_u32 s98, s98, 0x80
	s_addc_u32 s99, s99, 0
	s_add_u32 s100, s100, 0x80
	s_addc_u32 s101, s101, 0
	s_waitcnt lgkmcnt(0)
	v_mfma_f32_32x32x16_bf16 v[50:65], v[74:77], v[78:81], v[50:65]
	v_xor_b32_e32 v86, 0x20, v226
	v_add_u32_e32 v82, v86, v224
	v_add_u32_e32 v86, v86, v225
	v_mfma_f32_32x32x16_bf16 v[34:49], v[70:73], v[78:81], v[34:49]
	ds_read_b128 v[78:81], v82
	ds_read_b128 v[82:85], v82 offset:4096
	v_mfma_f32_32x32x16_bf16 v[18:33], v[74:77], v[66:69], v[18:33]
	ds_read_b128 v[74:77], v86 offset:32768
	ds_read_b128 v[86:89], v86 offset:36864
	v_mfma_f32_32x32x16_bf16 v[2:17], v[70:73], v[66:69], v[2:17]
	s_waitcnt lgkmcnt(0)
	v_mfma_f32_32x32x16_bf16 v[50:65], v[74:77], v[78:81], v[50:65]
	v_xor_b32_e32 v70, 0x40, v226
	v_add_u32_e32 v66, v70, v224
	v_add_u32_e32 v70, v70, v225
	v_mfma_f32_32x32x16_bf16 v[34:49], v[86:89], v[78:81], v[34:49]
	ds_read_b128 v[78:81], v66
	ds_read_b128 v[66:69], v66 offset:4096
	v_mfma_f32_32x32x16_bf16 v[18:33], v[74:77], v[82:85], v[18:33]
	ds_read_b128 v[74:77], v70 offset:32768
	ds_read_b128 v[70:73], v70 offset:36864
	v_mfma_f32_32x32x16_bf16 v[2:17], v[86:89], v[82:85], v[2:17]
	s_waitcnt lgkmcnt(0)
	v_mfma_f32_32x32x16_bf16 v[50:65], v[74:77], v[78:81], v[50:65]
	v_xor_b32_e32 v86, 0x60, v226
	v_add_u32_e32 v82, v86, v224
	v_add_u32_e32 v86, v86, v225
	v_mfma_f32_32x32x16_bf16 v[34:49], v[70:73], v[78:81], v[34:49]
	ds_read_b128 v[78:81], v82
	ds_read_b128 v[82:85], v82 offset:4096
	v_mfma_f32_32x32x16_bf16 v[18:33], v[74:77], v[66:69], v[18:33]
	ds_read_b128 v[74:77], v86 offset:32768
	ds_read_b128 v[86:89], v86 offset:36864
	v_mfma_f32_32x32x16_bf16 v[2:17], v[70:73], v[66:69], v[2:17]
	s_add_u32 s98, s48, 0x500
	s_addc_u32 s99, s49, 0
	s_add_u32 s100, s44, 0x500
	s_addc_u32 s101, s45, 0
	s_waitcnt vmcnt(0) lgkmcnt(0)
	s_barrier
	s_waitcnt lgkmcnt(0)
	v_mfma_f32_32x32x16_bf16 v[50:65], v[74:77], v[78:81], v[50:65]
	v_mov_b32_e32 v70, v226
	v_add_u32_e32 v66, v70, v224
	v_add_u32_e32 v70, v70, v225
	v_mfma_f32_32x32x16_bf16 v[34:49], v[86:89], v[78:81], v[34:49]
	ds_read_b128 v[78:81], v66 offset:16384
	ds_read_b128 v[66:69], v66 offset:20480
	s_add_u32 m0, s30, 0x0
	s_nop 0
	global_load_lds_dwordx4 v200, s[98:99]
	s_add_u32 m0, s30, 0x1000
	s_nop 0
	global_load_lds_dwordx4 v201, s[98:99]
	v_mfma_f32_32x32x16_bf16 v[18:33], v[74:77], v[82:85], v[18:33]
	ds_read_b128 v[74:77], v70 offset:49152
	ds_read_b128 v[70:73], v70 offset:53248
	s_add_u32 m0, s30, 0x2000
	s_nop 0
	global_load_lds_dwordx4 v202, s[98:99]
	s_add_u32 m0, s30, 0x3000
	s_nop 0
	global_load_lds_dwordx4 v204, s[98:99]
	v_mfma_f32_32x32x16_bf16 v[2:17], v[86:89], v[82:85], v[2:17]
	s_add_u32 m0, s30, 0x8000
	s_nop 0
	global_load_lds_dwordx4 v200, s[100:101]
	s_add_u32 m0, s30, 0x9000
	s_nop 0
	global_load_lds_dwordx4 v201, s[100:101]
	s_add_u32 m0, s30, 0xa000
	s_nop 0
	global_load_lds_dwordx4 v202, s[100:101]
	s_add_u32 m0, s30, 0xb000
	s_nop 0
	global_load_lds_dwordx4 v204, s[100:101]
	s_add_u32 s98, s98, 0x80
	s_addc_u32 s99, s99, 0
	s_add_u32 s100, s100, 0x80
	s_addc_u32 s101, s101, 0
	s_waitcnt lgkmcnt(0)
	v_mfma_f32_32x32x16_bf16 v[50:65], v[74:77], v[78:81], v[50:65]
	v_xor_b32_e32 v86, 0x20, v226
	v_add_u32_e32 v82, v86, v224
	v_add_u32_e32 v86, v86, v225
	v_mfma_f32_32x32x16_bf16 v[34:49], v[70:73], v[78:81], v[34:49]
	ds_read_b128 v[78:81], v82 offset:16384
	ds_read_b128 v[82:85], v82 offset:20480
	v_mfma_f32_32x32x16_bf16 v[18:33], v[74:77], v[66:69], v[18:33]
	ds_read_b128 v[74:77], v86 offset:49152
	ds_read_b128 v[86:89], v86 offset:53248
	v_mfma_f32_32x32x16_bf16 v[2:17], v[70:73], v[66:69], v[2:17]
	s_waitcnt lgkmcnt(0)
	v_mfma_f32_32x32x16_bf16 v[50:65], v[74:77], v[78:81], v[50:65]
	v_xor_b32_e32 v70, 0x40, v226
	v_add_u32_e32 v66, v70, v224
	v_add_u32_e32 v70, v70, v225
	v_mfma_f32_32x32x16_bf16 v[34:49], v[86:89], v[78:81], v[34:49]
	ds_read_b128 v[78:81], v66 offset:16384
	ds_read_b128 v[66:69], v66 offset:20480
	v_mfma_f32_32x32x16_bf16 v[18:33], v[74:77], v[82:85], v[18:33]
	ds_read_b128 v[74:77], v70 offset:49152
	ds_read_b128 v[70:73], v70 offset:53248
	v_mfma_f32_32x32x16_bf16 v[2:17], v[86:89], v[82:85], v[2:17]
	s_waitcnt lgkmcnt(0)
	v_mfma_f32_32x32x16_bf16 v[50:65], v[74:77], v[78:81], v[50:65]
	v_xor_b32_e32 v86, 0x60, v226
	v_add_u32_e32 v82, v86, v224
	v_add_u32_e32 v86, v86, v225
	v_mfma_f32_32x32x16_bf16 v[34:49], v[70:73], v[78:81], v[34:49]
	ds_read_b128 v[78:81], v82 offset:16384
	ds_read_b128 v[82:85], v82 offset:20480
	v_mfma_f32_32x32x16_bf16 v[18:33], v[74:77], v[66:69], v[18:33]
	ds_read_b128 v[74:77], v86 offset:49152
	ds_read_b128 v[86:89], v86 offset:53248
	v_mfma_f32_32x32x16_bf16 v[2:17], v[70:73], v[66:69], v[2:17]
	s_waitcnt vmcnt(0) lgkmcnt(0)
	s_barrier
	s_waitcnt lgkmcnt(0)
	v_mfma_f32_32x32x16_bf16 v[50:65], v[74:77], v[78:81], v[50:65]
	v_mov_b32_e32 v70, v226
	v_add_u32_e32 v66, v70, v224
	v_add_u32_e32 v70, v70, v225
	v_mfma_f32_32x32x16_bf16 v[34:49], v[86:89], v[78:81], v[34:49]
	ds_read_b128 v[78:81], v66
	ds_read_b128 v[66:69], v66 offset:4096
	s_add_u32 m0, s30, 0x4000
	s_nop 0
	global_load_lds_dwordx4 v200, s[98:99]
	s_add_u32 m0, s30, 0x5000
	s_nop 0
	global_load_lds_dwordx4 v201, s[98:99]
	v_mfma_f32_32x32x16_bf16 v[18:33], v[74:77], v[82:85], v[18:33]
	ds_read_b128 v[74:77], v70 offset:32768
	ds_read_b128 v[70:73], v70 offset:36864
	s_add_u32 m0, s30, 0x6000
	s_nop 0
	global_load_lds_dwordx4 v202, s[98:99]
	s_add_u32 m0, s30, 0x7000
	s_nop 0
	global_load_lds_dwordx4 v204, s[98:99]
	v_mfma_f32_32x32x16_bf16 v[2:17], v[86:89], v[82:85], v[2:17]
	s_add_u32 m0, s30, 0xc000
	s_nop 0
	global_load_lds_dwordx4 v200, s[100:101]
	s_add_u32 m0, s30, 0xd000
	s_nop 0
	global_load_lds_dwordx4 v201, s[100:101]
	s_add_u32 m0, s30, 0xe000
	s_nop 0
	global_load_lds_dwordx4 v202, s[100:101]
	s_add_u32 m0, s30, 0xf000
	s_nop 0
	global_load_lds_dwordx4 v204, s[100:101]
	s_add_u32 s98, s98, 0x80
	s_addc_u32 s99, s99, 0
	s_add_u32 s100, s100, 0x80
	s_addc_u32 s101, s101, 0
	s_nop 15
	v_lshlrev_b32_e32 v220, 16, v130
	v_and_b32_e32 v221, 0xffff0000, v130
	v_fmac_f32_e32 v227, v2, v220
	v_fmac_f32_e32 v228, v3, v221
	v_lshlrev_b32_e32 v220, 16, v131
	v_and_b32_e32 v221, 0xffff0000, v131
	v_fmac_f32_e32 v229, v4, v220
	v_fmac_f32_e32 v230, v5, v221
	v_lshlrev_b32_e32 v220, 16, v132
	v_and_b32_e32 v221, 0xffff0000, v132
	v_fmac_f32_e32 v231, v6, v220
	v_fmac_f32_e32 v232, v7, v221
	v_lshlrev_b32_e32 v220, 16, v133
	v_and_b32_e32 v221, 0xffff0000, v133
	v_fmac_f32_e32 v233, v8, v220
	v_fmac_f32_e32 v234, v9, v221
	v_lshlrev_b32_e32 v220, 16, v134
	v_and_b32_e32 v221, 0xffff0000, v134
	v_fmac_f32_e32 v235, v10, v220
	v_fmac_f32_e32 v236, v11, v221
	v_lshlrev_b32_e32 v220, 16, v135
	v_and_b32_e32 v221, 0xffff0000, v135
	v_fmac_f32_e32 v237, v12, v220
	v_fmac_f32_e32 v238, v13, v221
	v_lshlrev_b32_e32 v220, 16, v136
	v_and_b32_e32 v221, 0xffff0000, v136
	v_fmac_f32_e32 v239, v14, v220
	v_fmac_f32_e32 v240, v15, v221
	v_lshlrev_b32_e32 v220, 16, v137
	v_and_b32_e32 v221, 0xffff0000, v137
	v_fmac_f32_e32 v241, v16, v220
	v_fmac_f32_e32 v242, v17, v221
	v_lshlrev_b32_e32 v220, 16, v138
	v_and_b32_e32 v221, 0xffff0000, v138
	v_fmac_f32_e32 v243, v18, v220
	v_fmac_f32_e32 v244, v19, v221
	v_lshlrev_b32_e32 v220, 16, v139
	v_and_b32_e32 v221, 0xffff0000, v139
	v_fmac_f32_e32 v245, v20, v220
	v_fmac_f32_e32 v246, v21, v221
	v_lshlrev_b32_e32 v220, 16, v140
	v_and_b32_e32 v221, 0xffff0000, v140
	v_fmac_f32_e32 v247, v22, v220
	v_fmac_f32_e32 v248, v23, v221
	v_lshlrev_b32_e32 v220, 16, v141
	v_and_b32_e32 v221, 0xffff0000, v141
	v_fmac_f32_e32 v249, v24, v220
	v_fmac_f32_e32 v250, v25, v221
	v_lshlrev_b32_e32 v220, 16, v142
	v_and_b32_e32 v221, 0xffff0000, v142
	v_fmac_f32_e32 v251, v26, v220
	v_fmac_f32_e32 v90, v27, v221
	v_lshlrev_b32_e32 v220, 16, v143
	v_and_b32_e32 v221, 0xffff0000, v143
	v_fmac_f32_e32 v91, v28, v220
	v_fmac_f32_e32 v92, v29, v221
	v_lshlrev_b32_e32 v220, 16, v144
	v_and_b32_e32 v221, 0xffff0000, v144
	v_fmac_f32_e32 v93, v30, v220
	v_fmac_f32_e32 v94, v31, v221
	v_lshlrev_b32_e32 v220, 16, v145
	v_and_b32_e32 v221, 0xffff0000, v145
	v_fmac_f32_e32 v95, v32, v220
	v_fmac_f32_e32 v96, v33, v221
	v_lshlrev_b32_e32 v220, 16, v146
	v_and_b32_e32 v221, 0xffff0000, v146
	v_fmac_f32_e32 v98, v34, v220
	v_fmac_f32_e32 v99, v35, v221
	v_lshlrev_b32_e32 v220, 16, v147
	v_and_b32_e32 v221, 0xffff0000, v147
	v_fmac_f32_e32 v100, v36, v220
	v_fmac_f32_e32 v101, v37, v221
	v_lshlrev_b32_e32 v220, 16, v148
	v_and_b32_e32 v221, 0xffff0000, v148
	v_fmac_f32_e32 v102, v38, v220
	v_fmac_f32_e32 v103, v39, v221
	v_lshlrev_b32_e32 v220, 16, v149
	v_and_b32_e32 v221, 0xffff0000, v149
	v_fmac_f32_e32 v104, v40, v220
	v_fmac_f32_e32 v105, v41, v221
	v_lshlrev_b32_e32 v220, 16, v150
	v_and_b32_e32 v221, 0xffff0000, v150
	v_fmac_f32_e32 v106, v42, v220
	v_fmac_f32_e32 v107, v43, v221
	v_lshlrev_b32_e32 v220, 16, v151
	v_and_b32_e32 v221, 0xffff0000, v151
	v_fmac_f32_e32 v108, v44, v220
	v_fmac_f32_e32 v109, v45, v221
	v_lshlrev_b32_e32 v220, 16, v152
	v_and_b32_e32 v221, 0xffff0000, v152
	v_fmac_f32_e32 v110, v46, v220
	v_fmac_f32_e32 v111, v47, v221
	v_lshlrev_b32_e32 v220, 16, v153
	v_and_b32_e32 v221, 0xffff0000, v153
	v_fmac_f32_e32 v112, v48, v220
	v_fmac_f32_e32 v113, v49, v221
	v_lshlrev_b32_e32 v220, 16, v154
	v_and_b32_e32 v221, 0xffff0000, v154
	v_fmac_f32_e32 v114, v50, v220
	v_fmac_f32_e32 v115, v51, v221
	v_lshlrev_b32_e32 v220, 16, v155
	v_and_b32_e32 v221, 0xffff0000, v155
	v_fmac_f32_e32 v116, v52, v220
	v_fmac_f32_e32 v117, v53, v221
	v_lshlrev_b32_e32 v220, 16, v156
	v_and_b32_e32 v221, 0xffff0000, v156
	v_fmac_f32_e32 v118, v54, v220
	v_fmac_f32_e32 v119, v55, v221
	v_lshlrev_b32_e32 v220, 16, v157
	v_and_b32_e32 v221, 0xffff0000, v157
	v_fmac_f32_e32 v120, v56, v220
	v_fmac_f32_e32 v121, v57, v221
	v_lshlrev_b32_e32 v220, 16, v158
	v_and_b32_e32 v221, 0xffff0000, v158
	v_fmac_f32_e32 v122, v58, v220
	v_fmac_f32_e32 v123, v59, v221
	v_lshlrev_b32_e32 v220, 16, v159
	v_and_b32_e32 v221, 0xffff0000, v159
	v_fmac_f32_e32 v124, v60, v220
	v_fmac_f32_e32 v125, v61, v221
	v_lshlrev_b32_e32 v220, 16, v160
	v_and_b32_e32 v221, 0xffff0000, v160
	v_fmac_f32_e32 v126, v62, v220
	v_fmac_f32_e32 v127, v63, v221
	v_lshlrev_b32_e32 v220, 16, v161
	v_and_b32_e32 v221, 0xffff0000, v161
	v_fmac_f32_e32 v128, v64, v220
	v_fmac_f32_e32 v129, v65, v221
	v_mov_b32_e32 v2, 0
	v_mov_b32_e32 v3, 0
	v_mov_b32_e32 v4, 0
	v_mov_b32_e32 v5, 0
	v_mov_b32_e32 v6, 0
	v_mov_b32_e32 v7, 0
	v_mov_b32_e32 v8, 0
	v_mov_b32_e32 v9, 0
	v_mov_b32_e32 v10, 0
	v_mov_b32_e32 v11, 0
	v_mov_b32_e32 v12, 0
	v_mov_b32_e32 v13, 0
	v_mov_b32_e32 v14, 0
	v_mov_b32_e32 v15, 0
	v_mov_b32_e32 v16, 0
	v_mov_b32_e32 v17, 0
	v_mov_b32_e32 v18, 0
	v_mov_b32_e32 v19, 0
	v_mov_b32_e32 v20, 0
	v_mov_b32_e32 v21, 0
	v_mov_b32_e32 v22, 0
	v_mov_b32_e32 v23, 0
	v_mov_b32_e32 v24, 0
	v_mov_b32_e32 v25, 0
	v_mov_b32_e32 v26, 0
	v_mov_b32_e32 v27, 0
	v_mov_b32_e32 v28, 0
	v_mov_b32_e32 v29, 0
	v_mov_b32_e32 v30, 0
	v_mov_b32_e32 v31, 0
	v_mov_b32_e32 v32, 0
	v_mov_b32_e32 v33, 0
	v_mov_b32_e32 v34, 0
	v_mov_b32_e32 v35, 0
	v_mov_b32_e32 v36, 0
	v_mov_b32_e32 v37, 0
	v_mov_b32_e32 v38, 0
	v_mov_b32_e32 v39, 0
	v_mov_b32_e32 v40, 0
	v_mov_b32_e32 v41, 0
	v_mov_b32_e32 v42, 0
	v_mov_b32_e32 v43, 0
	v_mov_b32_e32 v44, 0
	v_mov_b32_e32 v45, 0
	v_mov_b32_e32 v46, 0
	v_mov_b32_e32 v47, 0
	v_mov_b32_e32 v48, 0
	v_mov_b32_e32 v49, 0
	v_mov_b32_e32 v50, 0
	v_mov_b32_e32 v51, 0
	v_mov_b32_e32 v52, 0
	v_mov_b32_e32 v53, 0
	v_mov_b32_e32 v54, 0
	v_mov_b32_e32 v55, 0
	v_mov_b32_e32 v56, 0
	v_mov_b32_e32 v57, 0
	v_mov_b32_e32 v58, 0
	v_mov_b32_e32 v59, 0
	v_mov_b32_e32 v60, 0
	v_mov_b32_e32 v61, 0
	v_mov_b32_e32 v62, 0
	v_mov_b32_e32 v63, 0
	v_mov_b32_e32 v64, 0
	v_mov_b32_e32 v65, 0
	s_nop 4
	s_waitcnt lgkmcnt(0)
	v_mfma_f32_32x32x16_bf16 v[50:65], v[74:77], v[78:81], v[50:65]
	v_xor_b32_e32 v86, 0x20, v226
	v_add_u32_e32 v82, v86, v224
	v_add_u32_e32 v86, v86, v225
	v_mfma_f32_32x32x16_bf16 v[34:49], v[70:73], v[78:81], v[34:49]
	ds_read_b128 v[78:81], v82
	ds_read_b128 v[82:85], v82 offset:4096
	v_mfma_f32_32x32x16_bf16 v[18:33], v[74:77], v[66:69], v[18:33]
	ds_read_b128 v[74:77], v86 offset:32768
	ds_read_b128 v[86:89], v86 offset:36864
	v_mfma_f32_32x32x16_bf16 v[2:17], v[70:73], v[66:69], v[2:17]
	s_waitcnt lgkmcnt(0)
	v_mfma_f32_32x32x16_bf16 v[50:65], v[74:77], v[78:81], v[50:65]
	v_xor_b32_e32 v70, 0x40, v226
	v_add_u32_e32 v66, v70, v224
	v_add_u32_e32 v70, v70, v225
	v_mfma_f32_32x32x16_bf16 v[34:49], v[86:89], v[78:81], v[34:49]
	ds_read_b128 v[78:81], v66
	ds_read_b128 v[66:69], v66 offset:4096
	v_mfma_f32_32x32x16_bf16 v[18:33], v[74:77], v[82:85], v[18:33]
	ds_read_b128 v[74:77], v70 offset:32768
	ds_read_b128 v[70:73], v70 offset:36864
	v_mfma_f32_32x32x16_bf16 v[2:17], v[86:89], v[82:85], v[2:17]
	s_waitcnt lgkmcnt(0)
	v_mfma_f32_32x32x16_bf16 v[50:65], v[74:77], v[78:81], v[50:65]
	v_xor_b32_e32 v86, 0x60, v226
	v_add_u32_e32 v82, v86, v224
	v_add_u32_e32 v86, v86, v225
	v_mfma_f32_32x32x16_bf16 v[34:49], v[70:73], v[78:81], v[34:49]
	ds_read_b128 v[78:81], v82
	ds_read_b128 v[82:85], v82 offset:4096
	v_mfma_f32_32x32x16_bf16 v[18:33], v[74:77], v[66:69], v[18:33]
	ds_read_b128 v[74:77], v86 offset:32768
	ds_read_b128 v[86:89], v86 offset:36864
	v_mfma_f32_32x32x16_bf16 v[2:17], v[70:73], v[66:69], v[2:17]
	s_waitcnt vmcnt(0) lgkmcnt(0)
	s_barrier
	s_waitcnt lgkmcnt(0)
	v_mfma_f32_32x32x16_bf16 v[50:65], v[74:77], v[78:81], v[50:65]
	v_mov_b32_e32 v70, v226
	v_add_u32_e32 v66, v70, v224
	v_add_u32_e32 v70, v70, v225
	v_mfma_f32_32x32x16_bf16 v[34:49], v[86:89], v[78:81], v[34:49]
	ds_read_b128 v[78:81], v66 offset:16384
	ds_read_b128 v[66:69], v66 offset:20480
	s_add_u32 m0, s30, 0x0
	s_nop 0
	global_load_lds_dwordx4 v200, s[98:99]
	s_add_u32 m0, s30, 0x1000
	s_nop 0
	global_load_lds_dwordx4 v201, s[98:99]
	v_mfma_f32_32x32x16_bf16 v[18:33], v[74:77], v[82:85], v[18:33]
	ds_read_b128 v[74:77], v70 offset:49152
	ds_read_b128 v[70:73], v70 offset:53248
	s_add_u32 m0, s30, 0x2000
	s_nop 0
	global_load_lds_dwordx4 v202, s[98:99]
	s_add_u32 m0, s30, 0x3000
	s_nop 0
	global_load_lds_dwordx4 v204, s[98:99]
	v_mfma_f32_32x32x16_bf16 v[2:17], v[86:89], v[82:85], v[2:17]
	s_add_u32 m0, s30, 0x8000
	s_nop 0
	global_load_lds_dwordx4 v200, s[100:101]
	s_add_u32 m0, s30, 0x9000
	s_nop 0
	global_load_lds_dwordx4 v201, s[100:101]
	s_add_u32 m0, s30, 0xa000
	s_nop 0
	global_load_lds_dwordx4 v202, s[100:101]
	s_add_u32 m0, s30, 0xb000
	s_nop 0
	global_load_lds_dwordx4 v204, s[100:101]
	s_add_u32 s98, s98, 0x80
	s_addc_u32 s99, s99, 0
	s_add_u32 s100, s100, 0x80
	s_addc_u32 s101, s101, 0
	s_waitcnt lgkmcnt(0)
	v_mfma_f32_32x32x16_bf16 v[50:65], v[74:77], v[78:81], v[50:65]
	v_xor_b32_e32 v86, 0x20, v226
	v_add_u32_e32 v82, v86, v224
	v_add_u32_e32 v86, v86, v225
	v_mfma_f32_32x32x16_bf16 v[34:49], v[70:73], v[78:81], v[34:49]
	ds_read_b128 v[78:81], v82 offset:16384
	ds_read_b128 v[82:85], v82 offset:20480
	v_mfma_f32_32x32x16_bf16 v[18:33], v[74:77], v[66:69], v[18:33]
	ds_read_b128 v[74:77], v86 offset:49152
	ds_read_b128 v[86:89], v86 offset:53248
	v_mfma_f32_32x32x16_bf16 v[2:17], v[70:73], v[66:69], v[2:17]
	s_waitcnt lgkmcnt(0)
	v_mfma_f32_32x32x16_bf16 v[50:65], v[74:77], v[78:81], v[50:65]
	v_xor_b32_e32 v70, 0x40, v226
	v_add_u32_e32 v66, v70, v224
	v_add_u32_e32 v70, v70, v225
	v_mfma_f32_32x32x16_bf16 v[34:49], v[86:89], v[78:81], v[34:49]
	ds_read_b128 v[78:81], v66 offset:16384
	ds_read_b128 v[66:69], v66 offset:20480
	v_mfma_f32_32x32x16_bf16 v[18:33], v[74:77], v[82:85], v[18:33]
	ds_read_b128 v[74:77], v70 offset:49152
	ds_read_b128 v[70:73], v70 offset:53248
	v_mfma_f32_32x32x16_bf16 v[2:17], v[86:89], v[82:85], v[2:17]
	s_waitcnt lgkmcnt(0)
	v_mfma_f32_32x32x16_bf16 v[50:65], v[74:77], v[78:81], v[50:65]
	v_xor_b32_e32 v86, 0x60, v226
	v_add_u32_e32 v82, v86, v224
	v_add_u32_e32 v86, v86, v225
	v_mfma_f32_32x32x16_bf16 v[34:49], v[70:73], v[78:81], v[34:49]
	ds_read_b128 v[78:81], v82 offset:16384
	ds_read_b128 v[82:85], v82 offset:20480
	v_mfma_f32_32x32x16_bf16 v[18:33], v[74:77], v[66:69], v[18:33]
	ds_read_b128 v[74:77], v86 offset:49152
	ds_read_b128 v[86:89], v86 offset:53248
	v_mfma_f32_32x32x16_bf16 v[2:17], v[70:73], v[66:69], v[2:17]
	s_waitcnt vmcnt(0) lgkmcnt(0)
	s_barrier
	s_waitcnt lgkmcnt(0)
	v_mfma_f32_32x32x16_bf16 v[50:65], v[74:77], v[78:81], v[50:65]
	v_mov_b32_e32 v70, v226
	v_add_u32_e32 v66, v70, v224
	v_add_u32_e32 v70, v70, v225
	v_mfma_f32_32x32x16_bf16 v[34:49], v[86:89], v[78:81], v[34:49]
	ds_read_b128 v[78:81], v66
	ds_read_b128 v[66:69], v66 offset:4096
	s_add_u32 m0, s30, 0x4000
	s_nop 0
	global_load_lds_dwordx4 v200, s[98:99]
	s_add_u32 m0, s30, 0x5000
	s_nop 0
	global_load_lds_dwordx4 v201, s[98:99]
	v_mfma_f32_32x32x16_bf16 v[18:33], v[74:77], v[82:85], v[18:33]
	ds_read_b128 v[74:77], v70 offset:32768
	ds_read_b128 v[70:73], v70 offset:36864
	s_add_u32 m0, s30, 0x6000
	s_nop 0
	global_load_lds_dwordx4 v202, s[98:99]
	s_add_u32 m0, s30, 0x7000
	s_nop 0
	global_load_lds_dwordx4 v204, s[98:99]
	v_mfma_f32_32x32x16_bf16 v[2:17], v[86:89], v[82:85], v[2:17]
	s_add_u32 m0, s30, 0xc000
	s_nop 0
	global_load_lds_dwordx4 v200, s[100:101]
	s_add_u32 m0, s30, 0xd000
	s_nop 0
	global_load_lds_dwordx4 v201, s[100:101]
	s_add_u32 m0, s30, 0xe000
	s_nop 0
	global_load_lds_dwordx4 v202, s[100:101]
	s_add_u32 m0, s30, 0xf000
	s_nop 0
	global_load_lds_dwordx4 v204, s[100:101]
	s_add_u32 s98, s98, 0x80
	s_addc_u32 s99, s99, 0
	s_add_u32 s100, s100, 0x80
	s_addc_u32 s101, s101, 0
	s_waitcnt lgkmcnt(0)
	v_mfma_f32_32x32x16_bf16 v[50:65], v[74:77], v[78:81], v[50:65]
	v_xor_b32_e32 v86, 0x20, v226
	v_add_u32_e32 v82, v86, v224
	v_add_u32_e32 v86, v86, v225
	v_mfma_f32_32x32x16_bf16 v[34:49], v[70:73], v[78:81], v[34:49]
	ds_read_b128 v[78:81], v82
	ds_read_b128 v[82:85], v82 offset:4096
	v_mfma_f32_32x32x16_bf16 v[18:33], v[74:77], v[66:69], v[18:33]
	ds_read_b128 v[74:77], v86 offset:32768
	ds_read_b128 v[86:89], v86 offset:36864
	v_mfma_f32_32x32x16_bf16 v[2:17], v[70:73], v[66:69], v[2:17]
	s_waitcnt lgkmcnt(0)
	v_mfma_f32_32x32x16_bf16 v[50:65], v[74:77], v[78:81], v[50:65]
	v_xor_b32_e32 v70, 0x40, v226
	v_add_u32_e32 v66, v70, v224
	v_add_u32_e32 v70, v70, v225
	v_mfma_f32_32x32x16_bf16 v[34:49], v[86:89], v[78:81], v[34:49]
	ds_read_b128 v[78:81], v66
	ds_read_b128 v[66:69], v66 offset:4096
	v_mfma_f32_32x32x16_bf16 v[18:33], v[74:77], v[82:85], v[18:33]
	ds_read_b128 v[74:77], v70 offset:32768
	ds_read_b128 v[70:73], v70 offset:36864
	v_mfma_f32_32x32x16_bf16 v[2:17], v[86:89], v[82:85], v[2:17]
	s_waitcnt lgkmcnt(0)
	v_mfma_f32_32x32x16_bf16 v[50:65], v[74:77], v[78:81], v[50:65]
	v_xor_b32_e32 v86, 0x60, v226
	v_add_u32_e32 v82, v86, v224
	v_add_u32_e32 v86, v86, v225
	v_mfma_f32_32x32x16_bf16 v[34:49], v[70:73], v[78:81], v[34:49]
	ds_read_b128 v[78:81], v82
	ds_read_b128 v[82:85], v82 offset:4096
	v_mfma_f32_32x32x16_bf16 v[18:33], v[74:77], v[66:69], v[18:33]
	ds_read_b128 v[74:77], v86 offset:32768
	ds_read_b128 v[86:89], v86 offset:36864
	v_mfma_f32_32x32x16_bf16 v[2:17], v[70:73], v[66:69], v[2:17]
	s_waitcnt vmcnt(0) lgkmcnt(0)
	s_barrier
	s_waitcnt lgkmcnt(0)
	v_mfma_f32_32x32x16_bf16 v[50:65], v[74:77], v[78:81], v[50:65]
	v_mov_b32_e32 v70, v226
	v_add_u32_e32 v66, v70, v224
	v_add_u32_e32 v70, v70, v225
	v_mfma_f32_32x32x16_bf16 v[34:49], v[86:89], v[78:81], v[34:49]
	ds_read_b128 v[78:81], v66 offset:16384
	ds_read_b128 v[66:69], v66 offset:20480
	v_mfma_f32_32x32x16_bf16 v[18:33], v[74:77], v[82:85], v[18:33]
	ds_read_b128 v[74:77], v70 offset:49152
	ds_read_b128 v[70:73], v70 offset:53248
	v_mfma_f32_32x32x16_bf16 v[2:17], v[86:89], v[82:85], v[2:17]
	s_waitcnt lgkmcnt(0)
	v_mfma_f32_32x32x16_bf16 v[50:65], v[74:77], v[78:81], v[50:65]
	v_xor_b32_e32 v86, 0x20, v226
	v_add_u32_e32 v82, v86, v224
	v_add_u32_e32 v86, v86, v225
	v_mfma_f32_32x32x16_bf16 v[34:49], v[70:73], v[78:81], v[34:49]
	ds_read_b128 v[78:81], v82 offset:16384
	ds_read_b128 v[82:85], v82 offset:20480
	v_mfma_f32_32x32x16_bf16 v[18:33], v[74:77], v[66:69], v[18:33]
	ds_read_b128 v[74:77], v86 offset:49152
	ds_read_b128 v[86:89], v86 offset:53248
	v_mfma_f32_32x32x16_bf16 v[2:17], v[70:73], v[66:69], v[2:17]
	s_waitcnt lgkmcnt(0)
	v_mfma_f32_32x32x16_bf16 v[50:65], v[74:77], v[78:81], v[50:65]
	v_xor_b32_e32 v70, 0x40, v226
	v_add_u32_e32 v66, v70, v224
	v_add_u32_e32 v70, v70, v225
	v_mfma_f32_32x32x16_bf16 v[34:49], v[86:89], v[78:81], v[34:49]
	ds_read_b128 v[78:81], v66 offset:16384
	ds_read_b128 v[66:69], v66 offset:20480
	v_mfma_f32_32x32x16_bf16 v[18:33], v[74:77], v[82:85], v[18:33]
	ds_read_b128 v[74:77], v70 offset:49152
	ds_read_b128 v[70:73], v70 offset:53248
	v_mfma_f32_32x32x16_bf16 v[2:17], v[86:89], v[82:85], v[2:17]
	s_waitcnt lgkmcnt(0)
	v_mfma_f32_32x32x16_bf16 v[50:65], v[74:77], v[78:81], v[50:65]
	v_xor_b32_e32 v86, 0x60, v226
	v_add_u32_e32 v82, v86, v224
	v_add_u32_e32 v86, v86, v225
	v_mfma_f32_32x32x16_bf16 v[34:49], v[70:73], v[78:81], v[34:49]
	ds_read_b128 v[78:81], v82 offset:16384
	ds_read_b128 v[82:85], v82 offset:20480
	v_mfma_f32_32x32x16_bf16 v[18:33], v[74:77], v[66:69], v[18:33]
	ds_read_b128 v[74:77], v86 offset:49152
	ds_read_b128 v[86:89], v86 offset:53248
	v_mfma_f32_32x32x16_bf16 v[2:17], v[70:73], v[66:69], v[2:17]
	s_waitcnt lgkmcnt(0)
	v_mfma_f32_32x32x16_bf16 v[50:65], v[74:77], v[78:81], v[50:65]
	v_mfma_f32_32x32x16_bf16 v[34:49], v[86:89], v[78:81], v[34:49]
	v_mfma_f32_32x32x16_bf16 v[18:33], v[74:77], v[82:85], v[18:33]
	v_mfma_f32_32x32x16_bf16 v[2:17], v[86:89], v[82:85], v[2:17]
	s_nop 15
	v_lshlrev_b32_e32 v220, 16, v162
	v_and_b32_e32 v221, 0xffff0000, v162
	v_fma_f32 v2, v2, v220, v227
	v_fma_f32 v3, v3, v221, v228
	v_lshlrev_b32_e32 v220, 16, v163
	v_and_b32_e32 v221, 0xffff0000, v163
	v_fma_f32 v4, v4, v220, v229
	v_fma_f32 v5, v5, v221, v230
	v_lshlrev_b32_e32 v220, 16, v164
	v_and_b32_e32 v221, 0xffff0000, v164
	v_fma_f32 v6, v6, v220, v231
	v_fma_f32 v7, v7, v221, v232
	v_lshlrev_b32_e32 v220, 16, v165
	v_and_b32_e32 v221, 0xffff0000, v165
	v_fma_f32 v8, v8, v220, v233
	v_fma_f32 v9, v9, v221, v234
	v_lshlrev_b32_e32 v220, 16, v166
	v_and_b32_e32 v221, 0xffff0000, v166
	v_fma_f32 v10, v10, v220, v235
	v_fma_f32 v11, v11, v221, v236
	v_lshlrev_b32_e32 v220, 16, v167
	v_and_b32_e32 v221, 0xffff0000, v167
	v_fma_f32 v12, v12, v220, v237
	v_fma_f32 v13, v13, v221, v238
	v_lshlrev_b32_e32 v220, 16, v168
	v_and_b32_e32 v221, 0xffff0000, v168
	v_fma_f32 v14, v14, v220, v239
	v_fma_f32 v15, v15, v221, v240
	v_lshlrev_b32_e32 v220, 16, v169
	v_and_b32_e32 v221, 0xffff0000, v169
	v_fma_f32 v16, v16, v220, v241
	v_fma_f32 v17, v17, v221, v242
	v_lshlrev_b32_e32 v220, 16, v170
	v_and_b32_e32 v221, 0xffff0000, v170
	v_fma_f32 v18, v18, v220, v243
	v_fma_f32 v19, v19, v221, v244
	v_lshlrev_b32_e32 v220, 16, v171
	v_and_b32_e32 v221, 0xffff0000, v171
	v_fma_f32 v20, v20, v220, v245
	v_fma_f32 v21, v21, v221, v246
	v_lshlrev_b32_e32 v220, 16, v172
	v_and_b32_e32 v221, 0xffff0000, v172
	v_fma_f32 v22, v22, v220, v247
	v_fma_f32 v23, v23, v221, v248
	v_lshlrev_b32_e32 v220, 16, v173
	v_and_b32_e32 v221, 0xffff0000, v173
	v_fma_f32 v24, v24, v220, v249
	v_fma_f32 v25, v25, v221, v250
	v_lshlrev_b32_e32 v220, 16, v174
	v_and_b32_e32 v221, 0xffff0000, v174
	v_fma_f32 v26, v26, v220, v251
	v_fma_f32 v27, v27, v221, v90
	v_lshlrev_b32_e32 v220, 16, v175
	v_and_b32_e32 v221, 0xffff0000, v175
	v_fma_f32 v28, v28, v220, v91
	v_fma_f32 v29, v29, v221, v92
	v_lshlrev_b32_e32 v220, 16, v176
	v_and_b32_e32 v221, 0xffff0000, v176
	v_fma_f32 v30, v30, v220, v93
	v_fma_f32 v31, v31, v221, v94
	v_lshlrev_b32_e32 v220, 16, v177
	v_and_b32_e32 v221, 0xffff0000, v177
	v_fma_f32 v32, v32, v220, v95
	v_fma_f32 v33, v33, v221, v96
	v_lshlrev_b32_e32 v220, 16, v178
	v_and_b32_e32 v221, 0xffff0000, v178
	v_fma_f32 v34, v34, v220, v98
	v_fma_f32 v35, v35, v221, v99
	v_lshlrev_b32_e32 v220, 16, v179
	v_and_b32_e32 v221, 0xffff0000, v179
	v_fma_f32 v36, v36, v220, v100
	v_fma_f32 v37, v37, v221, v101
	v_lshlrev_b32_e32 v220, 16, v180
	v_and_b32_e32 v221, 0xffff0000, v180
	v_fma_f32 v38, v38, v220, v102
	v_fma_f32 v39, v39, v221, v103
	v_lshlrev_b32_e32 v220, 16, v181
	v_and_b32_e32 v221, 0xffff0000, v181
	v_fma_f32 v40, v40, v220, v104
	v_fma_f32 v41, v41, v221, v105
	v_lshlrev_b32_e32 v220, 16, v182
	v_and_b32_e32 v221, 0xffff0000, v182
	v_fma_f32 v42, v42, v220, v106
	v_fma_f32 v43, v43, v221, v107
	v_lshlrev_b32_e32 v220, 16, v183
	v_and_b32_e32 v221, 0xffff0000, v183
	v_fma_f32 v44, v44, v220, v108
	v_fma_f32 v45, v45, v221, v109
	v_lshlrev_b32_e32 v220, 16, v184
	v_and_b32_e32 v221, 0xffff0000, v184
	v_fma_f32 v46, v46, v220, v110
	v_fma_f32 v47, v47, v221, v111
	v_lshlrev_b32_e32 v220, 16, v185
	v_and_b32_e32 v221, 0xffff0000, v185
	v_fma_f32 v48, v48, v220, v112
	v_fma_f32 v49, v49, v221, v113
	v_lshlrev_b32_e32 v220, 16, v186
	v_and_b32_e32 v221, 0xffff0000, v186
	v_fma_f32 v50, v50, v220, v114
	v_fma_f32 v51, v51, v221, v115
	v_lshlrev_b32_e32 v220, 16, v187
	v_and_b32_e32 v221, 0xffff0000, v187
	v_fma_f32 v52, v52, v220, v116
	v_fma_f32 v53, v53, v221, v117
	v_lshlrev_b32_e32 v220, 16, v188
	v_and_b32_e32 v221, 0xffff0000, v188
	v_fma_f32 v54, v54, v220, v118
	v_fma_f32 v55, v55, v221, v119
	v_lshlrev_b32_e32 v220, 16, v189
	v_and_b32_e32 v221, 0xffff0000, v189
	v_fma_f32 v56, v56, v220, v120
	v_fma_f32 v57, v57, v221, v121
	v_lshlrev_b32_e32 v220, 16, v190
	v_and_b32_e32 v221, 0xffff0000, v190
	v_fma_f32 v58, v58, v220, v122
	v_fma_f32 v59, v59, v221, v123
	v_lshlrev_b32_e32 v220, 16, v191
	v_and_b32_e32 v221, 0xffff0000, v191
	v_fma_f32 v60, v60, v220, v124
	v_fma_f32 v61, v61, v221, v125
	v_lshlrev_b32_e32 v220, 16, v192
	v_and_b32_e32 v221, 0xffff0000, v192
	v_fma_f32 v62, v62, v220, v126
	v_fma_f32 v63, v63, v221, v127
	v_lshlrev_b32_e32 v220, 16, v193
	v_and_b32_e32 v221, 0xffff0000, v193
	v_fma_f32 v64, v64, v220, v128
	v_fma_f32 v65, v65, v221, v129
	v_mov_b32_e32 v114, v2
	v_mov_b32_e32 v112, v3
	v_mov_b32_e32 v115, v4
	v_mov_b32_e32 v113, v5
	v_mov_b32_e32 v110, v6
	v_mov_b32_e32 v108, v7
	v_mov_b32_e32 v111, v8
	v_mov_b32_e32 v109, v9
	v_mov_b32_e32 v104, v10
	v_mov_b32_e32 v102, v11
	v_mov_b32_e32 v105, v12
	v_mov_b32_e32 v103, v13
	v_mov_b32_e32 v98, v14
	v_mov_b32_e32 v100, v15
	v_mov_b32_e32 v99, v16
	v_mov_b32_e32 v101, v17
	v_mov_b32_e32 v130, v18
	v_mov_b32_e32 v128, v19
	v_mov_b32_e32 v131, v20
	v_mov_b32_e32 v129, v21
	v_mov_b32_e32 v126, v22
	v_mov_b32_e32 v124, v23
	v_mov_b32_e32 v127, v24
	v_mov_b32_e32 v125, v25
	v_mov_b32_e32 v120, v26
	v_mov_b32_e32 v118, v27
	v_mov_b32_e32 v121, v28
	v_mov_b32_e32 v119, v29
	v_mov_b32_e32 v106, v30
	v_mov_b32_e32 v116, v31
	v_mov_b32_e32 v107, v32
	v_mov_b32_e32 v117, v33
	v_mov_b32_e32 v146, v34
	v_mov_b32_e32 v144, v35
	v_mov_b32_e32 v147, v36
	v_mov_b32_e32 v145, v37
	v_mov_b32_e32 v142, v38
	v_mov_b32_e32 v140, v39
	v_mov_b32_e32 v143, v40
	v_mov_b32_e32 v141, v41
	v_mov_b32_e32 v136, v42
	v_mov_b32_e32 v134, v43
	v_mov_b32_e32 v137, v44
	v_mov_b32_e32 v135, v45
	v_mov_b32_e32 v122, v46
	v_mov_b32_e32 v132, v47
	v_mov_b32_e32 v123, v48
	v_mov_b32_e32 v133, v49
	v_mov_b32_e32 v160, v50
	v_mov_b32_e32 v158, v51
	v_mov_b32_e32 v161, v52
	v_mov_b32_e32 v159, v53
	v_mov_b32_e32 v156, v54
	v_mov_b32_e32 v154, v55
	v_mov_b32_e32 v157, v56
	v_mov_b32_e32 v155, v57
	v_mov_b32_e32 v152, v58
	v_mov_b32_e32 v150, v59
	v_mov_b32_e32 v153, v60
	v_mov_b32_e32 v151, v61
	v_mov_b32_e32 v138, v62
	v_mov_b32_e32 v148, v63
	v_mov_b32_e32 v139, v64
	v_mov_b32_e32 v149, v65
	s_branch .LBB0_915
